# v57 + GEMM phases: the trailing half's offset-restoring barrier between units deferred from the epilogue end to the K-loop entry (unit set-up and accumulator zeroing of both halves overlap)
# speedup vs baseline: 1.0071x; 1.0071x over previous
.LBB0_205:
	s_or_b64 exec, exec, s[4:5]
	s_mov_b32 s90, 0
	s_cmpk_lt_i32 s2, 0x800
	s_cselect_b64 s[6:7], -1, 0
	s_mov_b64 s[4:5], s[0:1]
	v_mov_b32_e32 v0, v202
	v_mov_b32_e32 v8, v202
	s_and_b64 vcc, exec, s[6:7]
	v_readfirstlane_b32 s20, v8
	s_cbranch_vccz .LBB0_207
	s_ashr_i32 s3, s2, 31
	s_lshr_b32 s3, s3, 29
	s_add_i32 s3, s2, s3
	s_and_b32 s8, s3, -8
	s_sub_i32 s8, s2, s8
	s_lshl_b32 s10, s8, 8
	s_ashr_i32 s3, s3, 3
	s_mul_i32 s9, s8, 0x101
	s_cmp_lt_i32 s8, 0
	s_cselect_b32 s8, s9, s10
	s_add_i32 s3, s8, s3
	s_ashr_i32 s8, s3, 31
	s_lshr_b32 s8, s8, 25
	s_add_i32 s8, s3, s8
	s_ashr_i32 s9, s8, 7
	s_and_b32 s8, s8, 0xffffff80
	s_sub_i32 s3, s3, s8
	s_bfe_i32 s8, s3, 0x80000
	s_bfe_u32 s8, s8, 0x3000c
	s_add_i32 s8, s3, s8
	s_bfe_i32 s10, s8, 0x80000
	s_and_b32 s8, s8, 0xf8
	s_sub_i32 s3, s3, s8
	s_lshl_b32 s9, s9, 3
	s_sext_i32_i16 s11, s10
	s_sext_i32_i8 s3, s3
	s_add_i32 s10, s9, s3
	s_ashr_i32 s8, s11, 3

.LBB0_219:
	s_ashr_i32 s45, s44, 31
	s_lshl_b64 s[46:47], s[44:45], 19
	s_add_u32 s46, s14, s46
	s_addc_u32 s47, s15, s47
	s_and_b64 s[48:49], s[6:7], exec
	s_cselect_b32 s9, s47, s51
	s_cselect_b32 s11, s46, s50
	s_ashr_i32 s43, s42, 31
	s_lshl_b64 s[48:49], s[42:43], 19
	s_add_u32 s48, s27, s48
	s_addc_u32 s49, s29, s49
	s_and_b64 s[54:55], s[6:7], exec
	s_cselect_b32 s20, s49, s53
	s_cselect_b32 s33, s48, s52
	s_add_u32 s50, s50, 0x40080
	s_addc_u32 s51, s51, 0
	s_add_u32 s43, s52, 0x100
	v_mov_b32_e32 v0, 0
	s_addc_u32 s45, s53, 0
	s_mov_b32 s66, -2
	v_mov_b32_e32 v1, v0
	s_waitcnt lgkmcnt(0)
	v_mov_b32_e32 v2, v0
	v_mov_b32_e32 v3, v0
	v_mov_b32_e32 v4, v0
	v_mov_b32_e32 v5, v0
	v_mov_b32_e32 v6, v0
	v_mov_b32_e32 v7, v0
	v_mov_b32_e32 v16, v0
	v_mov_b32_e32 v17, v0
	v_mov_b32_e32 v18, v0
	v_mov_b32_e32 v19, v0
	v_mov_b32_e32 v20, v0
	v_mov_b32_e32 v21, v0
	v_mov_b32_e32 v22, v0
	v_mov_b32_e32 v23, v0
	v_mov_b32_e32 v32, v0
	v_mov_b32_e32 v33, v0
	v_mov_b32_e32 v34, v0
	v_mov_b32_e32 v35, v0
	v_mov_b32_e32 v36, v0
	v_mov_b32_e32 v37, v0
	v_mov_b32_e32 v38, v0
	v_mov_b32_e32 v39, v0
	s_waitcnt vmcnt(0)
	v_mov_b32_e32 v48, v0
	v_mov_b32_e32 v49, v0
	v_mov_b32_e32 v50, v0
	v_mov_b32_e32 v51, v0
	v_mov_b32_e32 v52, v0
	v_mov_b32_e32 v53, v0
	v_mov_b32_e32 v54, v0
	v_mov_b32_e32 v55, v0
	v_mov_b32_e32 v8, v0
	v_mov_b32_e32 v9, v0
	v_mov_b32_e32 v10, v0
	v_mov_b32_e32 v11, v0
	v_mov_b32_e32 v12, v0
	v_mov_b32_e32 v13, v0
	v_mov_b32_e32 v14, v0
	v_mov_b32_e32 v15, v0
	v_mov_b32_e32 v24, v0
	v_mov_b32_e32 v25, v0
	v_mov_b32_e32 v26, v0
	v_mov_b32_e32 v27, v0
	v_mov_b32_e32 v28, v0
	v_mov_b32_e32 v29, v0
	v_mov_b32_e32 v30, v0
	v_mov_b32_e32 v31, v0
	v_mov_b32_e32 v40, v0
	v_mov_b32_e32 v41, v0
	v_mov_b32_e32 v42, v0
	v_mov_b32_e32 v43, v0
	v_mov_b32_e32 v44, v0
	v_mov_b32_e32 v45, v0
	v_mov_b32_e32 v46, v0
	v_mov_b32_e32 v47, v0
	v_mov_b32_e32 v56, v0
	v_mov_b32_e32 v57, v0
	v_mov_b32_e32 v58, v0
	v_mov_b32_e32 v59, v0
	v_mov_b32_e32 v60, v0
	v_mov_b32_e32 v61, v0
	v_mov_b32_e32 v62, v0
	v_mov_b32_e32 v63, v0
	v_mov_b32_e32 v64, v0
	v_mov_b32_e32 v65, v0
	v_mov_b32_e32 v66, v0
	v_mov_b32_e32 v67, v0
	v_mov_b32_e32 v68, v0
	v_mov_b32_e32 v69, v0
	v_mov_b32_e32 v70, v0
	v_mov_b32_e32 v71, v0
	v_mov_b32_e32 v80, v0
	v_mov_b32_e32 v81, v0
	v_mov_b32_e32 v82, v0
	v_mov_b32_e32 v83, v0
	v_mov_b32_e32 v84, v0
	v_mov_b32_e32 v85, v0
	v_mov_b32_e32 v86, v0
	v_mov_b32_e32 v87, v0
	v_mov_b32_e32 v96, v0
	v_mov_b32_e32 v97, v0
	v_mov_b32_e32 v98, v0
	v_mov_b32_e32 v99, v0
	v_mov_b32_e32 v100, v0
	v_mov_b32_e32 v101, v0
	v_mov_b32_e32 v102, v0
	v_mov_b32_e32 v103, v0
	v_mov_b32_e32 v112, v0
	v_mov_b32_e32 v113, v0
	v_mov_b32_e32 v114, v0
	v_mov_b32_e32 v115, v0
	v_mov_b32_e32 v116, v0
	v_mov_b32_e32 v117, v0
	v_mov_b32_e32 v118, v0
	v_mov_b32_e32 v119, v0
	v_mov_b32_e32 v72, v0
	v_mov_b32_e32 v73, v0
	v_mov_b32_e32 v74, v0
	v_mov_b32_e32 v75, v0
	v_mov_b32_e32 v76, v0
	v_mov_b32_e32 v77, v0
	v_mov_b32_e32 v78, v0
	v_mov_b32_e32 v79, v0
	v_mov_b32_e32 v88, v0
	v_mov_b32_e32 v89, v0
	v_mov_b32_e32 v90, v0
	v_mov_b32_e32 v91, v0
	v_mov_b32_e32 v92, v0
	v_mov_b32_e32 v93, v0
	v_mov_b32_e32 v94, v0
	v_mov_b32_e32 v95, v0
	v_mov_b32_e32 v104, v0
	v_mov_b32_e32 v105, v0
	v_mov_b32_e32 v106, v0
	v_mov_b32_e32 v107, v0
	v_mov_b32_e32 v108, v0
	v_mov_b32_e32 v109, v0
	v_mov_b32_e32 v110, v0
	v_mov_b32_e32 v111, v0
	v_mov_b32_e32 v120, v0
	v_mov_b32_e32 v121, v0
	v_mov_b32_e32 v122, v0
	v_mov_b32_e32 v123, v0
	v_mov_b32_e32 v124, v0
	v_mov_b32_e32 v125, v0
	v_mov_b32_e32 v126, v0
	v_mov_b32_e32 v127, v0
	s_cmp_lg_u32 s90, 0
	s_cbranch_scc0 .Lkl_nobar_0
	s_barrier
	s_mov_b32 s90, 0
.Lkl_nobar_0:
.LBB0_220:
	ds_read_b128 v[148:151], v173
	ds_read_b128 v[152:155], v173 offset:1024
	ds_read_b128 v[156:159], v173 offset:2048
	ds_read_b128 v[160:163], v173 offset:3072
	ds_read_b128 v[164:167], v174
	ds_read_b128 v[180:183], v174 offset:1024
	ds_read_b128 v[184:187], v174 offset:2048
	ds_read_b128 v[188:191], v174 offset:3072
	s_add_u32 s52, s50, 0xfffc0080
	s_addc_u32 s53, s51, -1
	s_cmp_eq_u32 s66, 12
	s_cselect_b32 s55, s9, s53
	s_cselect_b32 s54, s11, s52
	s_cselect_b32 s53, s20, s45
	s_cselect_b32 s52, s33, s43
	v_lshl_add_u64 v[168:169], s[50:51], 0, v[140:141]
	s_add_i32 m0, s35, 0xc000
	ds_read_b128 v[192:195], v175
	ds_read_b128 v[196:199], v175 offset:1024
	ds_read_b128 v[204:207], v175 offset:2048
	ds_read_b128 v[208:211], v175 offset:3072
	ds_read_b128 v[212:215], v175 offset:4096
	ds_read_b128 v[216:219], v175 offset:5120
	ds_read_b128 v[220:223], v175 offset:6144
	ds_read_b128 v[224:227], v175 offset:7168
	global_load_lds_dwordx4 v[168:169], off
	s_add_i32 m0, s35, 0xe000
	v_lshl_add_u64 v[168:169], s[50:51], 0, v[142:143]
	global_load_lds_dwordx4 v[168:169], off
	s_waitcnt vmcnt(8) lgkmcnt(0)
	s_setprio 1
	s_barrier
	v_mfma_f32_16x16x32_bf16 v[124:127], v[148:151], v[192:195], v[124:127]
	v_mfma_f32_16x16x32_bf16 v[120:123], v[156:159], v[192:195], v[120:123]
	v_mfma_f32_16x16x32_bf16 v[108:111], v[148:151], v[204:207], v[108:111]
	v_mfma_f32_16x16x32_bf16 v[104:107], v[156:159], v[204:207], v[104:107]
	v_mfma_f32_16x16x32_bf16 v[92:95], v[148:151], v[212:215], v[92:95]
	v_mfma_f32_16x16x32_bf16 v[88:91], v[156:159], v[212:215], v[88:91]
	v_mfma_f32_16x16x32_bf16 v[76:79], v[148:151], v[220:223], v[76:79]
	v_mfma_f32_16x16x32_bf16 v[72:75], v[156:159], v[220:223], v[72:75]
	v_mfma_f32_16x16x32_bf16 v[124:127], v[152:155], v[196:199], v[124:127]
	v_mfma_f32_16x16x32_bf16 v[120:123], v[160:163], v[196:199], v[120:123]
	v_mfma_f32_16x16x32_bf16 v[108:111], v[152:155], v[208:211], v[108:111]
	v_mfma_f32_16x16x32_bf16 v[104:107], v[160:163], v[208:211], v[104:107]
	v_mfma_f32_16x16x32_bf16 v[92:95], v[152:155], v[216:219], v[92:95]
	v_mfma_f32_16x16x32_bf16 v[88:91], v[160:163], v[216:219], v[88:91]
	v_mfma_f32_16x16x32_bf16 v[76:79], v[152:155], v[224:227], v[76:79]
	v_mfma_f32_16x16x32_bf16 v[72:75], v[160:163], v[224:227], v[72:75]
	s_setprio 0
	s_setprio 1
	v_mfma_f32_16x16x32_bf16 v[116:119], v[164:167], v[192:195], v[116:119]
	v_mfma_f32_16x16x32_bf16 v[112:115], v[184:187], v[192:195], v[112:115]
	v_mfma_f32_16x16x32_bf16 v[100:103], v[164:167], v[204:207], v[100:103]
	v_mfma_f32_16x16x32_bf16 v[96:99], v[184:187], v[204:207], v[96:99]
	v_mfma_f32_16x16x32_bf16 v[84:87], v[164:167], v[212:215], v[84:87]
	v_mfma_f32_16x16x32_bf16 v[80:83], v[184:187], v[212:215], v[80:83]
	v_mfma_f32_16x16x32_bf16 v[68:71], v[164:167], v[220:223], v[68:71]
	v_mfma_f32_16x16x32_bf16 v[64:67], v[184:187], v[220:223], v[64:67]
	v_mfma_f32_16x16x32_bf16 v[116:119], v[180:183], v[196:199], v[116:119]
	v_mfma_f32_16x16x32_bf16 v[112:115], v[188:191], v[196:199], v[112:115]
	v_mfma_f32_16x16x32_bf16 v[100:103], v[180:183], v[208:211], v[100:103]
	v_mfma_f32_16x16x32_bf16 v[96:99], v[188:191], v[208:211], v[96:99]
	v_mfma_f32_16x16x32_bf16 v[84:87], v[180:183], v[216:219], v[84:87]
	v_mfma_f32_16x16x32_bf16 v[80:83], v[188:191], v[216:219], v[80:83]
	v_mfma_f32_16x16x32_bf16 v[68:71], v[180:183], v[224:227], v[68:71]
	v_mfma_f32_16x16x32_bf16 v[64:67], v[188:191], v[224:227], v[64:67]
	s_setprio 0
	s_barrier
	s_add_i32 s67, s63, s31
	v_lshl_add_u64 v[168:169], s[52:53], 0, v[130:131]
	s_mov_b32 m0, s67
	ds_read_b128 v[192:195], v175 offset:16384
	ds_read_b128 v[196:199], v175 offset:17408
	ds_read_b128 v[204:207], v175 offset:18432
	ds_read_b128 v[208:211], v175 offset:19456
	ds_read_b128 v[212:215], v175 offset:20480
	ds_read_b128 v[216:219], v175 offset:21504
	ds_read_b128 v[220:223], v175 offset:22528
	ds_read_b128 v[224:227], v175 offset:23552
	global_load_lds_dwordx4 v[168:169], off
	s_add_i32 m0, s67, 0x2000
	s_add_u32 s68, s52, 0x40000
	v_lshl_add_u64 v[200:201], s[52:53], 0, v[134:135]
	s_addc_u32 s69, s53, 0
	s_add_i32 s67, s64, s31
	global_load_lds_dwordx4 v[200:201], off
	v_lshl_add_u64 v[228:229], s[68:69], 0, v[130:131]
	s_mov_b32 m0, s67
	v_lshl_add_u64 v[230:231], s[54:55], 0, v[132:133]
	global_load_lds_dwordx4 v[228:229], off
	s_add_i32 m0, s67, 0x2000
	v_lshl_add_u64 v[228:229], s[68:69], 0, v[134:135]
	global_load_lds_dwordx4 v[228:229], off
	s_mov_b32 m0, s35
	v_lshl_add_u64 v[228:229], s[54:55], 0, v[128:129]
	global_load_lds_dwordx4 v[228:229], off
	s_mov_b32 m0, s37
	s_nop 0
	global_load_lds_dwordx4 v[230:231], off
	s_waitcnt vmcnt(8) lgkmcnt(0)
	s_setprio 1
	s_barrier
	v_mfma_f32_16x16x32_bf16 v[60:63], v[148:151], v[192:195], v[60:63]
	v_mfma_f32_16x16x32_bf16 v[56:59], v[156:159], v[192:195], v[56:59]
	v_mfma_f32_16x16x32_bf16 v[44:47], v[148:151], v[204:207], v[44:47]
	v_mfma_f32_16x16x32_bf16 v[40:43], v[156:159], v[204:207], v[40:43]
	v_mfma_f32_16x16x32_bf16 v[28:31], v[148:151], v[212:215], v[28:31]
	v_mfma_f32_16x16x32_bf16 v[24:27], v[156:159], v[212:215], v[24:27]
	v_mfma_f32_16x16x32_bf16 v[12:15], v[148:151], v[220:223], v[12:15]
	v_mfma_f32_16x16x32_bf16 v[8:11], v[156:159], v[220:223], v[8:11]
	v_mfma_f32_16x16x32_bf16 v[60:63], v[152:155], v[196:199], v[60:63]
	v_mfma_f32_16x16x32_bf16 v[56:59], v[160:163], v[196:199], v[56:59]
	v_mfma_f32_16x16x32_bf16 v[44:47], v[152:155], v[208:211], v[44:47]
	v_mfma_f32_16x16x32_bf16 v[40:43], v[160:163], v[208:211], v[40:43]
	v_mfma_f32_16x16x32_bf16 v[28:31], v[152:155], v[216:219], v[28:31]
	v_mfma_f32_16x16x32_bf16 v[24:27], v[160:163], v[216:219], v[24:27]
	v_mfma_f32_16x16x32_bf16 v[12:15], v[152:155], v[224:227], v[12:15]
	v_mfma_f32_16x16x32_bf16 v[8:11], v[160:163], v[224:227], v[8:11]
	s_setprio 0
	s_setprio 1
	v_mfma_f32_16x16x32_bf16 v[52:55], v[164:167], v[192:195], v[52:55]
	v_mfma_f32_16x16x32_bf16 v[48:51], v[184:187], v[192:195], v[48:51]
	v_mfma_f32_16x16x32_bf16 v[36:39], v[164:167], v[204:207], v[36:39]
	v_mfma_f32_16x16x32_bf16 v[32:35], v[184:187], v[204:207], v[32:35]
	v_mfma_f32_16x16x32_bf16 v[20:23], v[164:167], v[212:215], v[20:23]
	v_mfma_f32_16x16x32_bf16 v[16:19], v[184:187], v[212:215], v[16:19]
	v_mfma_f32_16x16x32_bf16 v[4:7], v[164:167], v[220:223], v[4:7]
	v_mfma_f32_16x16x32_bf16 v[0:3], v[184:187], v[220:223], v[0:3]
	v_mfma_f32_16x16x32_bf16 v[52:55], v[180:183], v[196:199], v[52:55]
	v_mfma_f32_16x16x32_bf16 v[48:51], v[188:191], v[196:199], v[48:51]
	v_mfma_f32_16x16x32_bf16 v[36:39], v[180:183], v[208:211], v[36:39]
	v_mfma_f32_16x16x32_bf16 v[32:35], v[188:191], v[208:211], v[32:35]
	v_mfma_f32_16x16x32_bf16 v[20:23], v[180:183], v[216:219], v[20:23]
	v_mfma_f32_16x16x32_bf16 v[16:19], v[188:191], v[216:219], v[16:19]
	v_mfma_f32_16x16x32_bf16 v[4:7], v[180:183], v[224:227], v[4:7]
	v_mfma_f32_16x16x32_bf16 v[0:3], v[188:191], v[224:227], v[0:3]
	s_setprio 0
	s_barrier
	s_add_i32 s67, 0, 0x18000
	v_add_u32_e32 v137, s67, v171
	s_add_i32 s68, 0, 0x1c000
	ds_read_b128 v[148:151], v137
	ds_read_b128 v[152:155], v137 offset:1024
	ds_read_b128 v[156:159], v137 offset:2048
	ds_read_b128 v[160:163], v137 offset:3072
	v_add_u32_e32 v137, s68, v171
	ds_read_b128 v[164:167], v137
	ds_read_b128 v[180:183], v137 offset:1024
	ds_read_b128 v[184:187], v137 offset:2048
	ds_read_b128 v[188:191], v137 offset:3072
	s_add_u32 s54, s54, 0x40000
	s_addc_u32 s55, s55, 0
	s_mov_b32 m0, s39
	v_lshl_add_u64 v[232:233], s[54:55], 0, v[128:129]
	ds_read_b128 v[192:195], v175 offset:32768
	ds_read_b128 v[196:199], v175 offset:33792
	ds_read_b128 v[204:207], v175 offset:34816
	ds_read_b128 v[208:211], v175 offset:35840
	ds_read_b128 v[212:215], v175 offset:36864
	ds_read_b128 v[216:219], v175 offset:37888
	ds_read_b128 v[220:223], v175 offset:38912
	ds_read_b128 v[224:227], v175 offset:39936
	global_load_lds_dwordx4 v[232:233], off
	s_mov_b32 m0, s41
	v_lshl_add_u64 v[232:233], s[54:55], 0, v[132:133]
	global_load_lds_dwordx4 v[232:233], off
	s_waitcnt vmcnt(8) lgkmcnt(0)
	s_setprio 1
	s_barrier
	v_mfma_f32_16x16x32_bf16 v[124:127], v[148:151], v[192:195], v[124:127]
	v_mfma_f32_16x16x32_bf16 v[120:123], v[156:159], v[192:195], v[120:123]
	v_mfma_f32_16x16x32_bf16 v[108:111], v[148:151], v[204:207], v[108:111]
	v_mfma_f32_16x16x32_bf16 v[104:107], v[156:159], v[204:207], v[104:107]
	v_mfma_f32_16x16x32_bf16 v[92:95], v[148:151], v[212:215], v[92:95]
	v_mfma_f32_16x16x32_bf16 v[88:91], v[156:159], v[212:215], v[88:91]
	v_mfma_f32_16x16x32_bf16 v[76:79], v[148:151], v[220:223], v[76:79]
	v_mfma_f32_16x16x32_bf16 v[72:75], v[156:159], v[220:223], v[72:75]
	v_mfma_f32_16x16x32_bf16 v[124:127], v[152:155], v[196:199], v[124:127]
	v_mfma_f32_16x16x32_bf16 v[120:123], v[160:163], v[196:199], v[120:123]
	v_mfma_f32_16x16x32_bf16 v[108:111], v[152:155], v[208:211], v[108:111]
	v_mfma_f32_16x16x32_bf16 v[104:107], v[160:163], v[208:211], v[104:107]
	v_mfma_f32_16x16x32_bf16 v[92:95], v[152:155], v[216:219], v[92:95]
	v_mfma_f32_16x16x32_bf16 v[88:91], v[160:163], v[216:219], v[88:91]
	v_mfma_f32_16x16x32_bf16 v[76:79], v[152:155], v[224:227], v[76:79]
	v_mfma_f32_16x16x32_bf16 v[72:75], v[160:163], v[224:227], v[72:75]
	s_setprio 0
	s_setprio 1
	v_mfma_f32_16x16x32_bf16 v[116:119], v[164:167], v[192:195], v[116:119]
	v_mfma_f32_16x16x32_bf16 v[112:115], v[184:187], v[192:195], v[112:115]
	v_mfma_f32_16x16x32_bf16 v[100:103], v[164:167], v[204:207], v[100:103]
	v_mfma_f32_16x16x32_bf16 v[96:99], v[184:187], v[204:207], v[96:99]
	v_mfma_f32_16x16x32_bf16 v[84:87], v[164:167], v[212:215], v[84:87]
	v_mfma_f32_16x16x32_bf16 v[80:83], v[184:187], v[212:215], v[80:83]
	v_mfma_f32_16x16x32_bf16 v[68:71], v[164:167], v[220:223], v[68:71]
	v_mfma_f32_16x16x32_bf16 v[64:67], v[184:187], v[220:223], v[64:67]
	v_mfma_f32_16x16x32_bf16 v[116:119], v[180:183], v[196:199], v[116:119]
	v_mfma_f32_16x16x32_bf16 v[112:115], v[188:191], v[196:199], v[112:115]
	v_mfma_f32_16x16x32_bf16 v[100:103], v[180:183], v[208:211], v[100:103]
	v_mfma_f32_16x16x32_bf16 v[96:99], v[188:191], v[208:211], v[96:99]
	v_mfma_f32_16x16x32_bf16 v[84:87], v[180:183], v[216:219], v[84:87]
	v_mfma_f32_16x16x32_bf16 v[80:83], v[188:191], v[216:219], v[80:83]
	v_mfma_f32_16x16x32_bf16 v[68:71], v[180:183], v[224:227], v[68:71]
	v_mfma_f32_16x16x32_bf16 v[64:67], v[188:191], v[224:227], v[64:67]
	s_setprio 0
	s_barrier
	s_add_i32 s54, s67, s31
	v_lshl_add_u64 v[168:169], v[168:169], 0, s[22:23]
	s_mov_b32 m0, s54
	ds_read_b128 v[192:195], v175 offset:49152
	ds_read_b128 v[196:199], v175 offset:50176
	ds_read_b128 v[204:207], v175 offset:51200
	ds_read_b128 v[208:211], v175 offset:52224
	ds_read_b128 v[212:215], v175 offset:53248
	ds_read_b128 v[216:219], v175 offset:54272
	ds_read_b128 v[220:223], v175 offset:55296
	ds_read_b128 v[224:227], v175 offset:56320
	global_load_lds_dwordx4 v[168:169], off
	s_add_i32 m0, s54, 0x2000
	s_add_u32 s52, s52, 0x40080
	v_lshl_add_u64 v[168:169], v[200:201], 0, s[22:23]
	s_addc_u32 s53, s53, 0
	s_add_i32 s54, s68, s31
	global_load_lds_dwordx4 v[168:169], off
	s_mov_b32 m0, s54
	v_lshl_add_u64 v[168:169], s[52:53], 0, v[130:131]
	global_load_lds_dwordx4 v[168:169], off
	s_add_i32 m0, s54, 0x2000
	v_lshl_add_u64 v[168:169], s[52:53], 0, v[134:135]
	global_load_lds_dwordx4 v[168:169], off
	s_mov_b32 m0, s60
	v_lshl_add_u64 v[168:169], v[228:229], 0, s[22:23]
	global_load_lds_dwordx4 v[168:169], off
	s_mov_b32 m0, s61
	v_lshl_add_u64 v[168:169], v[230:231], 0, s[22:23]
	global_load_lds_dwordx4 v[168:169], off
	s_waitcnt vmcnt(8) lgkmcnt(0)
	s_setprio 1
	s_barrier
	v_mfma_f32_16x16x32_bf16 v[60:63], v[148:151], v[192:195], v[60:63]
	v_mfma_f32_16x16x32_bf16 v[56:59], v[156:159], v[192:195], v[56:59]
	v_mfma_f32_16x16x32_bf16 v[44:47], v[148:151], v[204:207], v[44:47]
	v_mfma_f32_16x16x32_bf16 v[40:43], v[156:159], v[204:207], v[40:43]
	v_mfma_f32_16x16x32_bf16 v[28:31], v[148:151], v[212:215], v[28:31]
	v_mfma_f32_16x16x32_bf16 v[24:27], v[156:159], v[212:215], v[24:27]
	v_mfma_f32_16x16x32_bf16 v[12:15], v[148:151], v[220:223], v[12:15]
	v_mfma_f32_16x16x32_bf16 v[8:11], v[156:159], v[220:223], v[8:11]
	v_mfma_f32_16x16x32_bf16 v[60:63], v[152:155], v[196:199], v[60:63]
	v_mfma_f32_16x16x32_bf16 v[56:59], v[160:163], v[196:199], v[56:59]
	v_mfma_f32_16x16x32_bf16 v[44:47], v[152:155], v[208:211], v[44:47]
	v_mfma_f32_16x16x32_bf16 v[40:43], v[160:163], v[208:211], v[40:43]
	v_mfma_f32_16x16x32_bf16 v[28:31], v[152:155], v[216:219], v[28:31]
	v_mfma_f32_16x16x32_bf16 v[24:27], v[160:163], v[216:219], v[24:27]
	v_mfma_f32_16x16x32_bf16 v[12:15], v[152:155], v[224:227], v[12:15]
	v_mfma_f32_16x16x32_bf16 v[8:11], v[160:163], v[224:227], v[8:11]
	s_setprio 0
	s_setprio 1
	v_mfma_f32_16x16x32_bf16 v[52:55], v[164:167], v[192:195], v[52:55]
	v_mfma_f32_16x16x32_bf16 v[48:51], v[184:187], v[192:195], v[48:51]
	v_mfma_f32_16x16x32_bf16 v[36:39], v[164:167], v[204:207], v[36:39]
	v_mfma_f32_16x16x32_bf16 v[32:35], v[184:187], v[204:207], v[32:35]
	v_mfma_f32_16x16x32_bf16 v[20:23], v[164:167], v[212:215], v[20:23]
	v_mfma_f32_16x16x32_bf16 v[16:19], v[184:187], v[212:215], v[16:19]
	v_mfma_f32_16x16x32_bf16 v[4:7], v[164:167], v[220:223], v[4:7]
	v_mfma_f32_16x16x32_bf16 v[0:3], v[184:187], v[220:223], v[0:3]
	v_mfma_f32_16x16x32_bf16 v[52:55], v[180:183], v[196:199], v[52:55]
	v_mfma_f32_16x16x32_bf16 v[48:51], v[188:191], v[196:199], v[48:51]
	v_mfma_f32_16x16x32_bf16 v[36:39], v[180:183], v[208:211], v[36:39]
	v_mfma_f32_16x16x32_bf16 v[32:35], v[188:191], v[208:211], v[32:35]
	v_mfma_f32_16x16x32_bf16 v[20:23], v[180:183], v[216:219], v[20:23]
	v_mfma_f32_16x16x32_bf16 v[16:19], v[188:191], v[216:219], v[16:19]
	v_mfma_f32_16x16x32_bf16 v[4:7], v[180:183], v[224:227], v[4:7]
	v_mfma_f32_16x16x32_bf16 v[0:3], v[188:191], v[224:227], v[0:3]
	s_setprio 0
	s_add_i32 s66, s66, 2
	s_add_u32 s50, s50, 0x100
	s_addc_u32 s51, s51, 0
	s_add_u32 s43, s43, 0x100
	s_addc_u32 s45, s45, 0
	s_cmp_gt_u32 s66, 13
	s_barrier
	s_cbranch_scc0 .LBB0_220
	s_and_b64 vcc, exec, s[24:25]
	s_cbranch_vccz .LBB0_223
	s_barrier

.LBB0_271:
	s_andn2_b64 vcc, exec, s[6:7]
	s_mov_b64 s[6:7], -1
	s_cbranch_vccnz .LBB0_212
	s_andn2_b64 vcc, exec, s[12:13]
	s_cbranch_vccnz .LBB0_211
	s_mov_b32 s90, 1
	s_branch .LBB0_211

.LBB0_386:
	s_mov_b32 s90, 0
	s_or_b64 exec, exec, s[4:5]
	s_cmpk_lt_i32 s2, 0x200
	s_mov_b64 s[4:5], s[0:1]
	s_waitcnt lgkmcnt(0)
	v_mov_b32_e32 v0, v202
	v_mov_b32_e32 v8, v202
	s_barrier
	s_cselect_b64 s[6:7], -1, 0
	s_cmpk_gt_i32 s2, 0x1ff
	s_nop 0
	v_readfirstlane_b32 s8, v8
	s_cbranch_scc1 .LBB0_388
	s_lshr_b32 s9, s21, 29
	s_add_i32 s9, s2, s9
	s_and_b32 s10, s9, -8
	s_sub_i32 s10, s2, s10
	s_lshl_b32 s12, s10, 6
	s_ashr_i32 s9, s9, 3
	s_mul_i32 s11, s10, 0x41
	s_cmp_lt_i32 s10, 0
	s_cselect_b32 s10, s11, s12
	s_add_i32 s9, s10, s9
	s_ashr_i32 s10, s9, 31
	s_lshr_b32 s10, s10, 27
	s_add_i32 s10, s9, s10
	s_ashr_i32 s11, s10, 5
	s_andn2_b32 s10, s10, 31
	s_sub_i32 s9, s9, s10
	s_bfe_i32 s10, s9, 0x80000
	s_bfe_u32 s10, s10, 0x3000c
	s_add_i32 s10, s9, s10
	s_bfe_i32 s12, s10, 0x80000
	s_and_b32 s10, s10, 0xf8
	s_sub_i32 s9, s9, s10
	s_lshl_b32 s11, s11, 3
	s_sext_i32_i16 s12, s12
	s_sext_i32_i8 s9, s9
	s_add_i32 s40, s11, s9
	s_ashr_i32 s10, s12, 3

.LBB0_400:
	s_ashr_i32 s35, s34, 31
	s_lshl_b64 s[36:37], s[34:35], 20
	s_add_u32 s36, s14, s36
	s_addc_u32 s37, s15, s37
	s_and_b64 s[38:39], s[8:9], exec
	s_cselect_b32 s35, s37, s43
	s_cselect_b32 s41, s36, s42
	s_ashr_i32 s31, s30, 31
	s_lshl_b64 s[38:39], s[30:31], 20
	s_add_u32 s38, s20, s38
	s_addc_u32 s39, s25, s39
	s_and_b64 s[44:45], s[8:9], exec
	s_cselect_b32 s31, s39, s5
	s_cselect_b32 s56, s38, s4
	s_add_u32 s42, s42, 0x80080
	s_addc_u32 s43, s43, 0
	s_add_u32 s57, s4, 0x100
	v_mov_b32_e32 v0, 0
	s_addc_u32 s58, s5, 0
	s_mov_b32 s59, -2
	s_waitcnt lgkmcnt(0)
	v_mov_b32_e32 v1, v0
	v_mov_b32_e32 v2, v0
	v_mov_b32_e32 v3, v0
	v_mov_b32_e32 v4, v0
	v_mov_b32_e32 v5, v0
	v_mov_b32_e32 v6, v0
	v_mov_b32_e32 v7, v0
	v_mov_b32_e32 v16, v0
	v_mov_b32_e32 v17, v0
	v_mov_b32_e32 v18, v0
	v_mov_b32_e32 v19, v0
	v_mov_b32_e32 v20, v0
	v_mov_b32_e32 v21, v0
	v_mov_b32_e32 v22, v0
	v_mov_b32_e32 v23, v0
	v_mov_b32_e32 v32, v0
	v_mov_b32_e32 v33, v0
	v_mov_b32_e32 v34, v0
	v_mov_b32_e32 v35, v0
	v_mov_b32_e32 v36, v0
	v_mov_b32_e32 v37, v0
	v_mov_b32_e32 v38, v0
	v_mov_b32_e32 v39, v0
	s_waitcnt vmcnt(0)
	v_mov_b32_e32 v48, v0
	v_mov_b32_e32 v49, v0
	v_mov_b32_e32 v50, v0
	v_mov_b32_e32 v51, v0
	v_mov_b32_e32 v52, v0
	v_mov_b32_e32 v53, v0
	v_mov_b32_e32 v54, v0
	v_mov_b32_e32 v55, v0
	v_mov_b32_e32 v8, v0
	v_mov_b32_e32 v9, v0
	v_mov_b32_e32 v10, v0
	v_mov_b32_e32 v11, v0
	v_mov_b32_e32 v12, v0
	v_mov_b32_e32 v13, v0
	v_mov_b32_e32 v14, v0
	v_mov_b32_e32 v15, v0
	v_mov_b32_e32 v24, v0
	v_mov_b32_e32 v25, v0
	v_mov_b32_e32 v26, v0
	v_mov_b32_e32 v27, v0
	v_mov_b32_e32 v28, v0
	v_mov_b32_e32 v29, v0
	v_mov_b32_e32 v30, v0
	v_mov_b32_e32 v31, v0
	v_mov_b32_e32 v40, v0
	v_mov_b32_e32 v41, v0
	v_mov_b32_e32 v42, v0
	v_mov_b32_e32 v43, v0
	v_mov_b32_e32 v44, v0
	v_mov_b32_e32 v45, v0
	v_mov_b32_e32 v46, v0
	v_mov_b32_e32 v47, v0
	v_mov_b32_e32 v56, v0
	v_mov_b32_e32 v57, v0
	v_mov_b32_e32 v58, v0
	v_mov_b32_e32 v59, v0
	v_mov_b32_e32 v60, v0
	v_mov_b32_e32 v61, v0
	v_mov_b32_e32 v62, v0
	v_mov_b32_e32 v63, v0
	v_mov_b32_e32 v64, v0
	v_mov_b32_e32 v65, v0
	v_mov_b32_e32 v66, v0
	v_mov_b32_e32 v67, v0
	v_mov_b32_e32 v68, v0
	v_mov_b32_e32 v69, v0
	v_mov_b32_e32 v70, v0
	v_mov_b32_e32 v71, v0
	v_mov_b32_e32 v80, v0
	v_mov_b32_e32 v81, v0
	v_mov_b32_e32 v82, v0
	v_mov_b32_e32 v83, v0
	v_mov_b32_e32 v84, v0
	v_mov_b32_e32 v85, v0
	v_mov_b32_e32 v86, v0
	v_mov_b32_e32 v87, v0
	v_mov_b32_e32 v96, v0
	v_mov_b32_e32 v97, v0
	v_mov_b32_e32 v98, v0
	v_mov_b32_e32 v99, v0
	v_mov_b32_e32 v100, v0
	v_mov_b32_e32 v101, v0
	v_mov_b32_e32 v102, v0
	v_mov_b32_e32 v103, v0
	v_mov_b32_e32 v112, v0
	v_mov_b32_e32 v113, v0
	v_mov_b32_e32 v114, v0
	v_mov_b32_e32 v115, v0
	v_mov_b32_e32 v116, v0
	v_mov_b32_e32 v117, v0
	v_mov_b32_e32 v118, v0
	v_mov_b32_e32 v119, v0
	v_mov_b32_e32 v72, v0
	v_mov_b32_e32 v73, v0
	v_mov_b32_e32 v74, v0
	v_mov_b32_e32 v75, v0
	v_mov_b32_e32 v76, v0
	v_mov_b32_e32 v77, v0
	v_mov_b32_e32 v78, v0
	v_mov_b32_e32 v79, v0
	v_mov_b32_e32 v88, v0
	v_mov_b32_e32 v89, v0
	v_mov_b32_e32 v90, v0
	v_mov_b32_e32 v91, v0
	v_mov_b32_e32 v92, v0
	v_mov_b32_e32 v93, v0
	v_mov_b32_e32 v94, v0
	v_mov_b32_e32 v95, v0
	v_mov_b32_e32 v104, v0
	v_mov_b32_e32 v105, v0
	v_mov_b32_e32 v106, v0
	v_mov_b32_e32 v107, v0
	v_mov_b32_e32 v108, v0
	v_mov_b32_e32 v109, v0
	v_mov_b32_e32 v110, v0
	v_mov_b32_e32 v111, v0
	v_mov_b32_e32 v120, v0
	v_mov_b32_e32 v121, v0
	v_mov_b32_e32 v122, v0
	v_mov_b32_e32 v123, v0
	v_mov_b32_e32 v124, v0
	v_mov_b32_e32 v125, v0
	v_mov_b32_e32 v126, v0
	v_mov_b32_e32 v127, v0
	s_cmp_lg_u32 s90, 0
	s_cbranch_scc0 .Lkl_nobar_1
	s_barrier
	s_mov_b32 s90, 0
.Lkl_nobar_1:
.LBB0_401:
	ds_read_b128 v[128:131], v189
	ds_read_b128 v[132:135], v189 offset:1024
	ds_read_b128 v[136:139], v189 offset:2048
	ds_read_b128 v[140:143], v189 offset:3072
	ds_read_b128 v[144:147], v190
	ds_read_b128 v[148:151], v190 offset:1024
	ds_read_b128 v[168:171], v190 offset:2048
	ds_read_b128 v[172:175], v190 offset:3072
	s_add_u32 s4, s42, 0xfff80080
	s_addc_u32 s5, s43, -1
	s_cmp_eq_u32 s59, 28
	s_cselect_b32 s45, s35, s5
	s_cselect_b32 s44, s41, s4
	s_cselect_b32 s5, s31, s58
	s_cselect_b32 s4, s56, s57
	v_lshl_add_u64 v[184:185], s[42:43], 0, v[160:161]
	s_add_i32 m0, s47, 0xc000
	ds_read_b128 v[176:179], v191
	ds_read_b128 v[180:183], v191 offset:1024
	ds_read_b128 v[194:197], v191 offset:2048
	ds_read_b128 v[198:201], v191 offset:3072
	ds_read_b128 v[204:207], v191 offset:4096
	ds_read_b128 v[208:211], v191 offset:5120
	ds_read_b128 v[212:215], v191 offset:6144
	ds_read_b128 v[216:219], v191 offset:7168
	global_load_lds_dwordx4 v[184:185], off
	s_add_i32 m0, s47, 0xe000
	v_lshl_add_u64 v[184:185], s[42:43], 0, v[162:163]
	global_load_lds_dwordx4 v[184:185], off
	s_waitcnt vmcnt(8) lgkmcnt(0)
	s_setprio 1
	s_barrier
	v_mfma_f32_16x16x32_bf16 v[124:127], v[128:131], v[176:179], v[124:127]
	v_mfma_f32_16x16x32_bf16 v[120:123], v[136:139], v[176:179], v[120:123]
	v_mfma_f32_16x16x32_bf16 v[108:111], v[128:131], v[194:197], v[108:111]
	v_mfma_f32_16x16x32_bf16 v[104:107], v[136:139], v[194:197], v[104:107]
	v_mfma_f32_16x16x32_bf16 v[92:95], v[128:131], v[204:207], v[92:95]
	v_mfma_f32_16x16x32_bf16 v[88:91], v[136:139], v[204:207], v[88:91]
	v_mfma_f32_16x16x32_bf16 v[76:79], v[128:131], v[212:215], v[76:79]
	v_mfma_f32_16x16x32_bf16 v[72:75], v[136:139], v[212:215], v[72:75]
	v_mfma_f32_16x16x32_bf16 v[124:127], v[132:135], v[180:183], v[124:127]
	v_mfma_f32_16x16x32_bf16 v[120:123], v[140:143], v[180:183], v[120:123]
	v_mfma_f32_16x16x32_bf16 v[108:111], v[132:135], v[198:201], v[108:111]
	v_mfma_f32_16x16x32_bf16 v[104:107], v[140:143], v[198:201], v[104:107]
	v_mfma_f32_16x16x32_bf16 v[92:95], v[132:135], v[208:211], v[92:95]
	v_mfma_f32_16x16x32_bf16 v[88:91], v[140:143], v[208:211], v[88:91]
	v_mfma_f32_16x16x32_bf16 v[76:79], v[132:135], v[216:219], v[76:79]
	v_mfma_f32_16x16x32_bf16 v[72:75], v[140:143], v[216:219], v[72:75]
	s_setprio 0
	s_setprio 1
	v_mfma_f32_16x16x32_bf16 v[116:119], v[144:147], v[176:179], v[116:119]
	v_mfma_f32_16x16x32_bf16 v[112:115], v[168:171], v[176:179], v[112:115]
	v_mfma_f32_16x16x32_bf16 v[100:103], v[144:147], v[194:197], v[100:103]
	v_mfma_f32_16x16x32_bf16 v[96:99], v[168:171], v[194:197], v[96:99]
	v_mfma_f32_16x16x32_bf16 v[84:87], v[144:147], v[204:207], v[84:87]
	v_mfma_f32_16x16x32_bf16 v[80:83], v[168:171], v[204:207], v[80:83]
	v_mfma_f32_16x16x32_bf16 v[68:71], v[144:147], v[212:215], v[68:71]
	v_mfma_f32_16x16x32_bf16 v[64:67], v[168:171], v[212:215], v[64:67]
	v_mfma_f32_16x16x32_bf16 v[116:119], v[148:151], v[180:183], v[116:119]
	v_mfma_f32_16x16x32_bf16 v[112:115], v[172:175], v[180:183], v[112:115]
	v_mfma_f32_16x16x32_bf16 v[100:103], v[148:151], v[198:201], v[100:103]
	v_mfma_f32_16x16x32_bf16 v[96:99], v[172:175], v[198:201], v[96:99]
	v_mfma_f32_16x16x32_bf16 v[84:87], v[148:151], v[208:211], v[84:87]
	v_mfma_f32_16x16x32_bf16 v[80:83], v[172:175], v[208:211], v[80:83]
	v_mfma_f32_16x16x32_bf16 v[68:71], v[148:151], v[216:219], v[68:71]
	v_mfma_f32_16x16x32_bf16 v[64:67], v[172:175], v[216:219], v[64:67]
	s_setprio 0
	s_barrier
	s_add_i32 s60, s53, s46
	v_lshl_add_u64 v[184:185], s[4:5], 0, v[154:155]
	s_mov_b32 m0, s60
	ds_read_b128 v[176:179], v191 offset:16384
	ds_read_b128 v[180:183], v191 offset:17408
	ds_read_b128 v[194:197], v191 offset:18432
	ds_read_b128 v[198:201], v191 offset:19456
	ds_read_b128 v[204:207], v191 offset:20480
	ds_read_b128 v[208:211], v191 offset:21504
	ds_read_b128 v[212:215], v191 offset:22528
	ds_read_b128 v[216:219], v191 offset:23552
	global_load_lds_dwordx4 v[184:185], off
	s_add_i32 m0, s60, 0x2000
	s_add_u32 s60, s4, 0x80000
	v_lshl_add_u64 v[220:221], s[4:5], 0, v[158:159]
	s_addc_u32 s61, s5, 0
	s_add_i32 s62, s54, s46
	global_load_lds_dwordx4 v[220:221], off
	v_lshl_add_u64 v[222:223], s[60:61], 0, v[154:155]
	s_mov_b32 m0, s62
	v_lshl_add_u64 v[224:225], s[44:45], 0, v[156:157]
	global_load_lds_dwordx4 v[222:223], off
	s_add_i32 m0, s62, 0x2000
	v_lshl_add_u64 v[222:223], s[60:61], 0, v[158:159]
	global_load_lds_dwordx4 v[222:223], off
	s_mov_b32 m0, s47
	v_lshl_add_u64 v[222:223], s[44:45], 0, v[152:153]
	global_load_lds_dwordx4 v[222:223], off
	s_mov_b32 m0, s48
	s_nop 0
	global_load_lds_dwordx4 v[224:225], off
	s_waitcnt vmcnt(8) lgkmcnt(0)
	s_setprio 1
	s_barrier
	v_mfma_f32_16x16x32_bf16 v[60:63], v[128:131], v[176:179], v[60:63]
	v_mfma_f32_16x16x32_bf16 v[56:59], v[136:139], v[176:179], v[56:59]
	v_mfma_f32_16x16x32_bf16 v[44:47], v[128:131], v[194:197], v[44:47]
	v_mfma_f32_16x16x32_bf16 v[40:43], v[136:139], v[194:197], v[40:43]
	v_mfma_f32_16x16x32_bf16 v[28:31], v[128:131], v[204:207], v[28:31]
	v_mfma_f32_16x16x32_bf16 v[24:27], v[136:139], v[204:207], v[24:27]
	v_mfma_f32_16x16x32_bf16 v[12:15], v[128:131], v[212:215], v[12:15]
	v_mfma_f32_16x16x32_bf16 v[8:11], v[136:139], v[212:215], v[8:11]
	v_mfma_f32_16x16x32_bf16 v[60:63], v[132:135], v[180:183], v[60:63]
	v_mfma_f32_16x16x32_bf16 v[56:59], v[140:143], v[180:183], v[56:59]
	v_mfma_f32_16x16x32_bf16 v[44:47], v[132:135], v[198:201], v[44:47]
	v_mfma_f32_16x16x32_bf16 v[40:43], v[140:143], v[198:201], v[40:43]
	v_mfma_f32_16x16x32_bf16 v[28:31], v[132:135], v[208:211], v[28:31]
	v_mfma_f32_16x16x32_bf16 v[24:27], v[140:143], v[208:211], v[24:27]
	v_mfma_f32_16x16x32_bf16 v[12:15], v[132:135], v[216:219], v[12:15]
	v_mfma_f32_16x16x32_bf16 v[8:11], v[140:143], v[216:219], v[8:11]
	s_setprio 0
	s_setprio 1
	v_mfma_f32_16x16x32_bf16 v[52:55], v[144:147], v[176:179], v[52:55]
	v_mfma_f32_16x16x32_bf16 v[48:51], v[168:171], v[176:179], v[48:51]
	v_mfma_f32_16x16x32_bf16 v[36:39], v[144:147], v[194:197], v[36:39]
	v_mfma_f32_16x16x32_bf16 v[32:35], v[168:171], v[194:197], v[32:35]
	v_mfma_f32_16x16x32_bf16 v[20:23], v[144:147], v[204:207], v[20:23]
	v_mfma_f32_16x16x32_bf16 v[16:19], v[168:171], v[204:207], v[16:19]
	v_mfma_f32_16x16x32_bf16 v[4:7], v[144:147], v[212:215], v[4:7]
	v_mfma_f32_16x16x32_bf16 v[0:3], v[168:171], v[212:215], v[0:3]
	v_mfma_f32_16x16x32_bf16 v[52:55], v[148:151], v[180:183], v[52:55]
	v_mfma_f32_16x16x32_bf16 v[48:51], v[172:175], v[180:183], v[48:51]
	v_mfma_f32_16x16x32_bf16 v[36:39], v[148:151], v[198:201], v[36:39]
	v_mfma_f32_16x16x32_bf16 v[32:35], v[172:175], v[198:201], v[32:35]
	v_mfma_f32_16x16x32_bf16 v[20:23], v[148:151], v[208:211], v[20:23]
	v_mfma_f32_16x16x32_bf16 v[16:19], v[172:175], v[208:211], v[16:19]
	v_mfma_f32_16x16x32_bf16 v[4:7], v[148:151], v[216:219], v[4:7]
	v_mfma_f32_16x16x32_bf16 v[0:3], v[172:175], v[216:219], v[0:3]
	s_setprio 0
	s_barrier
	s_add_i32 s60, 0, 0x18000
	s_add_i32 s61, 0, 0x1c000
	v_add_u32_e32 v140, s60, v187
	v_add_u32_e32 v172, s61, v187
	ds_read_b128 v[128:131], v140
	ds_read_b128 v[132:135], v140 offset:1024
	ds_read_b128 v[136:139], v140 offset:2048
	ds_read_b128 v[140:143], v140 offset:3072
	ds_read_b128 v[144:147], v172
	ds_read_b128 v[148:151], v172 offset:1024
	ds_read_b128 v[168:171], v172 offset:2048
	ds_read_b128 v[172:175], v172 offset:3072
	s_add_u32 s44, s44, 0x80000
	s_addc_u32 s45, s45, 0
	s_mov_b32 m0, s49
	v_lshl_add_u64 v[226:227], s[44:45], 0, v[152:153]
	ds_read_b128 v[176:179], v191 offset:32768
	ds_read_b128 v[180:183], v191 offset:33792
	ds_read_b128 v[194:197], v191 offset:34816
	ds_read_b128 v[198:201], v191 offset:35840
	ds_read_b128 v[204:207], v191 offset:36864
	ds_read_b128 v[208:211], v191 offset:37888
	ds_read_b128 v[212:215], v191 offset:38912
	ds_read_b128 v[216:219], v191 offset:39936
	global_load_lds_dwordx4 v[226:227], off
	s_mov_b32 m0, s50
	v_lshl_add_u64 v[226:227], s[44:45], 0, v[156:157]
	global_load_lds_dwordx4 v[226:227], off
	s_waitcnt vmcnt(8) lgkmcnt(0)
	s_setprio 1
	s_barrier
	v_mfma_f32_16x16x32_bf16 v[124:127], v[128:131], v[176:179], v[124:127]
	v_mfma_f32_16x16x32_bf16 v[120:123], v[136:139], v[176:179], v[120:123]
	v_mfma_f32_16x16x32_bf16 v[108:111], v[128:131], v[194:197], v[108:111]
	v_mfma_f32_16x16x32_bf16 v[104:107], v[136:139], v[194:197], v[104:107]
	v_mfma_f32_16x16x32_bf16 v[92:95], v[128:131], v[204:207], v[92:95]
	v_mfma_f32_16x16x32_bf16 v[88:91], v[136:139], v[204:207], v[88:91]
	v_mfma_f32_16x16x32_bf16 v[76:79], v[128:131], v[212:215], v[76:79]
	v_mfma_f32_16x16x32_bf16 v[72:75], v[136:139], v[212:215], v[72:75]
	v_mfma_f32_16x16x32_bf16 v[124:127], v[132:135], v[180:183], v[124:127]
	v_mfma_f32_16x16x32_bf16 v[120:123], v[140:143], v[180:183], v[120:123]
	v_mfma_f32_16x16x32_bf16 v[108:111], v[132:135], v[198:201], v[108:111]
	v_mfma_f32_16x16x32_bf16 v[104:107], v[140:143], v[198:201], v[104:107]
	v_mfma_f32_16x16x32_bf16 v[92:95], v[132:135], v[208:211], v[92:95]
	v_mfma_f32_16x16x32_bf16 v[88:91], v[140:143], v[208:211], v[88:91]
	v_mfma_f32_16x16x32_bf16 v[76:79], v[132:135], v[216:219], v[76:79]
	v_mfma_f32_16x16x32_bf16 v[72:75], v[140:143], v[216:219], v[72:75]
	s_setprio 0
	s_setprio 1
	v_mfma_f32_16x16x32_bf16 v[116:119], v[144:147], v[176:179], v[116:119]
	v_mfma_f32_16x16x32_bf16 v[112:115], v[168:171], v[176:179], v[112:115]
	v_mfma_f32_16x16x32_bf16 v[100:103], v[144:147], v[194:197], v[100:103]
	v_mfma_f32_16x16x32_bf16 v[96:99], v[168:171], v[194:197], v[96:99]
	v_mfma_f32_16x16x32_bf16 v[84:87], v[144:147], v[204:207], v[84:87]
	v_mfma_f32_16x16x32_bf16 v[80:83], v[168:171], v[204:207], v[80:83]
	v_mfma_f32_16x16x32_bf16 v[68:71], v[144:147], v[212:215], v[68:71]
	v_mfma_f32_16x16x32_bf16 v[64:67], v[168:171], v[212:215], v[64:67]
	v_mfma_f32_16x16x32_bf16 v[116:119], v[148:151], v[180:183], v[116:119]
	v_mfma_f32_16x16x32_bf16 v[112:115], v[172:175], v[180:183], v[112:115]
	v_mfma_f32_16x16x32_bf16 v[100:103], v[148:151], v[198:201], v[100:103]
	v_mfma_f32_16x16x32_bf16 v[96:99], v[172:175], v[198:201], v[96:99]
	v_mfma_f32_16x16x32_bf16 v[84:87], v[148:151], v[208:211], v[84:87]
	v_mfma_f32_16x16x32_bf16 v[80:83], v[172:175], v[208:211], v[80:83]
	v_mfma_f32_16x16x32_bf16 v[68:71], v[148:151], v[216:219], v[68:71]
	v_mfma_f32_16x16x32_bf16 v[64:67], v[172:175], v[216:219], v[64:67]
	s_setprio 0
	s_barrier
	s_add_i32 s44, s60, s46
	v_lshl_add_u64 v[184:185], v[184:185], 0, s[26:27]
	s_mov_b32 m0, s44
	ds_read_b128 v[176:179], v191 offset:49152
	ds_read_b128 v[180:183], v191 offset:50176
	ds_read_b128 v[194:197], v191 offset:51200
	ds_read_b128 v[198:201], v191 offset:52224
	ds_read_b128 v[204:207], v191 offset:53248
	ds_read_b128 v[208:211], v191 offset:54272
	ds_read_b128 v[212:215], v191 offset:55296
	ds_read_b128 v[216:219], v191 offset:56320
	global_load_lds_dwordx4 v[184:185], off
	s_add_i32 m0, s44, 0x2000
	s_add_u32 s4, s4, 0x80080
	v_lshl_add_u64 v[184:185], v[220:221], 0, s[26:27]
	s_addc_u32 s5, s5, 0
	s_add_i32 s44, s61, s46
	global_load_lds_dwordx4 v[184:185], off
	s_mov_b32 m0, s44
	v_lshl_add_u64 v[184:185], s[4:5], 0, v[154:155]
	global_load_lds_dwordx4 v[184:185], off
	s_add_i32 m0, s44, 0x2000
	v_lshl_add_u64 v[184:185], s[4:5], 0, v[158:159]
	global_load_lds_dwordx4 v[184:185], off
	s_mov_b32 m0, s33
	v_lshl_add_u64 v[184:185], v[222:223], 0, s[26:27]
	global_load_lds_dwordx4 v[184:185], off
	s_mov_b32 m0, s52
	v_lshl_add_u64 v[184:185], v[224:225], 0, s[26:27]
	global_load_lds_dwordx4 v[184:185], off
	s_waitcnt vmcnt(8) lgkmcnt(0)
	s_setprio 1
	s_barrier
	v_mfma_f32_16x16x32_bf16 v[60:63], v[128:131], v[176:179], v[60:63]
	v_mfma_f32_16x16x32_bf16 v[56:59], v[136:139], v[176:179], v[56:59]
	v_mfma_f32_16x16x32_bf16 v[44:47], v[128:131], v[194:197], v[44:47]
	v_mfma_f32_16x16x32_bf16 v[40:43], v[136:139], v[194:197], v[40:43]
	v_mfma_f32_16x16x32_bf16 v[28:31], v[128:131], v[204:207], v[28:31]
	v_mfma_f32_16x16x32_bf16 v[24:27], v[136:139], v[204:207], v[24:27]
	v_mfma_f32_16x16x32_bf16 v[12:15], v[128:131], v[212:215], v[12:15]
	v_mfma_f32_16x16x32_bf16 v[8:11], v[136:139], v[212:215], v[8:11]
	v_mfma_f32_16x16x32_bf16 v[60:63], v[132:135], v[180:183], v[60:63]
	v_mfma_f32_16x16x32_bf16 v[56:59], v[140:143], v[180:183], v[56:59]
	v_mfma_f32_16x16x32_bf16 v[44:47], v[132:135], v[198:201], v[44:47]
	v_mfma_f32_16x16x32_bf16 v[40:43], v[140:143], v[198:201], v[40:43]
	v_mfma_f32_16x16x32_bf16 v[28:31], v[132:135], v[208:211], v[28:31]
	v_mfma_f32_16x16x32_bf16 v[24:27], v[140:143], v[208:211], v[24:27]
	v_mfma_f32_16x16x32_bf16 v[12:15], v[132:135], v[216:219], v[12:15]
	v_mfma_f32_16x16x32_bf16 v[8:11], v[140:143], v[216:219], v[8:11]
	s_setprio 0
	s_setprio 1
	v_mfma_f32_16x16x32_bf16 v[52:55], v[144:147], v[176:179], v[52:55]
	v_mfma_f32_16x16x32_bf16 v[48:51], v[168:171], v[176:179], v[48:51]
	v_mfma_f32_16x16x32_bf16 v[36:39], v[144:147], v[194:197], v[36:39]
	v_mfma_f32_16x16x32_bf16 v[32:35], v[168:171], v[194:197], v[32:35]
	v_mfma_f32_16x16x32_bf16 v[20:23], v[144:147], v[204:207], v[20:23]
	v_mfma_f32_16x16x32_bf16 v[16:19], v[168:171], v[204:207], v[16:19]
	v_mfma_f32_16x16x32_bf16 v[4:7], v[144:147], v[212:215], v[4:7]
	v_mfma_f32_16x16x32_bf16 v[0:3], v[168:171], v[212:215], v[0:3]
	v_mfma_f32_16x16x32_bf16 v[52:55], v[148:151], v[180:183], v[52:55]
	v_mfma_f32_16x16x32_bf16 v[48:51], v[172:175], v[180:183], v[48:51]
	v_mfma_f32_16x16x32_bf16 v[36:39], v[148:151], v[198:201], v[36:39]
	v_mfma_f32_16x16x32_bf16 v[32:35], v[172:175], v[198:201], v[32:35]
	v_mfma_f32_16x16x32_bf16 v[20:23], v[148:151], v[208:211], v[20:23]
	v_mfma_f32_16x16x32_bf16 v[16:19], v[172:175], v[208:211], v[16:19]
	v_mfma_f32_16x16x32_bf16 v[4:7], v[148:151], v[216:219], v[4:7]
	v_mfma_f32_16x16x32_bf16 v[0:3], v[172:175], v[216:219], v[0:3]
	s_setprio 0
	s_add_i32 s59, s59, 2
	s_add_u32 s42, s42, 0x100
	s_addc_u32 s43, s43, 0
	s_add_u32 s57, s57, 0x100
	s_addc_u32 s58, s58, 0
	s_cmp_gt_u32 s59, 29
	s_barrier
	s_cbranch_scc0 .LBB0_401
	s_and_b64 vcc, exec, s[28:29]
	s_cbranch_vccz .LBB0_404
	s_barrier

.LBB0_420:
	s_or_b64 exec, exec, s[4:5]
	s_andn2_b64 vcc, exec, s[8:9]
	s_mov_b64 s[4:5], -1
	s_cbranch_vccnz .LBB0_393
	s_andn2_b64 vcc, exec, s[12:13]
	s_cbranch_vccnz .LBB0_392
	s_mov_b32 s90, 1
	s_branch .LBB0_392

.LBB0_474:
	s_mov_b32 s90, 0
	s_mov_b32 s62, -1
	s_or_b64 exec, exec, s[6:7]
	s_cmpk_lt_i32 s2, 0xb00
	s_cselect_b64 s[4:5], -1, 0
	v_writelane_b32 v254, s4, 6
	s_waitcnt lgkmcnt(0)
	v_mov_b32_e32 v0, v202
	v_mov_b32_e32 v9, v202
	v_writelane_b32 v254, s5, 7
	s_mov_b64 s[4:5], s[0:1]
	s_barrier
	s_cmpk_gt_i32 s2, 0xaff
	s_nop 0
	v_readfirstlane_b32 s13, v9
	s_cbranch_scc1 .LBB0_490
	v_lshlrev_b32_e32 v0, 4, v9
	v_add_u32_e32 v1, 0x2000, v0
	v_ashrrev_i32_e32 v2, 31, v1
	v_lshrrev_b32_e32 v2, 22, v2
	v_add_u32_e32 v2, v1, v2
	v_ashrrev_i32_e32 v8, 10, v2
	v_mul_i32_i24_e32 v2, 0x400, v8
	v_sub_u32_e32 v1, v1, v2
	v_lshrrev_b32_e32 v2, 4, v1
	v_bitop3_b32 v1, v2, v1, 32 bitop3:0x6c
	v_ashrrev_i32_e32 v2, 31, v1
	v_lshrrev_b32_e32 v2, 26, v2
	v_add_u32_e32 v2, v1, v2
	v_lshlrev_b32_e32 v3, 3, v8
	v_ashrrev_i32_e32 v10, 6, v2
	v_and_b32_e32 v3, -16, v3
	v_add_u32_e32 v3, v10, v3
	s_load_dwordx2 s[6:7], s[4:5], 0xa0
	v_and_b32_e32 v4, 3, v10
	s_mov_b32 s4, 0x1fffe0
	v_lshrrev_b32_e32 v5, 2, v3
	v_lshlrev_b32_e32 v6, 1, v3
	v_and_b32_e32 v2, 0xc0, v2
	v_and_or_b32 v4, v3, s4, v4
	v_and_b32_e32 v5, 4, v5
	v_and_b32_e32 v6, 24, v6
	v_sub_u32_e32 v1, v1, v2
	v_mov_b32_e32 v2, 1
	v_or3_b32 v4, v4, v5, v6
	v_lshlrev_b32_e32 v5, 5, v8
	v_ashrrev_i16_sdwa v1, v2, sext(v1) dst_sel:DWORD dst_unused:UNUSED_PAD src0_sel:DWORD src1_sel:BYTE_0
	v_and_b32_e32 v5, 32, v5
	v_bfe_i32 v11, v1, 0, 16
	v_add_lshl_u32 v1, v5, v11, 1
	v_lshl_add_u32 v128, v4, 11, v1
	v_lshl_add_u32 v130, v3, 11, v1
	v_bfe_i32 v1, v9, 27, 1
	v_lshrrev_b32_e32 v1, 22, v1
	v_add_u32_e32 v1, v0, v1
	v_and_b32_e32 v1, 0xfffffc00, v1
	v_sub_u32_e32 v0, v0, v1
	v_lshrrev_b32_e32 v1, 4, v0
	v_ashrrev_i32_e32 v3, 31, v9
	v_bitop3_b32 v0, v1, v0, 32 bitop3:0x6c
	v_lshrrev_b32_e32 v3, 26, v3
	v_ashrrev_i32_e32 v1, 31, v0
	v_add_u32_e32 v3, v9, v3
	v_lshrrev_b32_e32 v1, 26, v1
	v_ashrrev_i32_e32 v13, 6, v3
	s_waitcnt lgkmcnt(0)
	s_add_u32 s14, s6, 0x4800000
	v_add_u32_e32 v1, v0, v1
	v_lshlrev_b32_e32 v3, 3, v13
	s_addc_u32 s15, s7, 0
	v_ashrrev_i32_e32 v12, 6, v1
	v_and_b32_e32 v3, -16, v3
	s_add_u32 s20, s6, 0x1800000
	v_add_u32_e32 v3, v12, v3
	v_and_b32_e32 v4, 3, v12
	s_addc_u32 s22, s7, 0
	v_and_or_b32 v4, v3, s4, v4
	s_lshr_b32 s4, s21, 29
	s_add_i32 s4, s2, s4
	s_ashr_i32 s28, s13, 6
	s_ashr_i32 s5, s4, 3
	s_and_b32 s4, s4, -8
	s_ashr_i32 s30, s13, 8
	s_lshl_b32 s23, s28, 10
	s_sub_i32 s4, s2, s4
	s_cmp_lt_i32 s4, 0
	s_movk_i32 s25, 0x161
	s_cselect_b32 s8, s25, 0x160
	s_mul_i32 s4, s4, s8
	s_add_i32 s4, s4, s5
	s_mul_hi_i32 s5, s4, 0x2e8ba2e9
	s_lshr_b32 s8, s5, 31
	s_ashr_i32 s5, s5, 5
	s_add_i32 s5, s5, s8
	s_lshl_b32 s8, s5, 3
	s_mulk_i32 s5, 0xb0
	s_sub_i32 s4, s4, s5
	s_sext_i32_i16 s5, s4
	s_bfe_u32 s5, s5, 0x3001c
	s_add_i32 s5, s4, s5
	s_sext_i32_i16 s9, s5
	s_and_b32 s5, s5, 0xfff8
	s_sub_i32 s4, s4, s5
	s_sext_i32_i16 s4, s4
	v_lshrrev_b32_e32 v5, 2, v3
	v_lshlrev_b32_e32 v6, 1, v3
	v_and_b32_e32 v1, 0xc0, v1
	s_lshr_b32 s12, s9, 3
	s_add_i32 s8, s8, s4
	v_and_b32_e32 v5, 4, v5
	v_and_b32_e32 v6, 24, v6
	v_sub_u32_e32 v0, v0, v1
	s_ashr_i32 s9, s8, 31
	s_bfe_i64 s[4:5], s[12:13], 0x100000
	v_or3_b32 v4, v4, v5, v6
	v_lshlrev_b32_e32 v5, 5, v13
	v_ashrrev_i16_sdwa v0, v2, sext(v0) dst_sel:DWORD dst_unused:UNUSED_PAD src0_sel:DWORD src1_sel:BYTE_0
	s_lshl_b64 s[10:11], s[8:9], 19
	s_lshl_b64 s[4:5], s[4:5], 19
	v_and_b32_e32 v5, 32, v5
	v_bfe_i32 v14, v0, 0, 16
	s_add_u32 s4, s20, s4
	v_add_lshl_u32 v0, v5, v14, 1
	s_addc_u32 s5, s22, s5
	s_add_i32 s42, s23, 0
	v_lshl_add_u32 v132, v4, 11, v0
	s_add_i32 m0, s42, 0x10000
	v_lshl_add_u32 v134, v3, 11, v0
	global_load_lds_dwordx4 v132, s[4:5]
	s_add_i32 m0, s42, 0x12000
	s_add_u32 s16, s4, 0x40000
	global_load_lds_dwordx4 v128, s[4:5]
	s_addc_u32 s17, s5, 0
	s_add_i32 m0, s42, 0x14000
	v_mov_b32_e32 v133, 0
	global_load_lds_dwordx4 v132, s[16:17]
	s_add_i32 m0, s42, 0x16000
	s_add_u32 s10, s14, s10
	s_addc_u32 s11, s15, s11
	s_add_i32 s43, s42, 0x2000
	global_load_lds_dwordx4 v128, s[16:17]
	s_mov_b32 m0, s42
	s_add_u32 s16, s10, 0x40000
	global_load_lds_dwordx4 v134, s[10:11]
	s_mov_b32 m0, s43
	s_addc_u32 s17, s11, 0
	s_add_i32 s44, s42, 0x4000
	global_load_lds_dwordx4 v130, s[10:11]
	s_mov_b32 m0, s44
	s_add_i32 s45, s42, 0x6000
	global_load_lds_dwordx4 v134, s[16:17]
	s_mov_b32 m0, s45
	v_mov_b32_e32 v129, v133
	global_load_lds_dwordx4 v130, s[16:17]
	v_mov_b32_e32 v135, v133
	v_mov_b32_e32 v131, v133
	s_cmp_eq_u32 s30, 1
	s_mov_b32 s46, 0
	v_lshl_add_u64 v[6:7], s[4:5], 0, v[132:133]
	v_lshl_add_u64 v[4:5], s[4:5], 0, v[128:129]
	v_lshl_add_u64 v[0:1], s[10:11], 0, v[134:135]
	s_cselect_b64 s[16:17], -1, 0
	s_cmp_lg_u32 s30, 1
	v_lshl_add_u64 v[2:3], s[10:11], 0, v[130:131]
	s_cbranch_scc1 .LBB0_477
	s_barrier

.LBB0_482:
	s_ashr_i32 s37, s36, 31
	s_lshl_b64 s[12:13], s[36:37], 19
	s_add_u32 s38, s14, s12
	s_addc_u32 s39, s15, s13
	s_and_b64 s[12:13], s[6:7], exec
	s_cselect_b32 s9, s39, s11
	s_cselect_b32 s37, s38, s10
	s_ashr_i32 s35, s34, 31
	s_lshl_b64 s[12:13], s[34:35], 19
	s_add_u32 s40, s20, s12
	s_addc_u32 s41, s22, s13
	s_and_b64 s[12:13], s[6:7], exec
	s_cselect_b32 s35, s41, s5
	s_cselect_b32 s53, s40, s4
	s_add_u32 s10, s10, 0x40080
	s_addc_u32 s11, s11, 0
	s_add_u32 s54, s4, 0x100
	v_mov_b32_e32 v0, 0
	s_addc_u32 s55, s5, 0
	s_mov_b32 s56, -2
	v_mov_b32_e32 v1, v0
	v_mov_b32_e32 v2, v0
	v_mov_b32_e32 v3, v0
	v_mov_b32_e32 v8, v0
	v_mov_b32_e32 v9, v0
	v_mov_b32_e32 v10, v0
	v_mov_b32_e32 v11, v0
	v_mov_b32_e32 v16, v0
	v_mov_b32_e32 v17, v0
	v_mov_b32_e32 v18, v0
	v_mov_b32_e32 v19, v0
	v_mov_b32_e32 v24, v0
	v_mov_b32_e32 v25, v0
	v_mov_b32_e32 v26, v0
	v_mov_b32_e32 v27, v0
	v_mov_b32_e32 v32, v0
	v_mov_b32_e32 v33, v0
	v_mov_b32_e32 v34, v0
	v_mov_b32_e32 v35, v0
	v_mov_b32_e32 v40, v0
	v_mov_b32_e32 v41, v0
	s_waitcnt vmcnt(0)
	v_mov_b32_e32 v42, v0
	v_mov_b32_e32 v43, v0
	v_mov_b32_e32 v48, v0
	v_mov_b32_e32 v49, v0
	v_mov_b32_e32 v50, v0
	v_mov_b32_e32 v51, v0
	v_mov_b32_e32 v56, v0
	v_mov_b32_e32 v57, v0
	v_mov_b32_e32 v58, v0
	v_mov_b32_e32 v59, v0
	v_mov_b32_e32 v4, v0
	v_mov_b32_e32 v5, v0
	v_mov_b32_e32 v6, v0
	v_mov_b32_e32 v7, v0
	v_mov_b32_e32 v12, v0
	v_mov_b32_e32 v13, v0
	v_mov_b32_e32 v14, v0
	v_mov_b32_e32 v15, v0
	v_mov_b32_e32 v20, v0
	v_mov_b32_e32 v21, v0
	v_mov_b32_e32 v22, v0
	v_mov_b32_e32 v23, v0
	v_mov_b32_e32 v28, v0
	v_mov_b32_e32 v29, v0
	v_mov_b32_e32 v30, v0
	v_mov_b32_e32 v31, v0
	v_mov_b32_e32 v36, v0
	v_mov_b32_e32 v37, v0
	v_mov_b32_e32 v38, v0
	v_mov_b32_e32 v39, v0
	v_mov_b32_e32 v44, v0
	v_mov_b32_e32 v45, v0
	v_mov_b32_e32 v46, v0
	v_mov_b32_e32 v47, v0
	v_mov_b32_e32 v52, v0
	v_mov_b32_e32 v53, v0
	v_mov_b32_e32 v54, v0
	v_mov_b32_e32 v55, v0
	v_mov_b32_e32 v60, v0
	v_mov_b32_e32 v61, v0
	v_mov_b32_e32 v62, v0
	v_mov_b32_e32 v63, v0
	v_mov_b32_e32 v64, v0
	v_mov_b32_e32 v65, v0
	v_mov_b32_e32 v66, v0
	v_mov_b32_e32 v67, v0
	v_mov_b32_e32 v72, v0
	v_mov_b32_e32 v73, v0
	v_mov_b32_e32 v74, v0
	v_mov_b32_e32 v75, v0
	v_mov_b32_e32 v80, v0
	v_mov_b32_e32 v81, v0
	v_mov_b32_e32 v82, v0
	v_mov_b32_e32 v83, v0
	v_mov_b32_e32 v88, v0
	v_mov_b32_e32 v89, v0
	v_mov_b32_e32 v90, v0
	v_mov_b32_e32 v91, v0
	v_mov_b32_e32 v96, v0
	v_mov_b32_e32 v97, v0
	v_mov_b32_e32 v98, v0
	v_mov_b32_e32 v99, v0
	v_mov_b32_e32 v104, v0
	v_mov_b32_e32 v105, v0
	v_mov_b32_e32 v106, v0
	v_mov_b32_e32 v107, v0
	v_mov_b32_e32 v112, v0
	v_mov_b32_e32 v113, v0
	v_mov_b32_e32 v114, v0
	v_mov_b32_e32 v115, v0
	v_mov_b32_e32 v120, v0
	v_mov_b32_e32 v121, v0
	v_mov_b32_e32 v122, v0
	v_mov_b32_e32 v123, v0
	v_mov_b32_e32 v68, v0
	v_mov_b32_e32 v69, v0
	v_mov_b32_e32 v70, v0
	v_mov_b32_e32 v71, v0
	v_mov_b32_e32 v76, v0
	v_mov_b32_e32 v77, v0
	v_mov_b32_e32 v78, v0
	v_mov_b32_e32 v79, v0
	v_mov_b32_e32 v84, v0
	v_mov_b32_e32 v85, v0
	v_mov_b32_e32 v86, v0
	v_mov_b32_e32 v87, v0
	v_mov_b32_e32 v92, v0
	v_mov_b32_e32 v93, v0
	v_mov_b32_e32 v94, v0
	v_mov_b32_e32 v95, v0
	v_mov_b32_e32 v100, v0
	v_mov_b32_e32 v101, v0
	v_mov_b32_e32 v102, v0
	v_mov_b32_e32 v103, v0
	v_mov_b32_e32 v108, v0
	v_mov_b32_e32 v109, v0
	v_mov_b32_e32 v110, v0
	v_mov_b32_e32 v111, v0
	v_mov_b32_e32 v116, v0
	v_mov_b32_e32 v117, v0
	v_mov_b32_e32 v118, v0
	v_mov_b32_e32 v119, v0
	v_mov_b32_e32 v124, v0
	v_mov_b32_e32 v125, v0
	v_mov_b32_e32 v126, v0
	v_mov_b32_e32 v127, v0
	s_cmp_lg_u32 s90, 0
	s_cbranch_scc0 .Lkl_nobar_2
	s_barrier
	s_mov_b32 s90, 0
.Lkl_nobar_2:
.LBB0_483:
	ds_read_b128 v[146:149], v169
	ds_read_b128 v[150:153], v169 offset:1024
	ds_read_b128 v[154:157], v169 offset:2048
	ds_read_b128 v[160:163], v169 offset:3072
	ds_read_b128 v[180:183], v171
	ds_read_b128 v[184:187], v171 offset:1024
	ds_read_b128 v[188:191], v171 offset:2048
	ds_read_b128 v[192:195], v171 offset:3072
	s_add_u32 s4, s10, 0xfffc0080
	s_addc_u32 s5, s11, -1
	s_cmp_eq_u32 s56, 12
	s_cselect_b32 s13, s9, s5
	s_cselect_b32 s12, s37, s4
	s_cselect_b32 s5, s35, s55
	s_cselect_b32 s4, s53, s54
	v_lshl_add_u64 v[200:201], s[10:11], 0, v[138:139]
	s_add_i32 m0, s42, 0xc000
	ds_read_b128 v[196:199], v173
	ds_read_b128 v[204:207], v173 offset:1024
	ds_read_b128 v[208:211], v173 offset:2048
	ds_read_b128 v[212:215], v173 offset:3072
	ds_read_b128 v[216:219], v173 offset:4096
	ds_read_b128 v[220:223], v173 offset:5120
	ds_read_b128 v[224:227], v173 offset:6144
	ds_read_b128 v[228:231], v173 offset:7168
	global_load_lds_dwordx4 v[200:201], off
	s_add_i32 m0, s42, 0xe000
	v_lshl_add_u64 v[200:201], s[10:11], 0, v[140:141]
	global_load_lds_dwordx4 v[200:201], off
	s_waitcnt vmcnt(8) lgkmcnt(0)
	s_setprio 1
	s_barrier
	v_mfma_f32_16x16x32_bf16 v[124:127], v[146:149], v[196:199], v[124:127]
	v_mfma_f32_16x16x32_bf16 v[116:119], v[154:157], v[196:199], v[116:119]
	v_mfma_f32_16x16x32_bf16 v[108:111], v[146:149], v[208:211], v[108:111]
	v_mfma_f32_16x16x32_bf16 v[100:103], v[154:157], v[208:211], v[100:103]
	v_mfma_f32_16x16x32_bf16 v[92:95], v[146:149], v[216:219], v[92:95]
	v_mfma_f32_16x16x32_bf16 v[84:87], v[154:157], v[216:219], v[84:87]
	v_mfma_f32_16x16x32_bf16 v[76:79], v[146:149], v[224:227], v[76:79]
	v_mfma_f32_16x16x32_bf16 v[68:71], v[154:157], v[224:227], v[68:71]
	v_mfma_f32_16x16x32_bf16 v[124:127], v[150:153], v[204:207], v[124:127]
	v_mfma_f32_16x16x32_bf16 v[116:119], v[160:163], v[204:207], v[116:119]
	v_mfma_f32_16x16x32_bf16 v[108:111], v[150:153], v[212:215], v[108:111]
	v_mfma_f32_16x16x32_bf16 v[100:103], v[160:163], v[212:215], v[100:103]
	v_mfma_f32_16x16x32_bf16 v[92:95], v[150:153], v[220:223], v[92:95]
	v_mfma_f32_16x16x32_bf16 v[84:87], v[160:163], v[220:223], v[84:87]
	v_mfma_f32_16x16x32_bf16 v[76:79], v[150:153], v[228:231], v[76:79]
	v_mfma_f32_16x16x32_bf16 v[68:71], v[160:163], v[228:231], v[68:71]
	s_setprio 0
	s_setprio 1
	v_mfma_f32_16x16x32_bf16 v[120:123], v[180:183], v[196:199], v[120:123]
	v_mfma_f32_16x16x32_bf16 v[112:115], v[188:191], v[196:199], v[112:115]
	v_mfma_f32_16x16x32_bf16 v[104:107], v[180:183], v[208:211], v[104:107]
	v_mfma_f32_16x16x32_bf16 v[96:99], v[188:191], v[208:211], v[96:99]
	v_mfma_f32_16x16x32_bf16 v[88:91], v[180:183], v[216:219], v[88:91]
	v_mfma_f32_16x16x32_bf16 v[80:83], v[188:191], v[216:219], v[80:83]
	v_mfma_f32_16x16x32_bf16 v[72:75], v[180:183], v[224:227], v[72:75]
	v_mfma_f32_16x16x32_bf16 v[64:67], v[188:191], v[224:227], v[64:67]
	v_mfma_f32_16x16x32_bf16 v[120:123], v[184:187], v[204:207], v[120:123]
	v_mfma_f32_16x16x32_bf16 v[112:115], v[192:195], v[204:207], v[112:115]
	v_mfma_f32_16x16x32_bf16 v[104:107], v[184:187], v[212:215], v[104:107]
	v_mfma_f32_16x16x32_bf16 v[96:99], v[192:195], v[212:215], v[96:99]
	v_mfma_f32_16x16x32_bf16 v[88:91], v[184:187], v[220:223], v[88:91]
	v_mfma_f32_16x16x32_bf16 v[80:83], v[192:195], v[220:223], v[80:83]
	v_mfma_f32_16x16x32_bf16 v[72:75], v[184:187], v[228:231], v[72:75]
	v_mfma_f32_16x16x32_bf16 v[64:67], v[192:195], v[228:231], v[64:67]
	s_setprio 0
	s_barrier
	s_add_i32 s57, s49, s23
	v_lshl_add_u64 v[200:201], s[4:5], 0, v[132:133]
	s_mov_b32 m0, s57
	ds_read_b128 v[196:199], v173 offset:16384
	ds_read_b128 v[204:207], v173 offset:17408
	ds_read_b128 v[208:211], v173 offset:18432
	ds_read_b128 v[212:215], v173 offset:19456
	ds_read_b128 v[216:219], v173 offset:20480
	ds_read_b128 v[220:223], v173 offset:21504
	ds_read_b128 v[224:227], v173 offset:22528
	ds_read_b128 v[228:231], v173 offset:23552
	global_load_lds_dwordx4 v[200:201], off
	s_add_i32 m0, s57, 0x2000
	s_add_u32 s58, s4, 0x40000
	v_lshl_add_u64 v[232:233], s[4:5], 0, v[128:129]
	s_addc_u32 s59, s5, 0
	s_add_i32 s57, s50, s23
	global_load_lds_dwordx4 v[232:233], off
	v_lshl_add_u64 v[234:235], s[58:59], 0, v[132:133]
	s_mov_b32 m0, s57
	v_lshl_add_u64 v[236:237], s[12:13], 0, v[130:131]
	global_load_lds_dwordx4 v[234:235], off
	s_add_i32 m0, s57, 0x2000
	v_lshl_add_u64 v[234:235], s[58:59], 0, v[128:129]
	global_load_lds_dwordx4 v[234:235], off
	s_mov_b32 m0, s42
	v_lshl_add_u64 v[234:235], s[12:13], 0, v[134:135]
	global_load_lds_dwordx4 v[234:235], off
	s_mov_b32 m0, s43
	s_nop 0
	global_load_lds_dwordx4 v[236:237], off
	s_waitcnt vmcnt(8) lgkmcnt(0)
	s_setprio 1
	s_barrier
	v_mfma_f32_16x16x32_bf16 v[60:63], v[146:149], v[196:199], v[60:63]
	v_mfma_f32_16x16x32_bf16 v[52:55], v[154:157], v[196:199], v[52:55]
	v_mfma_f32_16x16x32_bf16 v[44:47], v[146:149], v[208:211], v[44:47]
	v_mfma_f32_16x16x32_bf16 v[36:39], v[154:157], v[208:211], v[36:39]
	v_mfma_f32_16x16x32_bf16 v[28:31], v[146:149], v[216:219], v[28:31]
	v_mfma_f32_16x16x32_bf16 v[20:23], v[154:157], v[216:219], v[20:23]
	v_mfma_f32_16x16x32_bf16 v[12:15], v[146:149], v[224:227], v[12:15]
	v_mfma_f32_16x16x32_bf16 v[4:7], v[154:157], v[224:227], v[4:7]
	v_mfma_f32_16x16x32_bf16 v[60:63], v[150:153], v[204:207], v[60:63]
	v_mfma_f32_16x16x32_bf16 v[52:55], v[160:163], v[204:207], v[52:55]
	v_mfma_f32_16x16x32_bf16 v[44:47], v[150:153], v[212:215], v[44:47]
	v_mfma_f32_16x16x32_bf16 v[36:39], v[160:163], v[212:215], v[36:39]
	v_mfma_f32_16x16x32_bf16 v[28:31], v[150:153], v[220:223], v[28:31]
	v_mfma_f32_16x16x32_bf16 v[20:23], v[160:163], v[220:223], v[20:23]
	v_mfma_f32_16x16x32_bf16 v[12:15], v[150:153], v[228:231], v[12:15]
	v_mfma_f32_16x16x32_bf16 v[4:7], v[160:163], v[228:231], v[4:7]
	s_setprio 0
	s_setprio 1
	v_mfma_f32_16x16x32_bf16 v[56:59], v[180:183], v[196:199], v[56:59]
	v_mfma_f32_16x16x32_bf16 v[48:51], v[188:191], v[196:199], v[48:51]
	v_mfma_f32_16x16x32_bf16 v[40:43], v[180:183], v[208:211], v[40:43]
	v_mfma_f32_16x16x32_bf16 v[32:35], v[188:191], v[208:211], v[32:35]
	v_mfma_f32_16x16x32_bf16 v[24:27], v[180:183], v[216:219], v[24:27]
	v_mfma_f32_16x16x32_bf16 v[16:19], v[188:191], v[216:219], v[16:19]
	v_mfma_f32_16x16x32_bf16 v[8:11], v[180:183], v[224:227], v[8:11]
	v_mfma_f32_16x16x32_bf16 v[0:3], v[188:191], v[224:227], v[0:3]
	v_mfma_f32_16x16x32_bf16 v[56:59], v[184:187], v[204:207], v[56:59]
	v_mfma_f32_16x16x32_bf16 v[48:51], v[192:195], v[204:207], v[48:51]
	v_mfma_f32_16x16x32_bf16 v[40:43], v[184:187], v[212:215], v[40:43]
	v_mfma_f32_16x16x32_bf16 v[32:35], v[192:195], v[212:215], v[32:35]
	v_mfma_f32_16x16x32_bf16 v[24:27], v[184:187], v[220:223], v[24:27]
	v_mfma_f32_16x16x32_bf16 v[16:19], v[192:195], v[220:223], v[16:19]
	v_mfma_f32_16x16x32_bf16 v[8:11], v[184:187], v[228:231], v[8:11]
	v_mfma_f32_16x16x32_bf16 v[0:3], v[192:195], v[228:231], v[0:3]
	s_setprio 0
	s_barrier
	s_add_i32 s57, 0, 0x18000
	v_add_u32_e32 v158, s57, v165
	s_add_i32 s58, 0, 0x1c000
	ds_read_b128 v[146:149], v158
	ds_read_b128 v[150:153], v158 offset:1024
	ds_read_b128 v[154:157], v158 offset:2048
	ds_read_b128 v[160:163], v158 offset:3072
	v_add_u32_e32 v158, s58, v165
	ds_read_b128 v[180:183], v158
	ds_read_b128 v[184:187], v158 offset:1024
	ds_read_b128 v[188:191], v158 offset:2048
	ds_read_b128 v[192:195], v158 offset:3072
	s_add_u32 s12, s12, 0x40000
	s_addc_u32 s13, s13, 0
	s_mov_b32 m0, s44
	v_lshl_add_u64 v[238:239], s[12:13], 0, v[134:135]
	ds_read_b128 v[196:199], v173 offset:32768
	ds_read_b128 v[204:207], v173 offset:33792
	ds_read_b128 v[208:211], v173 offset:34816
	ds_read_b128 v[212:215], v173 offset:35840
	ds_read_b128 v[216:219], v173 offset:36864
	ds_read_b128 v[220:223], v173 offset:37888
	ds_read_b128 v[224:227], v173 offset:38912
	ds_read_b128 v[228:231], v173 offset:39936
	global_load_lds_dwordx4 v[238:239], off
	s_mov_b32 m0, s45
	v_lshl_add_u64 v[238:239], s[12:13], 0, v[130:131]
	global_load_lds_dwordx4 v[238:239], off
	s_waitcnt vmcnt(8) lgkmcnt(0)
	s_setprio 1
	s_barrier
	v_mfma_f32_16x16x32_bf16 v[124:127], v[146:149], v[196:199], v[124:127]
	v_mfma_f32_16x16x32_bf16 v[116:119], v[154:157], v[196:199], v[116:119]
	v_mfma_f32_16x16x32_bf16 v[108:111], v[146:149], v[208:211], v[108:111]
	v_mfma_f32_16x16x32_bf16 v[100:103], v[154:157], v[208:211], v[100:103]
	v_mfma_f32_16x16x32_bf16 v[92:95], v[146:149], v[216:219], v[92:95]
	v_mfma_f32_16x16x32_bf16 v[84:87], v[154:157], v[216:219], v[84:87]
	v_mfma_f32_16x16x32_bf16 v[76:79], v[146:149], v[224:227], v[76:79]
	v_mfma_f32_16x16x32_bf16 v[68:71], v[154:157], v[224:227], v[68:71]
	v_mfma_f32_16x16x32_bf16 v[124:127], v[150:153], v[204:207], v[124:127]
	v_mfma_f32_16x16x32_bf16 v[116:119], v[160:163], v[204:207], v[116:119]
	v_mfma_f32_16x16x32_bf16 v[108:111], v[150:153], v[212:215], v[108:111]
	v_mfma_f32_16x16x32_bf16 v[100:103], v[160:163], v[212:215], v[100:103]
	v_mfma_f32_16x16x32_bf16 v[92:95], v[150:153], v[220:223], v[92:95]
	v_mfma_f32_16x16x32_bf16 v[84:87], v[160:163], v[220:223], v[84:87]
	v_mfma_f32_16x16x32_bf16 v[76:79], v[150:153], v[228:231], v[76:79]
	v_mfma_f32_16x16x32_bf16 v[68:71], v[160:163], v[228:231], v[68:71]
	s_setprio 0
	s_setprio 1
	v_mfma_f32_16x16x32_bf16 v[120:123], v[180:183], v[196:199], v[120:123]
	v_mfma_f32_16x16x32_bf16 v[112:115], v[188:191], v[196:199], v[112:115]
	v_mfma_f32_16x16x32_bf16 v[104:107], v[180:183], v[208:211], v[104:107]
	v_mfma_f32_16x16x32_bf16 v[96:99], v[188:191], v[208:211], v[96:99]
	v_mfma_f32_16x16x32_bf16 v[88:91], v[180:183], v[216:219], v[88:91]
	v_mfma_f32_16x16x32_bf16 v[80:83], v[188:191], v[216:219], v[80:83]
	v_mfma_f32_16x16x32_bf16 v[72:75], v[180:183], v[224:227], v[72:75]
	v_mfma_f32_16x16x32_bf16 v[64:67], v[188:191], v[224:227], v[64:67]
	v_mfma_f32_16x16x32_bf16 v[120:123], v[184:187], v[204:207], v[120:123]
	v_mfma_f32_16x16x32_bf16 v[112:115], v[192:195], v[204:207], v[112:115]
	v_mfma_f32_16x16x32_bf16 v[104:107], v[184:187], v[212:215], v[104:107]
	v_mfma_f32_16x16x32_bf16 v[96:99], v[192:195], v[212:215], v[96:99]
	v_mfma_f32_16x16x32_bf16 v[88:91], v[184:187], v[220:223], v[88:91]
	v_mfma_f32_16x16x32_bf16 v[80:83], v[192:195], v[220:223], v[80:83]
	v_mfma_f32_16x16x32_bf16 v[72:75], v[184:187], v[228:231], v[72:75]
	v_mfma_f32_16x16x32_bf16 v[64:67], v[192:195], v[228:231], v[64:67]
	s_setprio 0
	s_barrier
	s_add_i32 s12, s57, s23
	v_lshl_add_u64 v[200:201], v[200:201], 0, s[28:29]
	s_mov_b32 m0, s12
	ds_read_b128 v[196:199], v173 offset:49152
	ds_read_b128 v[204:207], v173 offset:50176
	ds_read_b128 v[208:211], v173 offset:51200
	ds_read_b128 v[212:215], v173 offset:52224
	ds_read_b128 v[216:219], v173 offset:53248
	ds_read_b128 v[220:223], v173 offset:54272
	ds_read_b128 v[224:227], v173 offset:55296
	ds_read_b128 v[228:231], v173 offset:56320
	global_load_lds_dwordx4 v[200:201], off
	s_add_i32 m0, s12, 0x2000
	s_add_u32 s4, s4, 0x40080
	v_lshl_add_u64 v[200:201], v[232:233], 0, s[28:29]
	s_addc_u32 s5, s5, 0
	s_add_i32 s12, s58, s23
	global_load_lds_dwordx4 v[200:201], off
	s_mov_b32 m0, s12
	v_lshl_add_u64 v[200:201], s[4:5], 0, v[132:133]
	global_load_lds_dwordx4 v[200:201], off
	s_add_i32 m0, s12, 0x2000
	v_lshl_add_u64 v[200:201], s[4:5], 0, v[128:129]
	global_load_lds_dwordx4 v[200:201], off
	s_mov_b32 m0, s47
	v_lshl_add_u64 v[200:201], v[234:235], 0, s[28:29]
	global_load_lds_dwordx4 v[200:201], off
	s_mov_b32 m0, s48
	v_lshl_add_u64 v[200:201], v[236:237], 0, s[28:29]
	global_load_lds_dwordx4 v[200:201], off
	s_waitcnt vmcnt(8) lgkmcnt(0)
	s_setprio 1
	s_barrier
	v_mfma_f32_16x16x32_bf16 v[60:63], v[146:149], v[196:199], v[60:63]
	v_mfma_f32_16x16x32_bf16 v[52:55], v[154:157], v[196:199], v[52:55]
	v_mfma_f32_16x16x32_bf16 v[44:47], v[146:149], v[208:211], v[44:47]
	v_mfma_f32_16x16x32_bf16 v[36:39], v[154:157], v[208:211], v[36:39]
	v_mfma_f32_16x16x32_bf16 v[28:31], v[146:149], v[216:219], v[28:31]
	v_mfma_f32_16x16x32_bf16 v[20:23], v[154:157], v[216:219], v[20:23]
	v_mfma_f32_16x16x32_bf16 v[12:15], v[146:149], v[224:227], v[12:15]
	v_mfma_f32_16x16x32_bf16 v[4:7], v[154:157], v[224:227], v[4:7]
	v_mfma_f32_16x16x32_bf16 v[60:63], v[150:153], v[204:207], v[60:63]
	v_mfma_f32_16x16x32_bf16 v[52:55], v[160:163], v[204:207], v[52:55]
	v_mfma_f32_16x16x32_bf16 v[44:47], v[150:153], v[212:215], v[44:47]
	v_mfma_f32_16x16x32_bf16 v[36:39], v[160:163], v[212:215], v[36:39]
	v_mfma_f32_16x16x32_bf16 v[28:31], v[150:153], v[220:223], v[28:31]
	v_mfma_f32_16x16x32_bf16 v[20:23], v[160:163], v[220:223], v[20:23]
	v_mfma_f32_16x16x32_bf16 v[12:15], v[150:153], v[228:231], v[12:15]
	v_mfma_f32_16x16x32_bf16 v[4:7], v[160:163], v[228:231], v[4:7]
	s_setprio 0
	s_setprio 1
	v_mfma_f32_16x16x32_bf16 v[56:59], v[180:183], v[196:199], v[56:59]
	v_mfma_f32_16x16x32_bf16 v[48:51], v[188:191], v[196:199], v[48:51]
	v_mfma_f32_16x16x32_bf16 v[40:43], v[180:183], v[208:211], v[40:43]
	v_mfma_f32_16x16x32_bf16 v[32:35], v[188:191], v[208:211], v[32:35]
	v_mfma_f32_16x16x32_bf16 v[24:27], v[180:183], v[216:219], v[24:27]
	v_mfma_f32_16x16x32_bf16 v[16:19], v[188:191], v[216:219], v[16:19]
	v_mfma_f32_16x16x32_bf16 v[8:11], v[180:183], v[224:227], v[8:11]
	v_mfma_f32_16x16x32_bf16 v[0:3], v[188:191], v[224:227], v[0:3]
	v_mfma_f32_16x16x32_bf16 v[56:59], v[184:187], v[204:207], v[56:59]
	v_mfma_f32_16x16x32_bf16 v[48:51], v[192:195], v[204:207], v[48:51]
	v_mfma_f32_16x16x32_bf16 v[40:43], v[184:187], v[212:215], v[40:43]
	v_mfma_f32_16x16x32_bf16 v[32:35], v[192:195], v[212:215], v[32:35]
	v_mfma_f32_16x16x32_bf16 v[24:27], v[184:187], v[220:223], v[24:27]
	v_mfma_f32_16x16x32_bf16 v[16:19], v[192:195], v[220:223], v[16:19]
	v_mfma_f32_16x16x32_bf16 v[8:11], v[184:187], v[228:231], v[8:11]
	v_mfma_f32_16x16x32_bf16 v[0:3], v[192:195], v[228:231], v[0:3]
	s_setprio 0
	s_add_i32 s56, s56, 2
	s_add_u32 s10, s10, 0x100
	s_addc_u32 s11, s11, 0
	s_add_u32 s54, s54, 0x100
	s_addc_u32 s55, s55, 0
	s_cmp_gt_u32 s56, 13
	s_barrier
	s_cbranch_scc0 .LBB0_483
	s_and_b64 vcc, exec, s[30:31]
	s_cbranch_vccz .LBB0_486
	s_barrier

.Lrstd_done_p4:
	v_or_b32_e32 v160, 16, v162
	v_or_b32_e32 v156, 32, v162
	v_or_b32_e32 v154, 48, v162
	v_add_u32_e32 v148, 0x80, v162
	s_nop 0
	s_nop 0
	v_add_u32_e32 v152, 0x90, v162
	v_add_u32_e32 v150, 0xa0, v162
	s_nop 0
	s_nop 1
	v_add_u32_e32 v146, 0xb0, v162
	s_waitcnt lgkmcnt(0)
	s_waitcnt lgkmcnt(0)
	s_waitcnt vmcnt(1)
	s_waitcnt lgkmcnt(0)
	s_waitcnt lgkmcnt(0)
	s_waitcnt vmcnt(0)
	v_mov_b32_e32 v180, v120
	s_waitcnt lgkmcnt(0)
	s_waitcnt lgkmcnt(0)
	v_mov_b32_e32 v181, v124
	v_pk_mul_f32 v[180:181], v[180:181], v[176:177] op_sel_hi:[1,0]
	v_mov_b32_e32 v124, v121
	v_mul_f32_e32 v120, 0xbfb8aa3b, v181
	v_exp_f32_e32 v147, v120
	v_pk_mul_f32 v[120:121], v[124:125], v[176:177] op_sel_hi:[1,0]
	s_andn2_b64 vcc, exec, s[6:7]
	v_mul_f32_e32 v124, 0xbfb8aa3b, v121
	v_exp_f32_e32 v125, v124
	v_add_f32_e32 v147, 1.0, v147
	v_rcp_f32_e32 v147, v147
	v_lshl_or_b32 v124, s33, 7, v167
	v_add_f32_e32 v125, 1.0, v125
	v_rcp_f32_e32 v149, v125
	v_mul_f32_e32 v147, v181, v147
	v_mul_f32_e32 v147, v180, v147
	v_mov_b32_e32 v180, v122
	v_mov_b32_e32 v181, v126
	v_pk_mul_f32 v[180:181], v[180:181], v[176:177] op_sel_hi:[1,0]
	v_mov_b32_e32 v126, v123
	v_mul_f32_e32 v122, 0xbfb8aa3b, v181
	v_mul_f32_e32 v121, v121, v149
	v_exp_f32_e32 v149, v122
	v_pk_mul_f32 v[122:123], v[126:127], v[176:177] op_sel_hi:[1,0]
	v_mul_f32_e32 v127, v120, v121
	v_mul_f32_e32 v126, 0xbfb8aa3b, v123
	v_exp_f32_e32 v126, v126
	v_add_f32_e32 v120, 1.0, v149
	v_rcp_f32_e32 v149, v120
	v_mov_b32_e32 v121, v116
	v_add_f32_e32 v120, 1.0, v126
	v_rcp_f32_e32 v126, v120
	v_mov_b32_e32 v120, v112
	v_pk_mul_f32 v[120:121], v[120:121], v[176:177] op_sel_hi:[1,0]
	v_mul_f32_e32 v116, v181, v149
	v_mul_f32_e32 v112, 0xbfb8aa3b, v121
	v_exp_f32_e32 v112, v112
	v_mul_f32_e32 v149, v180, v116
	v_mov_b32_e32 v116, v113
	v_mul_f32_e32 v123, v123, v126
	v_add_f32_e32 v112, 1.0, v112
	v_rcp_f32_e32 v126, v112
	v_pk_mul_f32 v[112:113], v[116:117], v[176:177] op_sel_hi:[1,0]
	v_mul_f32_e32 v122, v122, v123
	v_mul_f32_e32 v116, 0xbfb8aa3b, v113
	v_exp_f32_e32 v116, v116
	v_mul_f32_e32 v117, v121, v126
	v_mul_f32_e32 v120, v120, v117
	v_mov_b32_e32 v117, v118
	v_add_f32_e32 v116, 1.0, v116
	v_rcp_f32_e32 v121, v116
	v_mov_b32_e32 v116, v114
	v_pk_mul_f32 v[116:117], v[116:117], v[176:177] op_sel_hi:[1,0]
	v_mov_b32_e32 v118, v115
	v_mul_f32_e32 v114, 0xbfb8aa3b, v117
	v_exp_f32_e32 v123, v114
	v_pk_mul_f32 v[114:115], v[118:119], v[176:177] op_sel_hi:[1,0]
	v_mul_f32_e32 v113, v113, v121
	v_mul_f32_e32 v118, 0xbfb8aa3b, v115
	v_exp_f32_e32 v118, v118
	v_add_f32_e32 v119, 1.0, v123
	v_rcp_f32_e32 v119, v119
	v_mul_f32_e32 v112, v112, v113
	v_add_f32_e32 v118, 1.0, v118
	v_rcp_f32_e32 v118, v118
	v_mul_f32_e32 v113, v117, v119
	v_mul_f32_e32 v113, v116, v113
	v_cvt_pk_bf16_f32 v116, v147, v127
	v_cvt_pk_bf16_f32 v117, v149, v122
	v_mov_b32_e32 v122, v104
	v_mov_b32_e32 v123, v108
	v_mul_f32_e32 v115, v115, v118
	v_pk_mul_f32 v[122:123], v[122:123], v[174:175] op_sel_hi:[1,0]
	v_ashrrev_i32_e32 v125, 31, v124
	v_mul_f32_e32 v114, v114, v115
	v_mul_f32_e32 v104, 0xbfb8aa3b, v123
	v_cvt_pk_bf16_f32 v118, v120, v112
	v_cvt_pk_bf16_f32 v119, v113, v114
	v_lshlrev_b64 v[114:115], 1, v[124:125]
	v_exp_f32_e32 v124, v104
	v_mov_b32_e32 v108, v105
	v_mov_b64_e32 v[112:113], s[26:27]
	v_pk_mul_f32 v[104:105], v[108:109], v[174:175] op_sel_hi:[1,0]
	v_mad_i64_i32 v[120:121], s[4:5], v162, s52, v[112:113]
	v_mul_f32_e32 v108, 0xbfb8aa3b, v105
	v_exp_f32_e32 v125, v108
	v_lshl_add_u64 v[108:109], v[120:121], 0, v[114:115]
	v_add_f32_e32 v120, 1.0, v124
	v_rcp_f32_e32 v120, v120
	global_store_dwordx4 v[108:109], v[116:119], off
	v_mov_b32_e32 v109, v110
	v_add_f32_e32 v121, 1.0, v125
	v_mul_f32_e32 v108, v123, v120
	v_mul_f32_e32 v116, v122, v108
	v_mov_b32_e32 v108, v106
	v_pk_mul_f32 v[108:109], v[108:109], v[174:175] op_sel_hi:[1,0]
	v_mov_b32_e32 v110, v107
	v_mul_f32_e32 v106, 0xbfb8aa3b, v109
	v_rcp_f32_e32 v121, v121
	v_exp_f32_e32 v117, v106
	v_pk_mul_f32 v[106:107], v[110:111], v[174:175] op_sel_hi:[1,0]
	v_mul_f32_e32 v105, v105, v121
	v_mul_f32_e32 v110, 0xbfb8aa3b, v107
	v_exp_f32_e32 v110, v110
	v_mul_f32_e32 v111, v104, v105
	v_add_f32_e32 v104, 1.0, v117
	v_rcp_f32_e32 v117, v104
	v_add_f32_e32 v104, 1.0, v110
	v_rcp_f32_e32 v110, v104
	v_mov_b32_e32 v104, v96
	v_mov_b32_e32 v105, v100
	v_pk_mul_f32 v[104:105], v[104:105], v[174:175] op_sel_hi:[1,0]
	v_mul_f32_e32 v100, v109, v117
	v_mul_f32_e32 v96, 0xbfb8aa3b, v105
	v_exp_f32_e32 v96, v96
	v_mul_f32_e32 v108, v108, v100
	v_mov_b32_e32 v100, v97
	v_mul_f32_e32 v107, v107, v110
	v_add_f32_e32 v96, 1.0, v96
	v_rcp_f32_e32 v109, v96
	v_pk_mul_f32 v[96:97], v[100:101], v[174:175] op_sel_hi:[1,0]
	v_mul_f32_e32 v106, v106, v107
	v_mul_f32_e32 v100, 0xbfb8aa3b, v97
	v_exp_f32_e32 v100, v100
	v_mul_f32_e32 v101, v105, v109
	v_mul_f32_e32 v104, v104, v101
	v_mov_b32_e32 v101, v102
	v_add_f32_e32 v100, 1.0, v100
	v_rcp_f32_e32 v105, v100
	v_mov_b32_e32 v100, v98
	v_pk_mul_f32 v[100:101], v[100:101], v[174:175] op_sel_hi:[1,0]
	v_mov_b32_e32 v102, v99
	v_mul_f32_e32 v98, 0xbfb8aa3b, v101
	v_exp_f32_e32 v107, v98
	v_pk_mul_f32 v[98:99], v[102:103], v[174:175] op_sel_hi:[1,0]
	v_mul_f32_e32 v97, v97, v105
	v_mul_f32_e32 v102, 0xbfb8aa3b, v99
	v_exp_f32_e32 v102, v102
	v_add_f32_e32 v103, 1.0, v107
	v_rcp_f32_e32 v103, v103
	v_mul_f32_e32 v105, v96, v97
	v_add_f32_e32 v102, 1.0, v102
	v_rcp_f32_e32 v102, v102
	v_mul_f32_e32 v96, v101, v103
	v_mul_f32_e32 v100, v100, v96
	v_mov_b32_e32 v103, v92
	v_mul_f32_e32 v96, v99, v102
	v_mov_b32_e32 v102, v88
	v_pk_mul_f32 v[102:103], v[102:103], v[172:173] op_sel_hi:[1,0]
	v_mul_f32_e32 v99, v98, v96
	v_mul_f32_e32 v88, 0xbfb8aa3b, v103
	v_cvt_pk_bf16_f32 v96, v116, v111
	v_cvt_pk_bf16_f32 v97, v108, v106
	v_cvt_pk_bf16_f32 v98, v104, v105
	v_exp_f32_e32 v104, v88
	v_mov_b32_e32 v92, v89
	v_pk_mul_f32 v[88:89], v[92:93], v[172:173] op_sel_hi:[1,0]
	v_cvt_pk_bf16_f32 v99, v100, v99
	v_mad_i64_i32 v[100:101], s[4:5], v160, s52, v[112:113]
	v_mul_f32_e32 v92, 0xbfb8aa3b, v89
	v_exp_f32_e32 v105, v92
	v_lshl_add_u64 v[92:93], v[100:101], 0, v[114:115]
	v_add_f32_e32 v100, 1.0, v104
	v_rcp_f32_e32 v100, v100
	global_store_dwordx4 v[92:93], v[96:99], off
	v_mov_b32_e32 v93, v94
	v_add_f32_e32 v101, 1.0, v105
	v_mul_f32_e32 v92, v103, v100
	v_mul_f32_e32 v96, v102, v92
	v_mov_b32_e32 v92, v90
	v_pk_mul_f32 v[92:93], v[92:93], v[172:173] op_sel_hi:[1,0]
	v_mov_b32_e32 v94, v91
	v_mul_f32_e32 v90, 0xbfb8aa3b, v93
	v_rcp_f32_e32 v101, v101
	v_exp_f32_e32 v97, v90
	v_pk_mul_f32 v[90:91], v[94:95], v[172:173] op_sel_hi:[1,0]
	v_mul_f32_e32 v89, v89, v101
	v_mul_f32_e32 v94, 0xbfb8aa3b, v91
	v_exp_f32_e32 v94, v94
	v_mul_f32_e32 v95, v88, v89
	v_add_f32_e32 v88, 1.0, v97
	v_rcp_f32_e32 v97, v88
	v_add_f32_e32 v88, 1.0, v94
	v_rcp_f32_e32 v94, v88
	v_mov_b32_e32 v88, v80
	v_mov_b32_e32 v89, v84
	v_pk_mul_f32 v[88:89], v[88:89], v[172:173] op_sel_hi:[1,0]
	v_mul_f32_e32 v84, v93, v97
	v_mul_f32_e32 v80, 0xbfb8aa3b, v89
	v_exp_f32_e32 v80, v80
	v_mul_f32_e32 v92, v92, v84
	v_mov_b32_e32 v84, v81
	v_mul_f32_e32 v91, v91, v94
	v_add_f32_e32 v80, 1.0, v80
	v_rcp_f32_e32 v93, v80
	v_pk_mul_f32 v[80:81], v[84:85], v[172:173] op_sel_hi:[1,0]
	v_mul_f32_e32 v90, v90, v91
	v_mul_f32_e32 v84, 0xbfb8aa3b, v81
	v_exp_f32_e32 v84, v84
	v_mul_f32_e32 v85, v89, v93
	v_mul_f32_e32 v88, v88, v85
	v_mov_b32_e32 v85, v86
	v_add_f32_e32 v84, 1.0, v84
	v_rcp_f32_e32 v89, v84
	v_mov_b32_e32 v84, v82
	v_pk_mul_f32 v[84:85], v[84:85], v[172:173] op_sel_hi:[1,0]
	v_mov_b32_e32 v86, v83
	v_mul_f32_e32 v82, 0xbfb8aa3b, v85
	v_exp_f32_e32 v91, v82
	v_pk_mul_f32 v[82:83], v[86:87], v[172:173] op_sel_hi:[1,0]
	v_mul_f32_e32 v81, v81, v89
	v_mul_f32_e32 v86, 0xbfb8aa3b, v83
	v_exp_f32_e32 v86, v86
	v_add_f32_e32 v87, 1.0, v91
	v_rcp_f32_e32 v87, v87
	v_mul_f32_e32 v89, v80, v81
	v_add_f32_e32 v86, 1.0, v86
	v_rcp_f32_e32 v86, v86
	v_mul_f32_e32 v80, v85, v87
	v_mul_f32_e32 v84, v84, v80
	v_mov_b32_e32 v87, v76
	v_mul_f32_e32 v80, v83, v86
	v_mov_b32_e32 v86, v72
	v_pk_mul_f32 v[86:87], v[86:87], v[170:171] op_sel_hi:[1,0]
	v_mul_f32_e32 v83, v82, v80
	v_mul_f32_e32 v72, 0xbfb8aa3b, v87
	v_cvt_pk_bf16_f32 v80, v96, v95
	v_cvt_pk_bf16_f32 v81, v92, v90
	v_cvt_pk_bf16_f32 v82, v88, v89
	v_exp_f32_e32 v88, v72
	v_mov_b32_e32 v76, v73
	v_pk_mul_f32 v[72:73], v[76:77], v[170:171] op_sel_hi:[1,0]
	v_cvt_pk_bf16_f32 v83, v84, v83
	v_mad_i64_i32 v[84:85], s[4:5], v156, s52, v[112:113]
	v_mul_f32_e32 v76, 0xbfb8aa3b, v73
	v_exp_f32_e32 v89, v76
	v_lshl_add_u64 v[76:77], v[84:85], 0, v[114:115]
	v_add_f32_e32 v84, 1.0, v88
	v_rcp_f32_e32 v84, v84
	global_store_dwordx4 v[76:77], v[80:83], off
	v_mov_b32_e32 v77, v78
	v_add_f32_e32 v85, 1.0, v89
	v_mul_f32_e32 v76, v87, v84
	v_mul_f32_e32 v80, v86, v76
	v_mov_b32_e32 v76, v74
	v_pk_mul_f32 v[76:77], v[76:77], v[170:171] op_sel_hi:[1,0]
	v_mov_b32_e32 v78, v75
	v_mul_f32_e32 v74, 0xbfb8aa3b, v77
	v_rcp_f32_e32 v85, v85
	v_exp_f32_e32 v81, v74
	v_pk_mul_f32 v[74:75], v[78:79], v[170:171] op_sel_hi:[1,0]
	v_mul_f32_e32 v73, v73, v85
	v_mul_f32_e32 v78, 0xbfb8aa3b, v75
	v_exp_f32_e32 v78, v78
	v_mul_f32_e32 v79, v72, v73
	v_add_f32_e32 v72, 1.0, v81
	v_rcp_f32_e32 v81, v72
	v_add_f32_e32 v72, 1.0, v78
	v_rcp_f32_e32 v78, v72
	v_mov_b32_e32 v72, v64
	v_mov_b32_e32 v73, v68
	v_pk_mul_f32 v[72:73], v[72:73], v[170:171] op_sel_hi:[1,0]
	v_mul_f32_e32 v68, v77, v81
	v_mul_f32_e32 v64, 0xbfb8aa3b, v73
	v_exp_f32_e32 v64, v64
	v_mul_f32_e32 v76, v76, v68
	v_mov_b32_e32 v68, v65
	v_mul_f32_e32 v75, v75, v78
	v_add_f32_e32 v64, 1.0, v64
	v_rcp_f32_e32 v77, v64
	v_pk_mul_f32 v[64:65], v[68:69], v[170:171] op_sel_hi:[1,0]
	v_mul_f32_e32 v74, v74, v75
	v_mul_f32_e32 v68, 0xbfb8aa3b, v65
	v_exp_f32_e32 v68, v68
	v_mul_f32_e32 v69, v73, v77
	v_mul_f32_e32 v72, v72, v69
	v_mov_b32_e32 v69, v70
	v_add_f32_e32 v68, 1.0, v68
	v_rcp_f32_e32 v73, v68
	v_mov_b32_e32 v68, v66
	v_pk_mul_f32 v[68:69], v[68:69], v[170:171] op_sel_hi:[1,0]
	v_mov_b32_e32 v70, v67
	v_mul_f32_e32 v66, 0xbfb8aa3b, v69
	v_exp_f32_e32 v75, v66
	v_pk_mul_f32 v[66:67], v[70:71], v[170:171] op_sel_hi:[1,0]
	v_mul_f32_e32 v65, v65, v73
	v_mul_f32_e32 v70, 0xbfb8aa3b, v67
	v_exp_f32_e32 v70, v70
	v_add_f32_e32 v71, 1.0, v75
	v_rcp_f32_e32 v71, v71
	v_mul_f32_e32 v73, v64, v65
	v_add_f32_e32 v70, 1.0, v70
	v_rcp_f32_e32 v70, v70
	v_mul_f32_e32 v64, v69, v71
	v_mul_f32_e32 v68, v68, v64
	v_mov_b32_e32 v71, v60
	v_mul_f32_e32 v64, v67, v70
	v_mov_b32_e32 v70, v56
	v_pk_mul_f32 v[70:71], v[70:71], v[168:169] op_sel_hi:[1,0]
	v_mul_f32_e32 v67, v66, v64
	v_mul_f32_e32 v56, 0xbfb8aa3b, v71
	v_cvt_pk_bf16_f32 v64, v80, v79
	v_cvt_pk_bf16_f32 v65, v76, v74
	v_cvt_pk_bf16_f32 v66, v72, v73
	v_exp_f32_e32 v72, v56
	v_mov_b32_e32 v60, v57
	v_pk_mul_f32 v[56:57], v[60:61], v[168:169] op_sel_hi:[1,0]
	v_cvt_pk_bf16_f32 v67, v68, v67
	v_mad_i64_i32 v[68:69], s[4:5], v154, s52, v[112:113]
	v_mul_f32_e32 v60, 0xbfb8aa3b, v57
	v_exp_f32_e32 v73, v60
	v_lshl_add_u64 v[60:61], v[68:69], 0, v[114:115]
	v_add_f32_e32 v68, 1.0, v72
	v_rcp_f32_e32 v68, v68
	global_store_dwordx4 v[60:61], v[64:67], off
	v_mov_b32_e32 v61, v62
	v_add_f32_e32 v69, 1.0, v73
	v_mul_f32_e32 v60, v71, v68
	v_mul_f32_e32 v64, v70, v60
	v_mov_b32_e32 v60, v58
	v_pk_mul_f32 v[60:61], v[60:61], v[168:169] op_sel_hi:[1,0]
	v_mov_b32_e32 v62, v59
	v_mul_f32_e32 v58, 0xbfb8aa3b, v61
	v_rcp_f32_e32 v69, v69
	v_exp_f32_e32 v65, v58
	v_pk_mul_f32 v[58:59], v[62:63], v[168:169] op_sel_hi:[1,0]
	v_mul_f32_e32 v57, v57, v69
	v_mul_f32_e32 v62, 0xbfb8aa3b, v59
	v_exp_f32_e32 v62, v62
	v_mul_f32_e32 v63, v56, v57
	v_add_f32_e32 v56, 1.0, v65
	v_rcp_f32_e32 v65, v56
	v_add_f32_e32 v56, 1.0, v62
	v_rcp_f32_e32 v62, v56
	v_mov_b32_e32 v56, v48
	v_mov_b32_e32 v57, v52
	v_pk_mul_f32 v[56:57], v[56:57], v[168:169] op_sel_hi:[1,0]
	v_mul_f32_e32 v52, v61, v65
	v_mul_f32_e32 v48, 0xbfb8aa3b, v57
	v_exp_f32_e32 v48, v48
	v_mul_f32_e32 v60, v60, v52
	v_mov_b32_e32 v52, v49
	v_mul_f32_e32 v59, v59, v62
	v_add_f32_e32 v48, 1.0, v48
	v_rcp_f32_e32 v61, v48
	v_pk_mul_f32 v[48:49], v[52:53], v[168:169] op_sel_hi:[1,0]
	v_mul_f32_e32 v58, v58, v59
	v_mul_f32_e32 v52, 0xbfb8aa3b, v49
	v_exp_f32_e32 v52, v52
	v_mul_f32_e32 v53, v57, v61
	v_mul_f32_e32 v56, v56, v53
	v_mov_b32_e32 v53, v54
	v_add_f32_e32 v52, 1.0, v52
	v_rcp_f32_e32 v57, v52
	v_mov_b32_e32 v52, v50
	v_pk_mul_f32 v[52:53], v[52:53], v[168:169] op_sel_hi:[1,0]
	v_mov_b32_e32 v54, v51
	v_mul_f32_e32 v50, 0xbfb8aa3b, v53
	v_exp_f32_e32 v59, v50
	v_pk_mul_f32 v[50:51], v[54:55], v[168:169] op_sel_hi:[1,0]
	v_mul_f32_e32 v49, v49, v57
	v_mul_f32_e32 v54, 0xbfb8aa3b, v51
	v_exp_f32_e32 v54, v54
	v_add_f32_e32 v55, 1.0, v59
	v_rcp_f32_e32 v55, v55
	v_mul_f32_e32 v57, v48, v49
	v_add_f32_e32 v54, 1.0, v54
	v_rcp_f32_e32 v54, v54
	v_mul_f32_e32 v48, v53, v55
	v_mul_f32_e32 v52, v52, v48
	v_mov_b32_e32 v55, v44
	v_mul_f32_e32 v48, v51, v54
	v_mov_b32_e32 v54, v40
	v_pk_mul_f32 v[54:55], v[54:55], v[166:167] op_sel_hi:[1,0]
	v_mul_f32_e32 v51, v50, v48
	v_mul_f32_e32 v40, 0xbfb8aa3b, v55
	v_cvt_pk_bf16_f32 v48, v64, v63
	v_cvt_pk_bf16_f32 v49, v60, v58
	v_cvt_pk_bf16_f32 v50, v56, v57
	v_exp_f32_e32 v56, v40
	v_mov_b32_e32 v44, v41
	v_pk_mul_f32 v[40:41], v[44:45], v[166:167] op_sel_hi:[1,0]
	v_cvt_pk_bf16_f32 v51, v52, v51
	v_mad_i64_i32 v[52:53], s[4:5], v148, s52, v[112:113]
	v_mul_f32_e32 v44, 0xbfb8aa3b, v41
	v_exp_f32_e32 v57, v44
	v_lshl_add_u64 v[44:45], v[52:53], 0, v[114:115]
	v_add_f32_e32 v52, 1.0, v56
	v_rcp_f32_e32 v52, v52
	global_store_dwordx4 v[44:45], v[48:51], off
	v_mov_b32_e32 v45, v46
	v_add_f32_e32 v53, 1.0, v57
	v_mul_f32_e32 v44, v55, v52
	v_mul_f32_e32 v48, v54, v44
	v_mov_b32_e32 v44, v42
	v_pk_mul_f32 v[44:45], v[44:45], v[166:167] op_sel_hi:[1,0]
	v_mov_b32_e32 v46, v43
	v_mul_f32_e32 v42, 0xbfb8aa3b, v45
	v_rcp_f32_e32 v53, v53
	v_exp_f32_e32 v49, v42
	v_pk_mul_f32 v[42:43], v[46:47], v[166:167] op_sel_hi:[1,0]
	v_mul_f32_e32 v41, v41, v53
	v_mul_f32_e32 v46, 0xbfb8aa3b, v43
	v_exp_f32_e32 v46, v46
	v_mul_f32_e32 v47, v40, v41
	v_add_f32_e32 v40, 1.0, v49
	v_rcp_f32_e32 v49, v40
	v_add_f32_e32 v40, 1.0, v46
	v_rcp_f32_e32 v46, v40
	v_mov_b32_e32 v40, v32
	v_mov_b32_e32 v41, v36
	v_pk_mul_f32 v[40:41], v[40:41], v[166:167] op_sel_hi:[1,0]
	v_mul_f32_e32 v36, v45, v49
	v_mul_f32_e32 v32, 0xbfb8aa3b, v41
	v_exp_f32_e32 v32, v32
	v_mul_f32_e32 v44, v44, v36
	v_mov_b32_e32 v36, v33
	v_mul_f32_e32 v43, v43, v46
	v_add_f32_e32 v32, 1.0, v32
	v_rcp_f32_e32 v45, v32
	v_pk_mul_f32 v[32:33], v[36:37], v[166:167] op_sel_hi:[1,0]
	v_mul_f32_e32 v42, v42, v43
	v_mul_f32_e32 v36, 0xbfb8aa3b, v33
	v_exp_f32_e32 v36, v36
	v_mul_f32_e32 v37, v41, v45
	v_mul_f32_e32 v40, v40, v37
	v_mov_b32_e32 v37, v38
	v_add_f32_e32 v36, 1.0, v36
	v_rcp_f32_e32 v41, v36
	v_mov_b32_e32 v36, v34
	v_pk_mul_f32 v[36:37], v[36:37], v[166:167] op_sel_hi:[1,0]
	v_mov_b32_e32 v38, v35
	v_mul_f32_e32 v34, 0xbfb8aa3b, v37
	v_exp_f32_e32 v43, v34
	v_pk_mul_f32 v[34:35], v[38:39], v[166:167] op_sel_hi:[1,0]
	v_mul_f32_e32 v33, v33, v41
	v_mul_f32_e32 v38, 0xbfb8aa3b, v35
	v_exp_f32_e32 v38, v38
	v_add_f32_e32 v39, 1.0, v43
	v_rcp_f32_e32 v39, v39
	v_mul_f32_e32 v41, v32, v33
	v_add_f32_e32 v38, 1.0, v38
	v_rcp_f32_e32 v38, v38
	v_mul_f32_e32 v32, v37, v39
	v_mul_f32_e32 v36, v36, v32
	v_mov_b32_e32 v39, v28
	v_mul_f32_e32 v32, v35, v38
	v_mov_b32_e32 v38, v24
	v_pk_mul_f32 v[38:39], v[38:39], v[164:165] op_sel_hi:[1,0]
	v_mul_f32_e32 v35, v34, v32
	v_mul_f32_e32 v24, 0xbfb8aa3b, v39
	v_cvt_pk_bf16_f32 v32, v48, v47
	v_cvt_pk_bf16_f32 v33, v44, v42
	v_cvt_pk_bf16_f32 v34, v40, v41
	v_exp_f32_e32 v40, v24
	v_mov_b32_e32 v28, v25
	v_pk_mul_f32 v[24:25], v[28:29], v[164:165] op_sel_hi:[1,0]
	v_cvt_pk_bf16_f32 v35, v36, v35
	v_mad_i64_i32 v[36:37], s[4:5], v152, s52, v[112:113]
	v_mul_f32_e32 v28, 0xbfb8aa3b, v25
	v_exp_f32_e32 v41, v28
	v_lshl_add_u64 v[28:29], v[36:37], 0, v[114:115]
	v_add_f32_e32 v36, 1.0, v40
	v_rcp_f32_e32 v36, v36
	global_store_dwordx4 v[28:29], v[32:35], off
	v_mov_b32_e32 v29, v30
	v_add_f32_e32 v37, 1.0, v41
	v_mul_f32_e32 v28, v39, v36
	v_mul_f32_e32 v32, v38, v28
	v_mov_b32_e32 v28, v26
	v_pk_mul_f32 v[28:29], v[28:29], v[164:165] op_sel_hi:[1,0]
	v_mov_b32_e32 v30, v27
	v_mul_f32_e32 v26, 0xbfb8aa3b, v29
	v_rcp_f32_e32 v37, v37
	v_exp_f32_e32 v33, v26
	v_pk_mul_f32 v[26:27], v[30:31], v[164:165] op_sel_hi:[1,0]
	v_mul_f32_e32 v25, v25, v37
	v_mul_f32_e32 v30, 0xbfb8aa3b, v27
	v_exp_f32_e32 v30, v30
	v_mul_f32_e32 v31, v24, v25
	v_add_f32_e32 v24, 1.0, v33
	v_rcp_f32_e32 v33, v24
	v_add_f32_e32 v24, 1.0, v30
	v_rcp_f32_e32 v30, v24
	v_mov_b32_e32 v24, v16
	v_mov_b32_e32 v25, v20
	v_pk_mul_f32 v[24:25], v[24:25], v[164:165] op_sel_hi:[1,0]
	v_mul_f32_e32 v20, v29, v33
	v_mul_f32_e32 v16, 0xbfb8aa3b, v25
	v_exp_f32_e32 v16, v16
	v_mul_f32_e32 v28, v28, v20
	v_mov_b32_e32 v20, v17
	v_mul_f32_e32 v27, v27, v30
	v_add_f32_e32 v16, 1.0, v16
	v_rcp_f32_e32 v29, v16
	v_pk_mul_f32 v[16:17], v[20:21], v[164:165] op_sel_hi:[1,0]
	v_mul_f32_e32 v26, v26, v27
	v_mul_f32_e32 v20, 0xbfb8aa3b, v17
	v_exp_f32_e32 v20, v20
	v_mul_f32_e32 v21, v25, v29
	v_mul_f32_e32 v24, v24, v21
	v_mov_b32_e32 v21, v22
	v_add_f32_e32 v20, 1.0, v20
	v_rcp_f32_e32 v25, v20
	v_mov_b32_e32 v20, v18
	v_pk_mul_f32 v[20:21], v[20:21], v[164:165] op_sel_hi:[1,0]
	v_mov_b32_e32 v22, v19
	v_mul_f32_e32 v18, 0xbfb8aa3b, v21
	v_exp_f32_e32 v27, v18
	v_pk_mul_f32 v[18:19], v[22:23], v[164:165] op_sel_hi:[1,0]
	v_mul_f32_e32 v17, v17, v25
	v_mul_f32_e32 v22, 0xbfb8aa3b, v19
	v_exp_f32_e32 v22, v22
	v_add_f32_e32 v23, 1.0, v27
	v_rcp_f32_e32 v23, v23
	v_mul_f32_e32 v25, v16, v17
	v_add_f32_e32 v22, 1.0, v22
	v_rcp_f32_e32 v22, v22
	v_mul_f32_e32 v16, v21, v23
	v_mul_f32_e32 v20, v20, v16
	v_mov_b32_e32 v23, v12
	v_mul_f32_e32 v16, v19, v22
	v_mov_b32_e32 v22, v8
	v_pk_mul_f32 v[22:23], v[22:23], v[158:159] op_sel_hi:[1,0]
	v_mul_f32_e32 v19, v18, v16
	v_mul_f32_e32 v8, 0xbfb8aa3b, v23
	v_cvt_pk_bf16_f32 v16, v32, v31
	v_cvt_pk_bf16_f32 v17, v28, v26
	v_cvt_pk_bf16_f32 v18, v24, v25
	v_exp_f32_e32 v24, v8
	v_mov_b32_e32 v12, v9
	v_pk_mul_f32 v[8:9], v[12:13], v[158:159] op_sel_hi:[1,0]
	v_cvt_pk_bf16_f32 v19, v20, v19
	v_mad_i64_i32 v[20:21], s[4:5], v150, s52, v[112:113]
	v_mul_f32_e32 v12, 0xbfb8aa3b, v9
	v_exp_f32_e32 v25, v12
	v_lshl_add_u64 v[12:13], v[20:21], 0, v[114:115]
	v_add_f32_e32 v20, 1.0, v24
	v_rcp_f32_e32 v20, v20
	global_store_dwordx4 v[12:13], v[16:19], off
	v_mov_b32_e32 v13, v14
	v_add_f32_e32 v21, 1.0, v25
	v_mul_f32_e32 v12, v23, v20
	v_mul_f32_e32 v16, v22, v12
	v_mov_b32_e32 v12, v10
	v_pk_mul_f32 v[12:13], v[12:13], v[158:159] op_sel_hi:[1,0]
	v_mov_b32_e32 v14, v11
	v_mul_f32_e32 v10, 0xbfb8aa3b, v13
	v_rcp_f32_e32 v21, v21
	v_exp_f32_e32 v17, v10
	v_pk_mul_f32 v[10:11], v[14:15], v[158:159] op_sel_hi:[1,0]
	v_mul_f32_e32 v9, v9, v21
	v_mul_f32_e32 v14, 0xbfb8aa3b, v11
	v_exp_f32_e32 v14, v14
	v_mul_f32_e32 v15, v8, v9
	v_add_f32_e32 v8, 1.0, v17
	v_rcp_f32_e32 v17, v8
	v_add_f32_e32 v8, 1.0, v14
	v_rcp_f32_e32 v14, v8
	v_mov_b32_e32 v8, v0
	v_mov_b32_e32 v9, v4
	v_pk_mul_f32 v[8:9], v[8:9], v[158:159] op_sel_hi:[1,0]
	v_mul_f32_e32 v4, v13, v17
	v_mul_f32_e32 v0, 0xbfb8aa3b, v9
	v_exp_f32_e32 v0, v0
	v_mul_f32_e32 v12, v12, v4
	v_mov_b32_e32 v4, v1
	v_mul_f32_e32 v11, v11, v14
	v_add_f32_e32 v0, 1.0, v0
	v_rcp_f32_e32 v13, v0
	v_pk_mul_f32 v[0:1], v[4:5], v[158:159] op_sel_hi:[1,0]
	v_mul_f32_e32 v10, v10, v11
	v_mul_f32_e32 v4, 0xbfb8aa3b, v1
	v_exp_f32_e32 v4, v4
	v_mul_f32_e32 v5, v9, v13
	v_mul_f32_e32 v8, v8, v5
	v_mov_b32_e32 v5, v6
	v_add_f32_e32 v4, 1.0, v4
	v_rcp_f32_e32 v9, v4
	v_mov_b32_e32 v4, v2
	v_pk_mul_f32 v[4:5], v[4:5], v[158:159] op_sel_hi:[1,0]
	v_mov_b32_e32 v6, v3
	v_mul_f32_e32 v2, 0xbfb8aa3b, v5
	v_exp_f32_e32 v11, v2
	v_pk_mul_f32 v[2:3], v[6:7], v[158:159] op_sel_hi:[1,0]
	v_mul_f32_e32 v1, v1, v9
	v_mul_f32_e32 v6, 0xbfb8aa3b, v3
	v_exp_f32_e32 v6, v6
	v_add_f32_e32 v7, 1.0, v11
	v_rcp_f32_e32 v7, v7
	v_mul_f32_e32 v9, v0, v1
	v_add_f32_e32 v6, 1.0, v6
	v_rcp_f32_e32 v6, v6
	v_mul_f32_e32 v0, v5, v7
	v_mul_f32_e32 v4, v4, v0
	v_mul_f32_e32 v0, v3, v6
	v_mul_f32_e32 v3, v2, v0
	v_cvt_pk_bf16_f32 v0, v16, v15
	v_cvt_pk_bf16_f32 v1, v12, v10
	v_cvt_pk_bf16_f32 v2, v8, v9
	v_cvt_pk_bf16_f32 v3, v4, v3
	v_mad_i64_i32 v[4:5], s[4:5], v146, s52, v[112:113]
	v_lshl_add_u64 v[4:5], v[4:5], 0, v[114:115]
	s_mov_b64 s[4:5], -1
	global_store_dwordx4 v[4:5], v[0:3], off
	s_cbranch_vccnz .LBB0_479
	s_andn2_b64 vcc, exec, s[16:17]
	s_cbranch_vccnz .LBB0_478
	s_mov_b32 s90, 1
	s_branch .LBB0_478

.LBB0_540:
	s_mov_b32 s90, 0
	s_or_b64 exec, exec, s[6:7]
	v_readlane_b32 s6, v254, 4
	s_mov_b64 s[4:5], s[0:1]
	s_waitcnt lgkmcnt(0)
	v_mov_b32_e32 v0, v202
	v_mov_b32_e32 v8, v202
	v_readlane_b32 s7, v254, 5
	s_barrier
	s_and_b64 vcc, exec, s[6:7]
	v_readfirstlane_b32 s8, v8
	s_cbranch_vccnz .LBB0_542
	s_lshr_b32 s6, s21, 29
	s_add_i32 s6, s2, s6
	s_and_b32 s7, s6, -8
	s_sub_i32 s7, s2, s7
	s_lshl_b32 s10, s7, 6
	s_ashr_i32 s6, s6, 3
	s_mul_i32 s9, s7, 0x41
	s_cmp_lt_i32 s7, 0
	s_cselect_b32 s7, s9, s10
	s_add_i32 s6, s7, s6
	s_ashr_i32 s7, s6, 31
	s_lshr_b32 s7, s7, 27
	s_add_i32 s7, s6, s7
	s_ashr_i32 s9, s7, 5
	s_andn2_b32 s7, s7, 31
	s_sub_i32 s6, s6, s7
	s_bfe_i32 s7, s6, 0x80000
	s_bfe_u32 s7, s7, 0x3000c
	s_add_i32 s7, s6, s7
	s_bfe_i32 s10, s7, 0x80000
	s_and_b32 s7, s7, 0xf8
	s_sub_i32 s6, s6, s7
	s_lshl_b32 s9, s9, 3
	s_sext_i32_i16 s10, s10
	s_sext_i32_i8 s6, s6
	s_add_i32 s54, s9, s6
	s_ashr_i32 s12, s10, 3

.LBB0_558:
	s_add_u32 s55, s4, 0x100
	v_mov_b32_e32 v0, 0
	s_addc_u32 s56, s5, 0
	s_mov_b32 s57, -2
	s_waitcnt lgkmcnt(0)
	v_mov_b32_e32 v1, v0
	v_mov_b32_e32 v2, v0
	v_mov_b32_e32 v3, v0
	v_mov_b32_e32 v4, v0
	v_mov_b32_e32 v5, v0
	v_mov_b32_e32 v6, v0
	v_mov_b32_e32 v7, v0
	v_mov_b32_e32 v16, v0
	v_mov_b32_e32 v17, v0
	v_mov_b32_e32 v18, v0
	v_mov_b32_e32 v19, v0
	v_mov_b32_e32 v20, v0
	v_mov_b32_e32 v21, v0
	v_mov_b32_e32 v22, v0
	v_mov_b32_e32 v23, v0
	v_mov_b32_e32 v32, v0
	v_mov_b32_e32 v33, v0
	v_mov_b32_e32 v34, v0
	v_mov_b32_e32 v35, v0
	v_mov_b32_e32 v36, v0
	v_mov_b32_e32 v37, v0
	v_mov_b32_e32 v38, v0
	v_mov_b32_e32 v39, v0
	s_waitcnt vmcnt(0)
	v_mov_b32_e32 v48, v0
	v_mov_b32_e32 v49, v0
	v_mov_b32_e32 v50, v0
	v_mov_b32_e32 v51, v0
	v_mov_b32_e32 v52, v0
	v_mov_b32_e32 v53, v0
	v_mov_b32_e32 v54, v0
	v_mov_b32_e32 v55, v0
	v_mov_b32_e32 v8, v0
	v_mov_b32_e32 v9, v0
	v_mov_b32_e32 v10, v0
	v_mov_b32_e32 v11, v0
	v_mov_b32_e32 v12, v0
	v_mov_b32_e32 v13, v0
	v_mov_b32_e32 v14, v0
	v_mov_b32_e32 v15, v0
	v_mov_b32_e32 v24, v0
	v_mov_b32_e32 v25, v0
	v_mov_b32_e32 v26, v0
	v_mov_b32_e32 v27, v0
	v_mov_b32_e32 v28, v0
	v_mov_b32_e32 v29, v0
	v_mov_b32_e32 v30, v0
	v_mov_b32_e32 v31, v0
	v_mov_b32_e32 v40, v0
	v_mov_b32_e32 v41, v0
	v_mov_b32_e32 v42, v0
	v_mov_b32_e32 v43, v0
	v_mov_b32_e32 v44, v0
	v_mov_b32_e32 v45, v0
	v_mov_b32_e32 v46, v0
	v_mov_b32_e32 v47, v0
	v_mov_b32_e32 v56, v0
	v_mov_b32_e32 v57, v0
	v_mov_b32_e32 v58, v0
	v_mov_b32_e32 v59, v0
	v_mov_b32_e32 v60, v0
	v_mov_b32_e32 v61, v0
	v_mov_b32_e32 v62, v0
	v_mov_b32_e32 v63, v0
	v_mov_b32_e32 v64, v0
	v_mov_b32_e32 v65, v0
	v_mov_b32_e32 v66, v0
	v_mov_b32_e32 v67, v0
	v_mov_b32_e32 v68, v0
	v_mov_b32_e32 v69, v0
	v_mov_b32_e32 v70, v0
	v_mov_b32_e32 v71, v0
	v_mov_b32_e32 v80, v0
	v_mov_b32_e32 v81, v0
	v_mov_b32_e32 v82, v0
	v_mov_b32_e32 v83, v0
	v_mov_b32_e32 v84, v0
	v_mov_b32_e32 v85, v0
	v_mov_b32_e32 v86, v0
	v_mov_b32_e32 v87, v0
	v_mov_b32_e32 v96, v0
	v_mov_b32_e32 v97, v0
	v_mov_b32_e32 v98, v0
	v_mov_b32_e32 v99, v0
	v_mov_b32_e32 v100, v0
	v_mov_b32_e32 v101, v0
	v_mov_b32_e32 v102, v0
	v_mov_b32_e32 v103, v0
	v_mov_b32_e32 v112, v0
	v_mov_b32_e32 v113, v0
	v_mov_b32_e32 v114, v0
	v_mov_b32_e32 v115, v0
	v_mov_b32_e32 v116, v0
	v_mov_b32_e32 v117, v0
	v_mov_b32_e32 v118, v0
	v_mov_b32_e32 v119, v0
	v_mov_b32_e32 v72, v0
	v_mov_b32_e32 v73, v0
	v_mov_b32_e32 v74, v0
	v_mov_b32_e32 v75, v0
	v_mov_b32_e32 v76, v0
	v_mov_b32_e32 v77, v0
	v_mov_b32_e32 v78, v0
	v_mov_b32_e32 v79, v0
	v_mov_b32_e32 v88, v0
	v_mov_b32_e32 v89, v0
	v_mov_b32_e32 v90, v0
	v_mov_b32_e32 v91, v0
	v_mov_b32_e32 v92, v0
	v_mov_b32_e32 v93, v0
	v_mov_b32_e32 v94, v0
	v_mov_b32_e32 v95, v0
	v_mov_b32_e32 v104, v0
	v_mov_b32_e32 v105, v0
	v_mov_b32_e32 v106, v0
	v_mov_b32_e32 v107, v0
	v_mov_b32_e32 v108, v0
	v_mov_b32_e32 v109, v0
	v_mov_b32_e32 v110, v0
	v_mov_b32_e32 v111, v0
	v_mov_b32_e32 v120, v0
	v_mov_b32_e32 v121, v0
	v_mov_b32_e32 v122, v0
	v_mov_b32_e32 v123, v0
	v_mov_b32_e32 v124, v0
	v_mov_b32_e32 v125, v0
	v_mov_b32_e32 v126, v0
	v_mov_b32_e32 v127, v0
	s_cmp_lg_u32 s90, 0
	s_cbranch_scc0 .Lkl_nobar_3
	s_barrier
	s_mov_b32 s90, 0
.Lkl_nobar_3:
.LBB0_559:
	ds_read_b128 v[128:131], v189
	ds_read_b128 v[132:135], v189 offset:1024
	ds_read_b128 v[136:139], v189 offset:2048
	ds_read_b128 v[140:143], v189 offset:3072
	ds_read_b128 v[144:147], v190
	ds_read_b128 v[148:151], v190 offset:1024
	ds_read_b128 v[168:171], v190 offset:2048
	ds_read_b128 v[172:175], v190 offset:3072
	s_add_u32 s4, s22, 0x100
	s_addc_u32 s5, s23, 0
	s_cmp_eq_u32 s57, 40
	s_cselect_b32 s41, s11, s5
	s_cselect_b32 s40, s10, s4
	s_cselect_b32 s39, s37, s56
	s_cselect_b32 s38, s36, s55
	v_lshl_add_u64 v[184:185], s[22:23], 0, v[160:161]
	s_add_i32 m0, s43, 0xc000
	ds_read_b128 v[176:179], v191
	ds_read_b128 v[180:183], v191 offset:1024
	ds_read_b128 v[194:197], v191 offset:2048
	ds_read_b128 v[198:201], v191 offset:3072
	ds_read_b128 v[204:207], v191 offset:4096
	ds_read_b128 v[208:211], v191 offset:5120
	ds_read_b128 v[212:215], v191 offset:6144
	ds_read_b128 v[216:219], v191 offset:7168
	global_load_lds_dwordx4 v[184:185], off
	s_add_i32 m0, s43, 0xe000
	v_lshl_add_u64 v[184:185], s[22:23], 0, v[162:163]
	global_load_lds_dwordx4 v[184:185], off
	s_waitcnt vmcnt(8) lgkmcnt(0)
	s_setprio 1
	s_barrier
	v_mfma_f32_16x16x32_bf16 v[124:127], v[128:131], v[176:179], v[124:127]
	v_mfma_f32_16x16x32_bf16 v[120:123], v[136:139], v[176:179], v[120:123]
	v_mfma_f32_16x16x32_bf16 v[108:111], v[128:131], v[194:197], v[108:111]
	v_mfma_f32_16x16x32_bf16 v[104:107], v[136:139], v[194:197], v[104:107]
	v_mfma_f32_16x16x32_bf16 v[92:95], v[128:131], v[204:207], v[92:95]
	v_mfma_f32_16x16x32_bf16 v[88:91], v[136:139], v[204:207], v[88:91]
	v_mfma_f32_16x16x32_bf16 v[76:79], v[128:131], v[212:215], v[76:79]
	v_mfma_f32_16x16x32_bf16 v[72:75], v[136:139], v[212:215], v[72:75]
	v_mfma_f32_16x16x32_bf16 v[124:127], v[132:135], v[180:183], v[124:127]
	v_mfma_f32_16x16x32_bf16 v[120:123], v[140:143], v[180:183], v[120:123]
	v_mfma_f32_16x16x32_bf16 v[108:111], v[132:135], v[198:201], v[108:111]
	v_mfma_f32_16x16x32_bf16 v[104:107], v[140:143], v[198:201], v[104:107]
	v_mfma_f32_16x16x32_bf16 v[92:95], v[132:135], v[208:211], v[92:95]
	v_mfma_f32_16x16x32_bf16 v[88:91], v[140:143], v[208:211], v[88:91]
	v_mfma_f32_16x16x32_bf16 v[76:79], v[132:135], v[216:219], v[76:79]
	v_mfma_f32_16x16x32_bf16 v[72:75], v[140:143], v[216:219], v[72:75]
	s_setprio 0
	s_setprio 1
	v_mfma_f32_16x16x32_bf16 v[116:119], v[144:147], v[176:179], v[116:119]
	v_mfma_f32_16x16x32_bf16 v[112:115], v[168:171], v[176:179], v[112:115]
	v_mfma_f32_16x16x32_bf16 v[100:103], v[144:147], v[194:197], v[100:103]
	v_mfma_f32_16x16x32_bf16 v[96:99], v[168:171], v[194:197], v[96:99]
	v_mfma_f32_16x16x32_bf16 v[84:87], v[144:147], v[204:207], v[84:87]
	v_mfma_f32_16x16x32_bf16 v[80:83], v[168:171], v[204:207], v[80:83]
	v_mfma_f32_16x16x32_bf16 v[68:71], v[144:147], v[212:215], v[68:71]
	v_mfma_f32_16x16x32_bf16 v[64:67], v[168:171], v[212:215], v[64:67]
	v_mfma_f32_16x16x32_bf16 v[116:119], v[148:151], v[180:183], v[116:119]
	v_mfma_f32_16x16x32_bf16 v[112:115], v[172:175], v[180:183], v[112:115]
	v_mfma_f32_16x16x32_bf16 v[100:103], v[148:151], v[198:201], v[100:103]
	v_mfma_f32_16x16x32_bf16 v[96:99], v[172:175], v[198:201], v[96:99]
	v_mfma_f32_16x16x32_bf16 v[84:87], v[148:151], v[208:211], v[84:87]
	v_mfma_f32_16x16x32_bf16 v[80:83], v[172:175], v[208:211], v[80:83]
	v_mfma_f32_16x16x32_bf16 v[68:71], v[148:151], v[216:219], v[68:71]
	v_mfma_f32_16x16x32_bf16 v[64:67], v[172:175], v[216:219], v[64:67]
	s_setprio 0
	s_barrier
	s_add_i32 s22, s49, s42
	v_lshl_add_u64 v[184:185], s[38:39], 0, v[154:155]
	s_mov_b32 m0, s22
	ds_read_b128 v[176:179], v191 offset:16384
	ds_read_b128 v[180:183], v191 offset:17408
	ds_read_b128 v[194:197], v191 offset:18432
	ds_read_b128 v[198:201], v191 offset:19456
	ds_read_b128 v[204:207], v191 offset:20480
	ds_read_b128 v[208:211], v191 offset:21504
	ds_read_b128 v[212:215], v191 offset:22528
	ds_read_b128 v[216:219], v191 offset:23552
	global_load_lds_dwordx4 v[184:185], off
	s_add_i32 m0, s22, 0x2000
	s_add_u32 s22, s38, 0xb0000
	v_lshl_add_u64 v[220:221], s[38:39], 0, v[158:159]
	s_addc_u32 s23, s39, 0
	s_add_i32 s58, s50, s42
	global_load_lds_dwordx4 v[220:221], off
	v_lshl_add_u64 v[222:223], s[22:23], 0, v[154:155]
	s_mov_b32 m0, s58
	v_lshl_add_u64 v[224:225], s[40:41], 0, v[156:157]
	global_load_lds_dwordx4 v[222:223], off
	s_add_i32 m0, s58, 0x2000
	v_lshl_add_u64 v[222:223], s[22:23], 0, v[158:159]
	global_load_lds_dwordx4 v[222:223], off
	s_mov_b32 m0, s43
	v_lshl_add_u64 v[222:223], s[40:41], 0, v[152:153]
	global_load_lds_dwordx4 v[222:223], off
	s_mov_b32 m0, s44
	s_nop 0
	global_load_lds_dwordx4 v[224:225], off
	s_waitcnt vmcnt(8) lgkmcnt(0)
	s_setprio 1
	s_barrier
	v_mfma_f32_16x16x32_bf16 v[60:63], v[128:131], v[176:179], v[60:63]
	v_mfma_f32_16x16x32_bf16 v[56:59], v[136:139], v[176:179], v[56:59]
	v_mfma_f32_16x16x32_bf16 v[44:47], v[128:131], v[194:197], v[44:47]
	v_mfma_f32_16x16x32_bf16 v[40:43], v[136:139], v[194:197], v[40:43]
	v_mfma_f32_16x16x32_bf16 v[28:31], v[128:131], v[204:207], v[28:31]
	v_mfma_f32_16x16x32_bf16 v[24:27], v[136:139], v[204:207], v[24:27]
	v_mfma_f32_16x16x32_bf16 v[12:15], v[128:131], v[212:215], v[12:15]
	v_mfma_f32_16x16x32_bf16 v[8:11], v[136:139], v[212:215], v[8:11]
	v_mfma_f32_16x16x32_bf16 v[60:63], v[132:135], v[180:183], v[60:63]
	v_mfma_f32_16x16x32_bf16 v[56:59], v[140:143], v[180:183], v[56:59]
	v_mfma_f32_16x16x32_bf16 v[44:47], v[132:135], v[198:201], v[44:47]
	v_mfma_f32_16x16x32_bf16 v[40:43], v[140:143], v[198:201], v[40:43]
	v_mfma_f32_16x16x32_bf16 v[28:31], v[132:135], v[208:211], v[28:31]
	v_mfma_f32_16x16x32_bf16 v[24:27], v[140:143], v[208:211], v[24:27]
	v_mfma_f32_16x16x32_bf16 v[12:15], v[132:135], v[216:219], v[12:15]
	v_mfma_f32_16x16x32_bf16 v[8:11], v[140:143], v[216:219], v[8:11]
	s_setprio 0
	s_setprio 1
	v_mfma_f32_16x16x32_bf16 v[52:55], v[144:147], v[176:179], v[52:55]
	v_mfma_f32_16x16x32_bf16 v[48:51], v[168:171], v[176:179], v[48:51]
	v_mfma_f32_16x16x32_bf16 v[36:39], v[144:147], v[194:197], v[36:39]
	v_mfma_f32_16x16x32_bf16 v[32:35], v[168:171], v[194:197], v[32:35]
	v_mfma_f32_16x16x32_bf16 v[20:23], v[144:147], v[204:207], v[20:23]
	v_mfma_f32_16x16x32_bf16 v[16:19], v[168:171], v[204:207], v[16:19]
	v_mfma_f32_16x16x32_bf16 v[4:7], v[144:147], v[212:215], v[4:7]
	v_mfma_f32_16x16x32_bf16 v[0:3], v[168:171], v[212:215], v[0:3]
	v_mfma_f32_16x16x32_bf16 v[52:55], v[148:151], v[180:183], v[52:55]
	v_mfma_f32_16x16x32_bf16 v[48:51], v[172:175], v[180:183], v[48:51]
	v_mfma_f32_16x16x32_bf16 v[36:39], v[148:151], v[198:201], v[36:39]
	v_mfma_f32_16x16x32_bf16 v[32:35], v[172:175], v[198:201], v[32:35]
	v_mfma_f32_16x16x32_bf16 v[20:23], v[148:151], v[208:211], v[20:23]
	v_mfma_f32_16x16x32_bf16 v[16:19], v[172:175], v[208:211], v[16:19]
	v_mfma_f32_16x16x32_bf16 v[4:7], v[148:151], v[216:219], v[4:7]
	v_mfma_f32_16x16x32_bf16 v[0:3], v[172:175], v[216:219], v[0:3]
	s_setprio 0
	s_barrier
	s_add_i32 s58, 0, 0x18000
	s_add_i32 s59, 0, 0x1c000
	v_add_u32_e32 v140, s58, v187
	v_add_u32_e32 v172, s59, v187
	ds_read_b128 v[128:131], v140
	ds_read_b128 v[132:135], v140 offset:1024
	ds_read_b128 v[136:139], v140 offset:2048
	ds_read_b128 v[140:143], v140 offset:3072
	ds_read_b128 v[144:147], v172
	ds_read_b128 v[148:151], v172 offset:1024
	ds_read_b128 v[168:171], v172 offset:2048
	ds_read_b128 v[172:175], v172 offset:3072
	s_add_u32 s22, s40, 0xb0000
	s_addc_u32 s23, s41, 0
	s_mov_b32 m0, s45
	v_lshl_add_u64 v[226:227], s[22:23], 0, v[152:153]
	ds_read_b128 v[176:179], v191 offset:32768
	ds_read_b128 v[180:183], v191 offset:33792
	ds_read_b128 v[194:197], v191 offset:34816
	ds_read_b128 v[198:201], v191 offset:35840
	ds_read_b128 v[204:207], v191 offset:36864
	ds_read_b128 v[208:211], v191 offset:37888
	ds_read_b128 v[212:215], v191 offset:38912
	ds_read_b128 v[216:219], v191 offset:39936
	global_load_lds_dwordx4 v[226:227], off
	s_mov_b32 m0, s46
	v_lshl_add_u64 v[226:227], s[22:23], 0, v[156:157]
	global_load_lds_dwordx4 v[226:227], off
	s_waitcnt vmcnt(8) lgkmcnt(0)
	s_setprio 1
	s_barrier
	v_mfma_f32_16x16x32_bf16 v[124:127], v[128:131], v[176:179], v[124:127]
	v_mfma_f32_16x16x32_bf16 v[120:123], v[136:139], v[176:179], v[120:123]
	v_mfma_f32_16x16x32_bf16 v[108:111], v[128:131], v[194:197], v[108:111]
	v_mfma_f32_16x16x32_bf16 v[104:107], v[136:139], v[194:197], v[104:107]
	v_mfma_f32_16x16x32_bf16 v[92:95], v[128:131], v[204:207], v[92:95]
	v_mfma_f32_16x16x32_bf16 v[88:91], v[136:139], v[204:207], v[88:91]
	v_mfma_f32_16x16x32_bf16 v[76:79], v[128:131], v[212:215], v[76:79]
	v_mfma_f32_16x16x32_bf16 v[72:75], v[136:139], v[212:215], v[72:75]
	v_mfma_f32_16x16x32_bf16 v[124:127], v[132:135], v[180:183], v[124:127]
	v_mfma_f32_16x16x32_bf16 v[120:123], v[140:143], v[180:183], v[120:123]
	v_mfma_f32_16x16x32_bf16 v[108:111], v[132:135], v[198:201], v[108:111]
	v_mfma_f32_16x16x32_bf16 v[104:107], v[140:143], v[198:201], v[104:107]
	v_mfma_f32_16x16x32_bf16 v[92:95], v[132:135], v[208:211], v[92:95]
	v_mfma_f32_16x16x32_bf16 v[88:91], v[140:143], v[208:211], v[88:91]
	v_mfma_f32_16x16x32_bf16 v[76:79], v[132:135], v[216:219], v[76:79]
	v_mfma_f32_16x16x32_bf16 v[72:75], v[140:143], v[216:219], v[72:75]
	s_setprio 0
	s_setprio 1
	v_mfma_f32_16x16x32_bf16 v[116:119], v[144:147], v[176:179], v[116:119]
	v_mfma_f32_16x16x32_bf16 v[112:115], v[168:171], v[176:179], v[112:115]
	v_mfma_f32_16x16x32_bf16 v[100:103], v[144:147], v[194:197], v[100:103]
	v_mfma_f32_16x16x32_bf16 v[96:99], v[168:171], v[194:197], v[96:99]
	v_mfma_f32_16x16x32_bf16 v[84:87], v[144:147], v[204:207], v[84:87]
	v_mfma_f32_16x16x32_bf16 v[80:83], v[168:171], v[204:207], v[80:83]
	v_mfma_f32_16x16x32_bf16 v[68:71], v[144:147], v[212:215], v[68:71]
	v_mfma_f32_16x16x32_bf16 v[64:67], v[168:171], v[212:215], v[64:67]
	v_mfma_f32_16x16x32_bf16 v[116:119], v[148:151], v[180:183], v[116:119]
	v_mfma_f32_16x16x32_bf16 v[112:115], v[172:175], v[180:183], v[112:115]
	v_mfma_f32_16x16x32_bf16 v[100:103], v[148:151], v[198:201], v[100:103]
	v_mfma_f32_16x16x32_bf16 v[96:99], v[172:175], v[198:201], v[96:99]
	v_mfma_f32_16x16x32_bf16 v[84:87], v[148:151], v[208:211], v[84:87]
	v_mfma_f32_16x16x32_bf16 v[80:83], v[172:175], v[208:211], v[80:83]
	v_mfma_f32_16x16x32_bf16 v[68:71], v[148:151], v[216:219], v[68:71]
	v_mfma_f32_16x16x32_bf16 v[64:67], v[172:175], v[216:219], v[64:67]
	s_setprio 0
	s_barrier
	s_add_i32 s22, s58, s42
	v_lshl_add_u64 v[184:185], v[184:185], 0, s[30:31]
	s_mov_b32 m0, s22
	ds_read_b128 v[176:179], v191 offset:49152
	ds_read_b128 v[180:183], v191 offset:50176
	ds_read_b128 v[194:197], v191 offset:51200
	ds_read_b128 v[198:201], v191 offset:52224
	ds_read_b128 v[204:207], v191 offset:53248
	ds_read_b128 v[208:211], v191 offset:54272
	ds_read_b128 v[212:215], v191 offset:55296
	ds_read_b128 v[216:219], v191 offset:56320
	global_load_lds_dwordx4 v[184:185], off
	s_add_i32 m0, s22, 0x2000
	s_add_u32 s22, s38, 0xb0080
	v_lshl_add_u64 v[184:185], v[220:221], 0, s[30:31]
	s_addc_u32 s23, s39, 0
	s_add_i32 s38, s59, s42
	global_load_lds_dwordx4 v[184:185], off
	s_mov_b32 m0, s38
	v_lshl_add_u64 v[184:185], s[22:23], 0, v[154:155]
	global_load_lds_dwordx4 v[184:185], off
	s_add_i32 m0, s38, 0x2000
	v_lshl_add_u64 v[184:185], s[22:23], 0, v[158:159]
	global_load_lds_dwordx4 v[184:185], off
	s_mov_b32 m0, s33
	v_lshl_add_u64 v[184:185], v[222:223], 0, s[30:31]
	global_load_lds_dwordx4 v[184:185], off
	s_mov_b32 m0, s48
	v_lshl_add_u64 v[184:185], v[224:225], 0, s[30:31]
	global_load_lds_dwordx4 v[184:185], off
	s_waitcnt vmcnt(8) lgkmcnt(0)
	s_setprio 1
	s_barrier
	v_mfma_f32_16x16x32_bf16 v[60:63], v[128:131], v[176:179], v[60:63]
	v_mfma_f32_16x16x32_bf16 v[56:59], v[136:139], v[176:179], v[56:59]
	v_mfma_f32_16x16x32_bf16 v[44:47], v[128:131], v[194:197], v[44:47]
	v_mfma_f32_16x16x32_bf16 v[40:43], v[136:139], v[194:197], v[40:43]
	v_mfma_f32_16x16x32_bf16 v[28:31], v[128:131], v[204:207], v[28:31]
	v_mfma_f32_16x16x32_bf16 v[24:27], v[136:139], v[204:207], v[24:27]
	v_mfma_f32_16x16x32_bf16 v[12:15], v[128:131], v[212:215], v[12:15]
	v_mfma_f32_16x16x32_bf16 v[8:11], v[136:139], v[212:215], v[8:11]
	v_mfma_f32_16x16x32_bf16 v[60:63], v[132:135], v[180:183], v[60:63]
	v_mfma_f32_16x16x32_bf16 v[56:59], v[140:143], v[180:183], v[56:59]
	v_mfma_f32_16x16x32_bf16 v[44:47], v[132:135], v[198:201], v[44:47]
	v_mfma_f32_16x16x32_bf16 v[40:43], v[140:143], v[198:201], v[40:43]
	v_mfma_f32_16x16x32_bf16 v[28:31], v[132:135], v[208:211], v[28:31]
	v_mfma_f32_16x16x32_bf16 v[24:27], v[140:143], v[208:211], v[24:27]
	v_mfma_f32_16x16x32_bf16 v[12:15], v[132:135], v[216:219], v[12:15]
	v_mfma_f32_16x16x32_bf16 v[8:11], v[140:143], v[216:219], v[8:11]
	s_setprio 0
	s_setprio 1
	v_mfma_f32_16x16x32_bf16 v[52:55], v[144:147], v[176:179], v[52:55]
	v_mfma_f32_16x16x32_bf16 v[48:51], v[168:171], v[176:179], v[48:51]
	v_mfma_f32_16x16x32_bf16 v[36:39], v[144:147], v[194:197], v[36:39]
	v_mfma_f32_16x16x32_bf16 v[32:35], v[168:171], v[194:197], v[32:35]
	v_mfma_f32_16x16x32_bf16 v[20:23], v[144:147], v[204:207], v[20:23]
	v_mfma_f32_16x16x32_bf16 v[16:19], v[168:171], v[204:207], v[16:19]
	v_mfma_f32_16x16x32_bf16 v[4:7], v[144:147], v[212:215], v[4:7]
	v_mfma_f32_16x16x32_bf16 v[0:3], v[168:171], v[212:215], v[0:3]
	v_mfma_f32_16x16x32_bf16 v[52:55], v[148:151], v[180:183], v[52:55]
	v_mfma_f32_16x16x32_bf16 v[48:51], v[172:175], v[180:183], v[48:51]
	v_mfma_f32_16x16x32_bf16 v[36:39], v[148:151], v[198:201], v[36:39]
	v_mfma_f32_16x16x32_bf16 v[32:35], v[172:175], v[198:201], v[32:35]
	v_mfma_f32_16x16x32_bf16 v[20:23], v[148:151], v[208:211], v[20:23]
	v_mfma_f32_16x16x32_bf16 v[16:19], v[172:175], v[208:211], v[16:19]
	v_mfma_f32_16x16x32_bf16 v[4:7], v[148:151], v[216:219], v[4:7]
	v_mfma_f32_16x16x32_bf16 v[0:3], v[172:175], v[216:219], v[0:3]
	s_setprio 0
	s_add_i32 s57, s57, 2
	s_add_u32 s55, s55, 0x100
	s_addc_u32 s56, s56, 0
	s_cmp_gt_u32 s57, 41
	s_mov_b64 s[22:23], s[4:5]
	s_barrier
	s_cbranch_scc0 .LBB0_559
	s_and_b64 vcc, exec, s[34:35]
	s_cbranch_vccz .LBB0_562
	s_barrier

.LBB0_578:
	s_or_b64 exec, exec, s[4:5]
	s_and_b64 vcc, exec, s[8:9]
	s_mov_b64 s[4:5], -1
	s_cbranch_vccnz .LBB0_547
	s_andn2_b64 vcc, exec, s[16:17]
	s_cbranch_vccnz .LBB0_546
	s_mov_b32 s90, 1
	s_branch .LBB0_546

.LBB0_632:
	s_mov_b32 s90, 0
	s_or_b64 exec, exec, s[6:7]
	s_cmpk_lt_i32 s2, 0x600
	s_mov_b64 s[4:5], s[0:1]
	s_waitcnt lgkmcnt(0)
	v_mov_b32_e32 v0, v202
	v_mov_b32_e32 v8, v202
	s_barrier
	s_cselect_b64 s[6:7], -1, 0
	s_cmpk_gt_i32 s2, 0x5ff
	s_nop 0
	v_readfirstlane_b32 s8, v8
	s_cbranch_scc1 .LBB0_634
	s_lshr_b32 s9, s21, 29
	s_add_i32 s9, s2, s9
	s_ashr_i32 s10, s9, 3
	s_and_b32 s9, s9, -8
	s_sub_i32 s9, s2, s9
	s_cmp_lt_i32 s9, 0
	s_movk_i32 s11, 0xc1
	s_cselect_b32 s11, s11, 0xc0
	s_mul_i32 s9, s9, s11
	s_add_i32 s9, s9, s10
	s_mul_hi_i32 s10, s9, 0x2aaaaaab
	s_lshr_b32 s11, s10, 31
	s_ashr_i32 s10, s10, 4
	s_add_i32 s10, s10, s11
	s_lshl_b32 s11, s10, 3
	s_mulk_i32 s10, 0x60
	s_sub_i32 s9, s9, s10
	s_bfe_i32 s10, s9, 0x80000
	s_bfe_u32 s10, s10, 0x3000c
	s_add_i32 s10, s9, s10
	s_bfe_i32 s12, s10, 0x80000
	s_and_b32 s10, s10, 0xf8
	s_sub_i32 s9, s9, s10
	s_sext_i32_i16 s13, s12
	s_sext_i32_i8 s9, s9
	s_add_i32 s12, s11, s9
	s_ashr_i32 s16, s13, 3

.LBB0_642:
	s_ashr_i32 s41, s40, 31
	s_lshl_b64 s[42:43], s[40:41], 19
	s_add_u32 s42, s14, s42
	s_addc_u32 s43, s15, s43
	s_and_b64 s[44:45], s[10:11], exec
	s_cselect_b32 s13, s43, s23
	s_cselect_b32 s17, s42, s22
	s_ashr_i32 s39, s38, 31
	s_lshl_b64 s[44:45], s[38:39], 19
	s_add_u32 s44, s20, s44
	s_addc_u32 s45, s25, s45
	s_and_b64 s[46:47], s[10:11], exec
	s_cselect_b32 s33, s45, s5
	s_cselect_b32 s39, s44, s4
	s_add_u32 s22, s22, 0x40080
	s_addc_u32 s23, s23, 0
	s_add_u32 s41, s4, 0x100
	v_mov_b32_e32 v0, 0
	s_addc_u32 s62, s5, 0
	s_mov_b32 s63, -2
	v_mov_b32_e32 v1, v0
	v_mov_b32_e32 v2, v0
	v_mov_b32_e32 v3, v0
	v_mov_b32_e32 v4, v0
	v_mov_b32_e32 v5, v0
	v_mov_b32_e32 v6, v0
	v_mov_b32_e32 v7, v0
	s_waitcnt vmcnt(0)
	v_mov_b32_e32 v16, v0
	v_mov_b32_e32 v17, v0
	v_mov_b32_e32 v18, v0
	v_mov_b32_e32 v19, v0
	v_mov_b32_e32 v20, v0
	v_mov_b32_e32 v21, v0
	v_mov_b32_e32 v22, v0
	v_mov_b32_e32 v23, v0
	v_mov_b32_e32 v32, v0
	v_mov_b32_e32 v33, v0
	v_mov_b32_e32 v34, v0
	v_mov_b32_e32 v35, v0
	v_mov_b32_e32 v36, v0
	v_mov_b32_e32 v37, v0
	v_mov_b32_e32 v38, v0
	v_mov_b32_e32 v39, v0
	s_waitcnt vmcnt(0)
	v_mov_b32_e32 v48, v0
	v_mov_b32_e32 v49, v0
	v_mov_b32_e32 v50, v0
	v_mov_b32_e32 v51, v0
	v_mov_b32_e32 v52, v0
	v_mov_b32_e32 v53, v0
	v_mov_b32_e32 v54, v0
	v_mov_b32_e32 v55, v0
	v_mov_b32_e32 v8, v0
	v_mov_b32_e32 v9, v0
	v_mov_b32_e32 v10, v0
	v_mov_b32_e32 v11, v0
	v_mov_b32_e32 v12, v0
	v_mov_b32_e32 v13, v0
	v_mov_b32_e32 v14, v0
	v_mov_b32_e32 v15, v0
	v_mov_b32_e32 v24, v0
	v_mov_b32_e32 v25, v0
	v_mov_b32_e32 v26, v0
	v_mov_b32_e32 v27, v0
	v_mov_b32_e32 v28, v0
	v_mov_b32_e32 v29, v0
	v_mov_b32_e32 v30, v0
	v_mov_b32_e32 v31, v0
	v_mov_b32_e32 v40, v0
	v_mov_b32_e32 v41, v0
	v_mov_b32_e32 v42, v0
	v_mov_b32_e32 v43, v0
	v_mov_b32_e32 v44, v0
	v_mov_b32_e32 v45, v0
	v_mov_b32_e32 v46, v0
	v_mov_b32_e32 v47, v0
	v_mov_b32_e32 v56, v0
	v_mov_b32_e32 v57, v0
	v_mov_b32_e32 v58, v0
	v_mov_b32_e32 v59, v0
	v_mov_b32_e32 v60, v0
	v_mov_b32_e32 v61, v0
	v_mov_b32_e32 v62, v0
	v_mov_b32_e32 v63, v0
	v_mov_b32_e32 v64, v0
	v_mov_b32_e32 v65, v0
	v_mov_b32_e32 v66, v0
	v_mov_b32_e32 v67, v0
	v_mov_b32_e32 v68, v0
	v_mov_b32_e32 v69, v0
	v_mov_b32_e32 v70, v0
	v_mov_b32_e32 v71, v0
	v_mov_b32_e32 v80, v0
	v_mov_b32_e32 v81, v0
	v_mov_b32_e32 v82, v0
	v_mov_b32_e32 v83, v0
	v_mov_b32_e32 v84, v0
	v_mov_b32_e32 v85, v0
	v_mov_b32_e32 v86, v0
	v_mov_b32_e32 v87, v0
	v_mov_b32_e32 v96, v0
	v_mov_b32_e32 v97, v0
	v_mov_b32_e32 v98, v0
	v_mov_b32_e32 v99, v0
	v_mov_b32_e32 v100, v0
	v_mov_b32_e32 v101, v0
	v_mov_b32_e32 v102, v0
	v_mov_b32_e32 v103, v0
	v_mov_b32_e32 v112, v0
	v_mov_b32_e32 v113, v0
	v_mov_b32_e32 v114, v0
	v_mov_b32_e32 v115, v0
	v_mov_b32_e32 v116, v0
	v_mov_b32_e32 v117, v0
	v_mov_b32_e32 v118, v0
	v_mov_b32_e32 v119, v0
	v_mov_b32_e32 v72, v0
	v_mov_b32_e32 v73, v0
	v_mov_b32_e32 v74, v0
	v_mov_b32_e32 v75, v0
	v_mov_b32_e32 v76, v0
	v_mov_b32_e32 v77, v0
	v_mov_b32_e32 v78, v0
	v_mov_b32_e32 v79, v0
	v_mov_b32_e32 v88, v0
	v_mov_b32_e32 v89, v0
	v_mov_b32_e32 v90, v0
	v_mov_b32_e32 v91, v0
	v_mov_b32_e32 v92, v0
	v_mov_b32_e32 v93, v0
	v_mov_b32_e32 v94, v0
	v_mov_b32_e32 v95, v0
	v_mov_b32_e32 v104, v0
	v_mov_b32_e32 v105, v0
	v_mov_b32_e32 v106, v0
	v_mov_b32_e32 v107, v0
	v_mov_b32_e32 v108, v0
	v_mov_b32_e32 v109, v0
	v_mov_b32_e32 v110, v0
	v_mov_b32_e32 v111, v0
	v_mov_b32_e32 v120, v0
	v_mov_b32_e32 v121, v0
	v_mov_b32_e32 v122, v0
	v_mov_b32_e32 v123, v0
	v_mov_b32_e32 v124, v0
	v_mov_b32_e32 v125, v0
	v_mov_b32_e32 v126, v0
	v_mov_b32_e32 v127, v0
	s_cmp_lg_u32 s90, 0
	s_cbranch_scc0 .Lkl_nobar_4
	s_barrier
	s_mov_b32 s90, 0
.Lkl_nobar_4:
.LBB0_643:
	ds_read_b128 v[128:131], v191
	ds_read_b128 v[132:135], v191 offset:1024
	ds_read_b128 v[156:159], v191 offset:2048
	ds_read_b128 v[160:163], v191 offset:3072
	ds_read_b128 v[164:167], v192
	ds_read_b128 v[168:171], v192 offset:1024
	ds_read_b128 v[172:175], v192 offset:2048
	ds_read_b128 v[176:179], v192 offset:3072
	s_add_u32 s4, s22, 0xfffc0080
	s_addc_u32 s5, s23, -1
	s_cmp_eq_u32 s63, 12
	s_cselect_b32 s47, s13, s5
	s_cselect_b32 s46, s17, s4
	s_cselect_b32 s5, s33, s62
	s_cselect_b32 s4, s39, s41
	v_lshl_add_u64 v[224:225], s[22:23], 0, v[148:149]
	s_add_i32 m0, s49, 0xc000
	ds_read_b128 v[180:183], v193
	ds_read_b128 v[184:187], v193 offset:1024
	ds_read_b128 v[198:201], v193 offset:2048
	ds_read_b128 v[204:207], v193 offset:3072
	ds_read_b128 v[208:211], v193 offset:4096
	ds_read_b128 v[212:215], v193 offset:5120
	ds_read_b128 v[216:219], v193 offset:6144
	ds_read_b128 v[220:223], v193 offset:7168
	global_load_lds_dwordx4 v[224:225], off
	s_add_i32 m0, s49, 0xe000
	v_lshl_add_u64 v[224:225], s[22:23], 0, v[150:151]
	global_load_lds_dwordx4 v[224:225], off
	s_waitcnt vmcnt(8) lgkmcnt(0)
	s_setprio 1
	s_barrier
	v_mfma_f32_16x16x32_bf16 v[124:127], v[128:131], v[180:183], v[124:127]
	v_mfma_f32_16x16x32_bf16 v[120:123], v[156:159], v[180:183], v[120:123]
	v_mfma_f32_16x16x32_bf16 v[108:111], v[128:131], v[198:201], v[108:111]
	v_mfma_f32_16x16x32_bf16 v[104:107], v[156:159], v[198:201], v[104:107]
	v_mfma_f32_16x16x32_bf16 v[92:95], v[128:131], v[208:211], v[92:95]
	v_mfma_f32_16x16x32_bf16 v[88:91], v[156:159], v[208:211], v[88:91]
	v_mfma_f32_16x16x32_bf16 v[76:79], v[128:131], v[216:219], v[76:79]
	v_mfma_f32_16x16x32_bf16 v[72:75], v[156:159], v[216:219], v[72:75]
	v_mfma_f32_16x16x32_bf16 v[124:127], v[132:135], v[184:187], v[124:127]
	v_mfma_f32_16x16x32_bf16 v[120:123], v[160:163], v[184:187], v[120:123]
	v_mfma_f32_16x16x32_bf16 v[108:111], v[132:135], v[204:207], v[108:111]
	v_mfma_f32_16x16x32_bf16 v[104:107], v[160:163], v[204:207], v[104:107]
	v_mfma_f32_16x16x32_bf16 v[92:95], v[132:135], v[212:215], v[92:95]
	v_mfma_f32_16x16x32_bf16 v[88:91], v[160:163], v[212:215], v[88:91]
	v_mfma_f32_16x16x32_bf16 v[76:79], v[132:135], v[220:223], v[76:79]
	v_mfma_f32_16x16x32_bf16 v[72:75], v[160:163], v[220:223], v[72:75]
	s_setprio 0
	s_setprio 1
	v_mfma_f32_16x16x32_bf16 v[116:119], v[164:167], v[180:183], v[116:119]
	v_mfma_f32_16x16x32_bf16 v[112:115], v[172:175], v[180:183], v[112:115]
	v_mfma_f32_16x16x32_bf16 v[100:103], v[164:167], v[198:201], v[100:103]
	v_mfma_f32_16x16x32_bf16 v[96:99], v[172:175], v[198:201], v[96:99]
	v_mfma_f32_16x16x32_bf16 v[84:87], v[164:167], v[208:211], v[84:87]
	v_mfma_f32_16x16x32_bf16 v[80:83], v[172:175], v[208:211], v[80:83]
	v_mfma_f32_16x16x32_bf16 v[68:71], v[164:167], v[216:219], v[68:71]
	v_mfma_f32_16x16x32_bf16 v[64:67], v[172:175], v[216:219], v[64:67]
	v_mfma_f32_16x16x32_bf16 v[116:119], v[168:171], v[184:187], v[116:119]
	v_mfma_f32_16x16x32_bf16 v[112:115], v[176:179], v[184:187], v[112:115]
	v_mfma_f32_16x16x32_bf16 v[100:103], v[168:171], v[204:207], v[100:103]
	v_mfma_f32_16x16x32_bf16 v[96:99], v[176:179], v[204:207], v[96:99]
	v_mfma_f32_16x16x32_bf16 v[84:87], v[168:171], v[212:215], v[84:87]
	v_mfma_f32_16x16x32_bf16 v[80:83], v[176:179], v[212:215], v[80:83]
	v_mfma_f32_16x16x32_bf16 v[68:71], v[168:171], v[220:223], v[68:71]
	v_mfma_f32_16x16x32_bf16 v[64:67], v[176:179], v[220:223], v[64:67]
	s_setprio 0
	s_barrier
	s_add_i32 s64, s59, s48
	v_lshl_add_u64 v[224:225], s[4:5], 0, v[138:139]
	s_mov_b32 m0, s64
	ds_read_b128 v[180:183], v193 offset:16384
	ds_read_b128 v[184:187], v193 offset:17408
	ds_read_b128 v[198:201], v193 offset:18432
	ds_read_b128 v[204:207], v193 offset:19456
	ds_read_b128 v[208:211], v193 offset:20480
	ds_read_b128 v[212:215], v193 offset:21504
	ds_read_b128 v[216:219], v193 offset:22528
	ds_read_b128 v[220:223], v193 offset:23552
	global_load_lds_dwordx4 v[224:225], off
	s_add_i32 m0, s64, 0x2000
	s_add_u32 s64, s4, 0x40000
	v_lshl_add_u64 v[226:227], s[4:5], 0, v[142:143]
	s_addc_u32 s65, s5, 0
	s_add_i32 s66, s60, s48
	global_load_lds_dwordx4 v[226:227], off
	v_lshl_add_u64 v[228:229], s[64:65], 0, v[138:139]
	s_mov_b32 m0, s66
	v_lshl_add_u64 v[230:231], s[46:47], 0, v[140:141]
	global_load_lds_dwordx4 v[228:229], off
	s_add_i32 m0, s66, 0x2000
	v_lshl_add_u64 v[228:229], s[64:65], 0, v[142:143]
	global_load_lds_dwordx4 v[228:229], off
	s_mov_b32 m0, s49
	v_lshl_add_u64 v[228:229], s[46:47], 0, v[136:137]
	global_load_lds_dwordx4 v[228:229], off
	s_mov_b32 m0, s50
	s_nop 0
	global_load_lds_dwordx4 v[230:231], off
	s_waitcnt vmcnt(8) lgkmcnt(0)
	s_setprio 1
	s_barrier
	v_mfma_f32_16x16x32_bf16 v[60:63], v[128:131], v[180:183], v[60:63]
	v_mfma_f32_16x16x32_bf16 v[56:59], v[156:159], v[180:183], v[56:59]
	v_mfma_f32_16x16x32_bf16 v[44:47], v[128:131], v[198:201], v[44:47]
	v_mfma_f32_16x16x32_bf16 v[40:43], v[156:159], v[198:201], v[40:43]
	v_mfma_f32_16x16x32_bf16 v[28:31], v[128:131], v[208:211], v[28:31]
	v_mfma_f32_16x16x32_bf16 v[24:27], v[156:159], v[208:211], v[24:27]
	v_mfma_f32_16x16x32_bf16 v[12:15], v[128:131], v[216:219], v[12:15]
	v_mfma_f32_16x16x32_bf16 v[8:11], v[156:159], v[216:219], v[8:11]
	v_mfma_f32_16x16x32_bf16 v[60:63], v[132:135], v[184:187], v[60:63]
	v_mfma_f32_16x16x32_bf16 v[56:59], v[160:163], v[184:187], v[56:59]
	v_mfma_f32_16x16x32_bf16 v[44:47], v[132:135], v[204:207], v[44:47]
	v_mfma_f32_16x16x32_bf16 v[40:43], v[160:163], v[204:207], v[40:43]
	v_mfma_f32_16x16x32_bf16 v[28:31], v[132:135], v[212:215], v[28:31]
	v_mfma_f32_16x16x32_bf16 v[24:27], v[160:163], v[212:215], v[24:27]
	v_mfma_f32_16x16x32_bf16 v[12:15], v[132:135], v[220:223], v[12:15]
	v_mfma_f32_16x16x32_bf16 v[8:11], v[160:163], v[220:223], v[8:11]
	s_setprio 0
	s_setprio 1
	v_mfma_f32_16x16x32_bf16 v[52:55], v[164:167], v[180:183], v[52:55]
	v_mfma_f32_16x16x32_bf16 v[48:51], v[172:175], v[180:183], v[48:51]
	v_mfma_f32_16x16x32_bf16 v[36:39], v[164:167], v[198:201], v[36:39]
	v_mfma_f32_16x16x32_bf16 v[32:35], v[172:175], v[198:201], v[32:35]
	v_mfma_f32_16x16x32_bf16 v[20:23], v[164:167], v[208:211], v[20:23]
	v_mfma_f32_16x16x32_bf16 v[16:19], v[172:175], v[208:211], v[16:19]
	v_mfma_f32_16x16x32_bf16 v[4:7], v[164:167], v[216:219], v[4:7]
	v_mfma_f32_16x16x32_bf16 v[0:3], v[172:175], v[216:219], v[0:3]
	v_mfma_f32_16x16x32_bf16 v[52:55], v[168:171], v[184:187], v[52:55]
	v_mfma_f32_16x16x32_bf16 v[48:51], v[176:179], v[184:187], v[48:51]
	v_mfma_f32_16x16x32_bf16 v[36:39], v[168:171], v[204:207], v[36:39]
	v_mfma_f32_16x16x32_bf16 v[32:35], v[176:179], v[204:207], v[32:35]
	v_mfma_f32_16x16x32_bf16 v[20:23], v[168:171], v[212:215], v[20:23]
	v_mfma_f32_16x16x32_bf16 v[16:19], v[176:179], v[212:215], v[16:19]
	v_mfma_f32_16x16x32_bf16 v[4:7], v[168:171], v[220:223], v[4:7]
	v_mfma_f32_16x16x32_bf16 v[0:3], v[176:179], v[220:223], v[0:3]
	s_setprio 0
	s_barrier
	s_add_i32 s64, 0, 0x18000
	v_add_u32_e32 v144, s64, v189
	s_add_i32 s65, 0, 0x1c000
	ds_read_b128 v[128:131], v144
	ds_read_b128 v[132:135], v144 offset:1024
	ds_read_b128 v[156:159], v144 offset:2048
	ds_read_b128 v[160:163], v144 offset:3072
	v_add_u32_e32 v144, s65, v189
	ds_read_b128 v[164:167], v144
	ds_read_b128 v[168:171], v144 offset:1024
	ds_read_b128 v[172:175], v144 offset:2048
	ds_read_b128 v[176:179], v144 offset:3072
	s_add_u32 s46, s46, 0x40000
	s_addc_u32 s47, s47, 0
	s_mov_b32 m0, s51
	v_lshl_add_u64 v[232:233], s[46:47], 0, v[136:137]
	ds_read_b128 v[180:183], v193 offset:32768
	ds_read_b128 v[184:187], v193 offset:33792
	ds_read_b128 v[198:201], v193 offset:34816
	ds_read_b128 v[204:207], v193 offset:35840
	ds_read_b128 v[208:211], v193 offset:36864
	ds_read_b128 v[212:215], v193 offset:37888
	ds_read_b128 v[216:219], v193 offset:38912
	ds_read_b128 v[220:223], v193 offset:39936
	global_load_lds_dwordx4 v[232:233], off
	s_mov_b32 m0, s52
	v_lshl_add_u64 v[232:233], s[46:47], 0, v[140:141]
	global_load_lds_dwordx4 v[232:233], off
	s_waitcnt vmcnt(8) lgkmcnt(0)
	s_setprio 1
	s_barrier
	v_mfma_f32_16x16x32_bf16 v[124:127], v[128:131], v[180:183], v[124:127]
	v_mfma_f32_16x16x32_bf16 v[120:123], v[156:159], v[180:183], v[120:123]
	v_mfma_f32_16x16x32_bf16 v[108:111], v[128:131], v[198:201], v[108:111]
	v_mfma_f32_16x16x32_bf16 v[104:107], v[156:159], v[198:201], v[104:107]
	v_mfma_f32_16x16x32_bf16 v[92:95], v[128:131], v[208:211], v[92:95]
	v_mfma_f32_16x16x32_bf16 v[88:91], v[156:159], v[208:211], v[88:91]
	v_mfma_f32_16x16x32_bf16 v[76:79], v[128:131], v[216:219], v[76:79]
	v_mfma_f32_16x16x32_bf16 v[72:75], v[156:159], v[216:219], v[72:75]
	v_mfma_f32_16x16x32_bf16 v[124:127], v[132:135], v[184:187], v[124:127]
	v_mfma_f32_16x16x32_bf16 v[120:123], v[160:163], v[184:187], v[120:123]
	v_mfma_f32_16x16x32_bf16 v[108:111], v[132:135], v[204:207], v[108:111]
	v_mfma_f32_16x16x32_bf16 v[104:107], v[160:163], v[204:207], v[104:107]
	v_mfma_f32_16x16x32_bf16 v[92:95], v[132:135], v[212:215], v[92:95]
	v_mfma_f32_16x16x32_bf16 v[88:91], v[160:163], v[212:215], v[88:91]
	v_mfma_f32_16x16x32_bf16 v[76:79], v[132:135], v[220:223], v[76:79]
	v_mfma_f32_16x16x32_bf16 v[72:75], v[160:163], v[220:223], v[72:75]
	s_setprio 0
	s_setprio 1
	v_mfma_f32_16x16x32_bf16 v[116:119], v[164:167], v[180:183], v[116:119]
	v_mfma_f32_16x16x32_bf16 v[112:115], v[172:175], v[180:183], v[112:115]
	v_mfma_f32_16x16x32_bf16 v[100:103], v[164:167], v[198:201], v[100:103]
	v_mfma_f32_16x16x32_bf16 v[96:99], v[172:175], v[198:201], v[96:99]
	v_mfma_f32_16x16x32_bf16 v[84:87], v[164:167], v[208:211], v[84:87]
	v_mfma_f32_16x16x32_bf16 v[80:83], v[172:175], v[208:211], v[80:83]
	v_mfma_f32_16x16x32_bf16 v[68:71], v[164:167], v[216:219], v[68:71]
	v_mfma_f32_16x16x32_bf16 v[64:67], v[172:175], v[216:219], v[64:67]
	v_mfma_f32_16x16x32_bf16 v[116:119], v[168:171], v[184:187], v[116:119]
	v_mfma_f32_16x16x32_bf16 v[112:115], v[176:179], v[184:187], v[112:115]
	v_mfma_f32_16x16x32_bf16 v[100:103], v[168:171], v[204:207], v[100:103]
	v_mfma_f32_16x16x32_bf16 v[96:99], v[176:179], v[204:207], v[96:99]
	v_mfma_f32_16x16x32_bf16 v[84:87], v[168:171], v[212:215], v[84:87]
	v_mfma_f32_16x16x32_bf16 v[80:83], v[176:179], v[212:215], v[80:83]
	v_mfma_f32_16x16x32_bf16 v[68:71], v[168:171], v[220:223], v[68:71]
	v_mfma_f32_16x16x32_bf16 v[64:67], v[176:179], v[220:223], v[64:67]
	s_setprio 0
	s_barrier
	s_add_i32 s46, s64, s48
	v_lshl_add_u64 v[224:225], v[224:225], 0, s[30:31]
	s_mov_b32 m0, s46
	ds_read_b128 v[180:183], v193 offset:49152
	ds_read_b128 v[184:187], v193 offset:50176
	ds_read_b128 v[198:201], v193 offset:51200
	ds_read_b128 v[204:207], v193 offset:52224
	ds_read_b128 v[208:211], v193 offset:53248
	ds_read_b128 v[212:215], v193 offset:54272
	ds_read_b128 v[216:219], v193 offset:55296
	ds_read_b128 v[220:223], v193 offset:56320
	global_load_lds_dwordx4 v[224:225], off
	s_add_i32 m0, s46, 0x2000
	s_add_u32 s4, s4, 0x40080
	v_lshl_add_u64 v[224:225], v[226:227], 0, s[30:31]
	s_addc_u32 s5, s5, 0
	s_add_i32 s46, s65, s48
	global_load_lds_dwordx4 v[224:225], off
	s_mov_b32 m0, s46
	v_lshl_add_u64 v[224:225], s[4:5], 0, v[138:139]
	global_load_lds_dwordx4 v[224:225], off
	s_add_i32 m0, s46, 0x2000
	v_lshl_add_u64 v[224:225], s[4:5], 0, v[142:143]
	global_load_lds_dwordx4 v[224:225], off
	s_mov_b32 m0, s56
	v_lshl_add_u64 v[224:225], v[228:229], 0, s[30:31]
	global_load_lds_dwordx4 v[224:225], off
	s_mov_b32 m0, s57
	v_lshl_add_u64 v[224:225], v[230:231], 0, s[30:31]
	global_load_lds_dwordx4 v[224:225], off
	s_waitcnt vmcnt(8) lgkmcnt(0)
	s_setprio 1
	s_barrier
	v_mfma_f32_16x16x32_bf16 v[60:63], v[128:131], v[180:183], v[60:63]
	v_mfma_f32_16x16x32_bf16 v[56:59], v[156:159], v[180:183], v[56:59]
	v_mfma_f32_16x16x32_bf16 v[44:47], v[128:131], v[198:201], v[44:47]
	v_mfma_f32_16x16x32_bf16 v[40:43], v[156:159], v[198:201], v[40:43]
	v_mfma_f32_16x16x32_bf16 v[28:31], v[128:131], v[208:211], v[28:31]
	v_mfma_f32_16x16x32_bf16 v[24:27], v[156:159], v[208:211], v[24:27]
	v_mfma_f32_16x16x32_bf16 v[12:15], v[128:131], v[216:219], v[12:15]
	v_mfma_f32_16x16x32_bf16 v[8:11], v[156:159], v[216:219], v[8:11]
	v_mfma_f32_16x16x32_bf16 v[60:63], v[132:135], v[184:187], v[60:63]
	v_mfma_f32_16x16x32_bf16 v[56:59], v[160:163], v[184:187], v[56:59]
	v_mfma_f32_16x16x32_bf16 v[44:47], v[132:135], v[204:207], v[44:47]
	v_mfma_f32_16x16x32_bf16 v[40:43], v[160:163], v[204:207], v[40:43]
	v_mfma_f32_16x16x32_bf16 v[28:31], v[132:135], v[212:215], v[28:31]
	v_mfma_f32_16x16x32_bf16 v[24:27], v[160:163], v[212:215], v[24:27]
	v_mfma_f32_16x16x32_bf16 v[12:15], v[132:135], v[220:223], v[12:15]
	v_mfma_f32_16x16x32_bf16 v[8:11], v[160:163], v[220:223], v[8:11]
	s_setprio 0
	s_setprio 1
	v_mfma_f32_16x16x32_bf16 v[52:55], v[164:167], v[180:183], v[52:55]
	v_mfma_f32_16x16x32_bf16 v[48:51], v[172:175], v[180:183], v[48:51]
	v_mfma_f32_16x16x32_bf16 v[36:39], v[164:167], v[198:201], v[36:39]
	v_mfma_f32_16x16x32_bf16 v[32:35], v[172:175], v[198:201], v[32:35]
	v_mfma_f32_16x16x32_bf16 v[20:23], v[164:167], v[208:211], v[20:23]
	v_mfma_f32_16x16x32_bf16 v[16:19], v[172:175], v[208:211], v[16:19]
	v_mfma_f32_16x16x32_bf16 v[4:7], v[164:167], v[216:219], v[4:7]
	v_mfma_f32_16x16x32_bf16 v[0:3], v[172:175], v[216:219], v[0:3]
	v_mfma_f32_16x16x32_bf16 v[52:55], v[168:171], v[184:187], v[52:55]
	v_mfma_f32_16x16x32_bf16 v[48:51], v[176:179], v[184:187], v[48:51]
	v_mfma_f32_16x16x32_bf16 v[36:39], v[168:171], v[204:207], v[36:39]
	v_mfma_f32_16x16x32_bf16 v[32:35], v[176:179], v[204:207], v[32:35]
	v_mfma_f32_16x16x32_bf16 v[20:23], v[168:171], v[212:215], v[20:23]
	v_mfma_f32_16x16x32_bf16 v[16:19], v[176:179], v[212:215], v[16:19]
	v_mfma_f32_16x16x32_bf16 v[4:7], v[168:171], v[220:223], v[4:7]
	v_mfma_f32_16x16x32_bf16 v[0:3], v[176:179], v[220:223], v[0:3]
	s_setprio 0
	s_add_i32 s63, s63, 2
	s_add_u32 s22, s22, 0x100
	s_addc_u32 s23, s23, 0
	s_add_u32 s41, s41, 0x100
	s_addc_u32 s62, s62, 0
	s_cmp_gt_u32 s63, 13
	s_barrier
	s_cbranch_scc0 .LBB0_643
	s_and_b64 vcc, exec, s[34:35]
	s_cbranch_vccz .LBB0_646
	s_barrier

.LBB0_694:
	v_pk_mul_f32 v[6:7], v[10:11], v[6:7]
	v_pk_mul_f32 v[10:11], v[10:11], v[2:3]
	v_pk_mul_f32 v[2:3], v[120:121], v[0:1]
	s_andn2_b64 vcc, exec, s[10:11]
	s_mov_b64 s[4:5], -1
	v_pk_mul_f32 v[4:5], v[120:121], v[4:5]
	s_nop 0
	v_cvt_pk_bf16_f32 v0, v4, v5
	v_cvt_pk_bf16_f32 v1, v6, v7
	v_cvt_pk_bf16_f32 v2, v2, v3
	v_cvt_pk_bf16_f32 v3, v10, v11
	global_store_dwordx4 v[8:9], v[0:3], off offset:256
	s_cbranch_vccnz .LBB0_639
	s_andn2_b64 vcc, exec, s[26:27]
	s_cbranch_vccnz .LBB0_638
	s_mov_b32 s90, 1
	s_branch .LBB0_638

.LBB0_951:
	s_mov_b32 s90, 0
	s_or_b64 exec, exec, s[6:7]
	v_readlane_b32 s6, v254, 4
	s_mov_b64 s[4:5], s[0:1]
	s_waitcnt lgkmcnt(0)
	v_mov_b32_e32 v0, v202
	v_mov_b32_e32 v8, v202
	v_readlane_b32 s7, v254, 5
	s_barrier
	s_and_b64 vcc, exec, s[6:7]
	v_readfirstlane_b32 s8, v8
	s_cbranch_vccnz .LBB0_953
	s_lshr_b32 s6, s21, 29
	s_add_i32 s6, s2, s6
	s_and_b32 s7, s6, -8
	s_sub_i32 s7, s2, s7
	s_lshl_b32 s10, s7, 6
	s_ashr_i32 s6, s6, 3
	s_mul_i32 s9, s7, 0x41
	s_cmp_lt_i32 s7, 0
	s_cselect_b32 s7, s9, s10
	s_add_i32 s6, s7, s6
	s_ashr_i32 s7, s6, 31
	s_lshr_b32 s7, s7, 27
	s_add_i32 s7, s6, s7
	s_ashr_i32 s9, s7, 5
	s_andn2_b32 s7, s7, 31
	s_sub_i32 s6, s6, s7
	s_bfe_i32 s7, s6, 0x80000
	s_bfe_u32 s7, s7, 0x3000c
	s_add_i32 s7, s6, s7
	s_bfe_i32 s10, s7, 0x80000
	s_and_b32 s7, s7, 0xf8
	s_sub_i32 s6, s6, s7
	s_lshl_b32 s9, s9, 3
	s_sext_i32_i16 s10, s10
	s_sext_i32_i8 s6, s6
	s_add_i32 s40, s9, s6
	s_ashr_i32 s10, s10, 3

.LBB0_965:
	s_ashr_i32 s35, s34, 31
	s_lshl_b64 s[36:37], s[34:35], 19
	s_add_u32 s36, s14, s36
	s_addc_u32 s37, s15, s37
	s_and_b64 s[38:39], s[8:9], exec
	s_cselect_b32 s35, s37, s23
	s_cselect_b32 s41, s36, s22
	s_ashr_i32 s31, s30, 31
	s_lshl_b64 s[38:39], s[30:31], 19
	s_add_u32 s38, s20, s38
	s_addc_u32 s39, s44, s39
	s_and_b64 s[42:43], s[8:9], exec
	s_cselect_b32 s31, s39, s5
	s_cselect_b32 s55, s38, s4
	s_add_u32 s22, s22, 0x40080
	s_addc_u32 s23, s23, 0
	s_add_u32 s56, s4, 0x100
	v_mov_b32_e32 v0, 0
	s_addc_u32 s57, s5, 0
	s_mov_b32 s58, -2
	s_waitcnt lgkmcnt(0)
	v_mov_b32_e32 v1, v0
	v_mov_b32_e32 v2, v0
	v_mov_b32_e32 v3, v0
	v_mov_b32_e32 v4, v0
	v_mov_b32_e32 v5, v0
	v_mov_b32_e32 v6, v0
	v_mov_b32_e32 v7, v0
	v_mov_b32_e32 v16, v0
	v_mov_b32_e32 v17, v0
	v_mov_b32_e32 v18, v0
	v_mov_b32_e32 v19, v0
	v_mov_b32_e32 v20, v0
	v_mov_b32_e32 v21, v0
	v_mov_b32_e32 v22, v0
	v_mov_b32_e32 v23, v0
	v_mov_b32_e32 v32, v0
	v_mov_b32_e32 v33, v0
	v_mov_b32_e32 v34, v0
	v_mov_b32_e32 v35, v0
	v_mov_b32_e32 v36, v0
	v_mov_b32_e32 v37, v0
	v_mov_b32_e32 v38, v0
	v_mov_b32_e32 v39, v0
	v_mov_b32_e32 v48, v0
	v_mov_b32_e32 v49, v0
	v_mov_b32_e32 v50, v0
	v_mov_b32_e32 v51, v0
	v_mov_b32_e32 v52, v0
	v_mov_b32_e32 v53, v0
	v_mov_b32_e32 v54, v0
	v_mov_b32_e32 v55, v0
	v_mov_b32_e32 v8, v0
	v_mov_b32_e32 v9, v0
	v_mov_b32_e32 v10, v0
	v_mov_b32_e32 v11, v0
	v_mov_b32_e32 v12, v0
	v_mov_b32_e32 v13, v0
	v_mov_b32_e32 v14, v0
	v_mov_b32_e32 v15, v0
	v_mov_b32_e32 v24, v0
	v_mov_b32_e32 v25, v0
	v_mov_b32_e32 v26, v0
	v_mov_b32_e32 v27, v0
	v_mov_b32_e32 v28, v0
	v_mov_b32_e32 v29, v0
	v_mov_b32_e32 v30, v0
	v_mov_b32_e32 v31, v0
	v_mov_b32_e32 v40, v0
	v_mov_b32_e32 v41, v0
	v_mov_b32_e32 v42, v0
	v_mov_b32_e32 v43, v0
	v_mov_b32_e32 v44, v0
	v_mov_b32_e32 v45, v0
	v_mov_b32_e32 v46, v0
	v_mov_b32_e32 v47, v0
	v_mov_b32_e32 v56, v0
	v_mov_b32_e32 v57, v0
	v_mov_b32_e32 v58, v0
	v_mov_b32_e32 v59, v0
	v_mov_b32_e32 v60, v0
	v_mov_b32_e32 v61, v0
	v_mov_b32_e32 v62, v0
	v_mov_b32_e32 v63, v0
	v_mov_b32_e32 v64, v0
	v_mov_b32_e32 v65, v0
	v_mov_b32_e32 v66, v0
	v_mov_b32_e32 v67, v0
	v_mov_b32_e32 v68, v0
	v_mov_b32_e32 v69, v0
	v_mov_b32_e32 v70, v0
	v_mov_b32_e32 v71, v0
	v_mov_b32_e32 v80, v0
	v_mov_b32_e32 v81, v0
	v_mov_b32_e32 v82, v0
	v_mov_b32_e32 v83, v0
	v_mov_b32_e32 v84, v0
	v_mov_b32_e32 v85, v0
	v_mov_b32_e32 v86, v0
	v_mov_b32_e32 v87, v0
	v_mov_b32_e32 v96, v0
	v_mov_b32_e32 v97, v0
	v_mov_b32_e32 v98, v0
	v_mov_b32_e32 v99, v0
	v_mov_b32_e32 v100, v0
	v_mov_b32_e32 v101, v0
	v_mov_b32_e32 v102, v0
	v_mov_b32_e32 v103, v0
	v_mov_b32_e32 v112, v0
	v_mov_b32_e32 v113, v0
	v_mov_b32_e32 v114, v0
	v_mov_b32_e32 v115, v0
	v_mov_b32_e32 v116, v0
	v_mov_b32_e32 v117, v0
	v_mov_b32_e32 v118, v0
	v_mov_b32_e32 v119, v0
	v_mov_b32_e32 v72, v0
	v_mov_b32_e32 v73, v0
	v_mov_b32_e32 v74, v0
	v_mov_b32_e32 v75, v0
	v_mov_b32_e32 v76, v0
	v_mov_b32_e32 v77, v0
	v_mov_b32_e32 v78, v0
	v_mov_b32_e32 v79, v0
	v_mov_b32_e32 v88, v0
	v_mov_b32_e32 v89, v0
	v_mov_b32_e32 v90, v0
	v_mov_b32_e32 v91, v0
	v_mov_b32_e32 v92, v0
	v_mov_b32_e32 v93, v0
	v_mov_b32_e32 v94, v0
	v_mov_b32_e32 v95, v0
	v_mov_b32_e32 v104, v0
	v_mov_b32_e32 v105, v0
	v_mov_b32_e32 v106, v0
	v_mov_b32_e32 v107, v0
	v_mov_b32_e32 v108, v0
	v_mov_b32_e32 v109, v0
	v_mov_b32_e32 v110, v0
	v_mov_b32_e32 v111, v0
	v_mov_b32_e32 v120, v0
	v_mov_b32_e32 v121, v0
	v_mov_b32_e32 v122, v0
	v_mov_b32_e32 v123, v0
	v_mov_b32_e32 v124, v0
	v_mov_b32_e32 v125, v0
	v_mov_b32_e32 v126, v0
	v_mov_b32_e32 v127, v0
	s_cmp_lg_u32 s90, 0
	s_cbranch_scc0 .Lkl_nobar_5
	s_barrier
	s_mov_b32 s90, 0
.Lkl_nobar_5:
.LBB0_966:
	ds_read_b128 v[128:131], v189
	ds_read_b128 v[132:135], v189 offset:1024
	ds_read_b128 v[136:139], v189 offset:2048
	ds_read_b128 v[140:143], v189 offset:3072
	ds_read_b128 v[144:147], v190
	ds_read_b128 v[148:151], v190 offset:1024
	ds_read_b128 v[168:171], v190 offset:2048
	ds_read_b128 v[172:175], v190 offset:3072
	s_add_u32 s4, s22, 0xfffc0080
	s_addc_u32 s5, s23, -1
	s_cmp_eq_u32 s58, 12
	s_cselect_b32 s43, s35, s5
	s_cselect_b32 s42, s41, s4
	s_cselect_b32 s5, s31, s57
	s_cselect_b32 s4, s55, s56
	v_lshl_add_u64 v[184:185], s[22:23], 0, v[160:161]
	s_add_i32 m0, s46, 0xc000
	ds_read_b128 v[176:179], v191
	ds_read_b128 v[180:183], v191 offset:1024
	ds_read_b128 v[192:195], v191 offset:2048
	ds_read_b128 v[198:201], v191 offset:3072
	ds_read_b128 v[204:207], v191 offset:4096
	ds_read_b128 v[208:211], v191 offset:5120
	ds_read_b128 v[212:215], v191 offset:6144
	ds_read_b128 v[216:219], v191 offset:7168
	global_load_lds_dwordx4 v[184:185], off
	s_add_i32 m0, s46, 0xe000
	v_lshl_add_u64 v[184:185], s[22:23], 0, v[162:163]
	global_load_lds_dwordx4 v[184:185], off
	s_waitcnt vmcnt(8) lgkmcnt(0)
	s_setprio 1
	s_barrier
	v_mfma_f32_16x16x32_bf16 v[124:127], v[128:131], v[176:179], v[124:127]
	v_mfma_f32_16x16x32_bf16 v[120:123], v[136:139], v[176:179], v[120:123]
	v_mfma_f32_16x16x32_bf16 v[108:111], v[128:131], v[192:195], v[108:111]
	v_mfma_f32_16x16x32_bf16 v[104:107], v[136:139], v[192:195], v[104:107]
	v_mfma_f32_16x16x32_bf16 v[92:95], v[128:131], v[204:207], v[92:95]
	v_mfma_f32_16x16x32_bf16 v[88:91], v[136:139], v[204:207], v[88:91]
	v_mfma_f32_16x16x32_bf16 v[76:79], v[128:131], v[212:215], v[76:79]
	v_mfma_f32_16x16x32_bf16 v[72:75], v[136:139], v[212:215], v[72:75]
	v_mfma_f32_16x16x32_bf16 v[124:127], v[132:135], v[180:183], v[124:127]
	v_mfma_f32_16x16x32_bf16 v[120:123], v[140:143], v[180:183], v[120:123]
	v_mfma_f32_16x16x32_bf16 v[108:111], v[132:135], v[198:201], v[108:111]
	v_mfma_f32_16x16x32_bf16 v[104:107], v[140:143], v[198:201], v[104:107]
	v_mfma_f32_16x16x32_bf16 v[92:95], v[132:135], v[208:211], v[92:95]
	v_mfma_f32_16x16x32_bf16 v[88:91], v[140:143], v[208:211], v[88:91]
	v_mfma_f32_16x16x32_bf16 v[76:79], v[132:135], v[216:219], v[76:79]
	v_mfma_f32_16x16x32_bf16 v[72:75], v[140:143], v[216:219], v[72:75]
	s_setprio 0
	s_setprio 1
	v_mfma_f32_16x16x32_bf16 v[116:119], v[144:147], v[176:179], v[116:119]
	v_mfma_f32_16x16x32_bf16 v[112:115], v[168:171], v[176:179], v[112:115]
	v_mfma_f32_16x16x32_bf16 v[100:103], v[144:147], v[192:195], v[100:103]
	v_mfma_f32_16x16x32_bf16 v[96:99], v[168:171], v[192:195], v[96:99]
	v_mfma_f32_16x16x32_bf16 v[84:87], v[144:147], v[204:207], v[84:87]
	v_mfma_f32_16x16x32_bf16 v[80:83], v[168:171], v[204:207], v[80:83]
	v_mfma_f32_16x16x32_bf16 v[68:71], v[144:147], v[212:215], v[68:71]
	v_mfma_f32_16x16x32_bf16 v[64:67], v[168:171], v[212:215], v[64:67]
	v_mfma_f32_16x16x32_bf16 v[116:119], v[148:151], v[180:183], v[116:119]
	v_mfma_f32_16x16x32_bf16 v[112:115], v[172:175], v[180:183], v[112:115]
	v_mfma_f32_16x16x32_bf16 v[100:103], v[148:151], v[198:201], v[100:103]
	v_mfma_f32_16x16x32_bf16 v[96:99], v[172:175], v[198:201], v[96:99]
	v_mfma_f32_16x16x32_bf16 v[84:87], v[148:151], v[208:211], v[84:87]
	v_mfma_f32_16x16x32_bf16 v[80:83], v[172:175], v[208:211], v[80:83]
	v_mfma_f32_16x16x32_bf16 v[68:71], v[148:151], v[216:219], v[68:71]
	v_mfma_f32_16x16x32_bf16 v[64:67], v[172:175], v[216:219], v[64:67]
	s_setprio 0
	s_barrier
	s_add_i32 s59, s52, s45
	v_lshl_add_u64 v[184:185], s[4:5], 0, v[154:155]
	s_mov_b32 m0, s59
	ds_read_b128 v[176:179], v191 offset:16384
	ds_read_b128 v[180:183], v191 offset:17408
	ds_read_b128 v[192:195], v191 offset:18432
	ds_read_b128 v[198:201], v191 offset:19456
	ds_read_b128 v[204:207], v191 offset:20480
	ds_read_b128 v[208:211], v191 offset:21504
	ds_read_b128 v[212:215], v191 offset:22528
	ds_read_b128 v[216:219], v191 offset:23552
	global_load_lds_dwordx4 v[184:185], off
	s_add_i32 m0, s59, 0x2000
	s_add_u32 s60, s4, 0x40000
	v_lshl_add_u64 v[220:221], s[4:5], 0, v[158:159]
	s_addc_u32 s61, s5, 0
	s_add_i32 s59, s53, s45
	global_load_lds_dwordx4 v[220:221], off
	v_lshl_add_u64 v[222:223], s[60:61], 0, v[154:155]
	s_mov_b32 m0, s59
	v_lshl_add_u64 v[224:225], s[42:43], 0, v[156:157]
	global_load_lds_dwordx4 v[222:223], off
	s_add_i32 m0, s59, 0x2000
	v_lshl_add_u64 v[222:223], s[60:61], 0, v[158:159]
	global_load_lds_dwordx4 v[222:223], off
	s_mov_b32 m0, s46
	v_lshl_add_u64 v[222:223], s[42:43], 0, v[152:153]
	global_load_lds_dwordx4 v[222:223], off
	s_mov_b32 m0, s33
	s_nop 0
	global_load_lds_dwordx4 v[224:225], off
	s_waitcnt vmcnt(8) lgkmcnt(0)
	s_setprio 1
	s_barrier
	v_mfma_f32_16x16x32_bf16 v[60:63], v[128:131], v[176:179], v[60:63]
	v_mfma_f32_16x16x32_bf16 v[56:59], v[136:139], v[176:179], v[56:59]
	v_mfma_f32_16x16x32_bf16 v[44:47], v[128:131], v[192:195], v[44:47]
	v_mfma_f32_16x16x32_bf16 v[40:43], v[136:139], v[192:195], v[40:43]
	v_mfma_f32_16x16x32_bf16 v[28:31], v[128:131], v[204:207], v[28:31]
	v_mfma_f32_16x16x32_bf16 v[24:27], v[136:139], v[204:207], v[24:27]
	v_mfma_f32_16x16x32_bf16 v[12:15], v[128:131], v[212:215], v[12:15]
	v_mfma_f32_16x16x32_bf16 v[8:11], v[136:139], v[212:215], v[8:11]
	v_mfma_f32_16x16x32_bf16 v[60:63], v[132:135], v[180:183], v[60:63]
	v_mfma_f32_16x16x32_bf16 v[56:59], v[140:143], v[180:183], v[56:59]
	v_mfma_f32_16x16x32_bf16 v[44:47], v[132:135], v[198:201], v[44:47]
	v_mfma_f32_16x16x32_bf16 v[40:43], v[140:143], v[198:201], v[40:43]
	v_mfma_f32_16x16x32_bf16 v[28:31], v[132:135], v[208:211], v[28:31]
	v_mfma_f32_16x16x32_bf16 v[24:27], v[140:143], v[208:211], v[24:27]
	v_mfma_f32_16x16x32_bf16 v[12:15], v[132:135], v[216:219], v[12:15]
	v_mfma_f32_16x16x32_bf16 v[8:11], v[140:143], v[216:219], v[8:11]
	s_setprio 0
	s_setprio 1
	v_mfma_f32_16x16x32_bf16 v[52:55], v[144:147], v[176:179], v[52:55]
	v_mfma_f32_16x16x32_bf16 v[48:51], v[168:171], v[176:179], v[48:51]
	v_mfma_f32_16x16x32_bf16 v[36:39], v[144:147], v[192:195], v[36:39]
	v_mfma_f32_16x16x32_bf16 v[32:35], v[168:171], v[192:195], v[32:35]
	v_mfma_f32_16x16x32_bf16 v[20:23], v[144:147], v[204:207], v[20:23]
	v_mfma_f32_16x16x32_bf16 v[16:19], v[168:171], v[204:207], v[16:19]
	v_mfma_f32_16x16x32_bf16 v[4:7], v[144:147], v[212:215], v[4:7]
	v_mfma_f32_16x16x32_bf16 v[0:3], v[168:171], v[212:215], v[0:3]
	v_mfma_f32_16x16x32_bf16 v[52:55], v[148:151], v[180:183], v[52:55]
	v_mfma_f32_16x16x32_bf16 v[48:51], v[172:175], v[180:183], v[48:51]
	v_mfma_f32_16x16x32_bf16 v[36:39], v[148:151], v[198:201], v[36:39]
	v_mfma_f32_16x16x32_bf16 v[32:35], v[172:175], v[198:201], v[32:35]
	v_mfma_f32_16x16x32_bf16 v[20:23], v[148:151], v[208:211], v[20:23]
	v_mfma_f32_16x16x32_bf16 v[16:19], v[172:175], v[208:211], v[16:19]
	v_mfma_f32_16x16x32_bf16 v[4:7], v[148:151], v[216:219], v[4:7]
	v_mfma_f32_16x16x32_bf16 v[0:3], v[172:175], v[216:219], v[0:3]
	s_setprio 0
	s_barrier
	s_add_i32 s59, 0, 0x18000
	s_add_i32 s60, 0, 0x1c000
	v_add_u32_e32 v140, s59, v187
	v_add_u32_e32 v172, s60, v187
	ds_read_b128 v[128:131], v140
	ds_read_b128 v[132:135], v140 offset:1024
	ds_read_b128 v[136:139], v140 offset:2048
	ds_read_b128 v[140:143], v140 offset:3072
	ds_read_b128 v[144:147], v172
	ds_read_b128 v[148:151], v172 offset:1024
	ds_read_b128 v[168:171], v172 offset:2048
	ds_read_b128 v[172:175], v172 offset:3072
	s_add_u32 s42, s42, 0x40000
	s_addc_u32 s43, s43, 0
	s_mov_b32 m0, s47
	v_lshl_add_u64 v[226:227], s[42:43], 0, v[152:153]
	ds_read_b128 v[176:179], v191 offset:32768
	ds_read_b128 v[180:183], v191 offset:33792
	ds_read_b128 v[192:195], v191 offset:34816
	ds_read_b128 v[198:201], v191 offset:35840
	ds_read_b128 v[204:207], v191 offset:36864
	ds_read_b128 v[208:211], v191 offset:37888
	ds_read_b128 v[212:215], v191 offset:38912
	ds_read_b128 v[216:219], v191 offset:39936
	global_load_lds_dwordx4 v[226:227], off
	s_mov_b32 m0, s48
	v_lshl_add_u64 v[226:227], s[42:43], 0, v[156:157]
	global_load_lds_dwordx4 v[226:227], off
	s_waitcnt vmcnt(8) lgkmcnt(0)
	s_setprio 1
	s_barrier
	v_mfma_f32_16x16x32_bf16 v[124:127], v[128:131], v[176:179], v[124:127]
	v_mfma_f32_16x16x32_bf16 v[120:123], v[136:139], v[176:179], v[120:123]
	v_mfma_f32_16x16x32_bf16 v[108:111], v[128:131], v[192:195], v[108:111]
	v_mfma_f32_16x16x32_bf16 v[104:107], v[136:139], v[192:195], v[104:107]
	v_mfma_f32_16x16x32_bf16 v[92:95], v[128:131], v[204:207], v[92:95]
	v_mfma_f32_16x16x32_bf16 v[88:91], v[136:139], v[204:207], v[88:91]
	v_mfma_f32_16x16x32_bf16 v[76:79], v[128:131], v[212:215], v[76:79]
	v_mfma_f32_16x16x32_bf16 v[72:75], v[136:139], v[212:215], v[72:75]
	v_mfma_f32_16x16x32_bf16 v[124:127], v[132:135], v[180:183], v[124:127]
	v_mfma_f32_16x16x32_bf16 v[120:123], v[140:143], v[180:183], v[120:123]
	v_mfma_f32_16x16x32_bf16 v[108:111], v[132:135], v[198:201], v[108:111]
	v_mfma_f32_16x16x32_bf16 v[104:107], v[140:143], v[198:201], v[104:107]
	v_mfma_f32_16x16x32_bf16 v[92:95], v[132:135], v[208:211], v[92:95]
	v_mfma_f32_16x16x32_bf16 v[88:91], v[140:143], v[208:211], v[88:91]
	v_mfma_f32_16x16x32_bf16 v[76:79], v[132:135], v[216:219], v[76:79]
	v_mfma_f32_16x16x32_bf16 v[72:75], v[140:143], v[216:219], v[72:75]
	s_setprio 0
	s_setprio 1
	v_mfma_f32_16x16x32_bf16 v[116:119], v[144:147], v[176:179], v[116:119]
	v_mfma_f32_16x16x32_bf16 v[112:115], v[168:171], v[176:179], v[112:115]
	v_mfma_f32_16x16x32_bf16 v[100:103], v[144:147], v[192:195], v[100:103]
	v_mfma_f32_16x16x32_bf16 v[96:99], v[168:171], v[192:195], v[96:99]
	v_mfma_f32_16x16x32_bf16 v[84:87], v[144:147], v[204:207], v[84:87]
	v_mfma_f32_16x16x32_bf16 v[80:83], v[168:171], v[204:207], v[80:83]
	v_mfma_f32_16x16x32_bf16 v[68:71], v[144:147], v[212:215], v[68:71]
	v_mfma_f32_16x16x32_bf16 v[64:67], v[168:171], v[212:215], v[64:67]
	v_mfma_f32_16x16x32_bf16 v[116:119], v[148:151], v[180:183], v[116:119]
	v_mfma_f32_16x16x32_bf16 v[112:115], v[172:175], v[180:183], v[112:115]
	v_mfma_f32_16x16x32_bf16 v[100:103], v[148:151], v[198:201], v[100:103]
	v_mfma_f32_16x16x32_bf16 v[96:99], v[172:175], v[198:201], v[96:99]
	v_mfma_f32_16x16x32_bf16 v[84:87], v[148:151], v[208:211], v[84:87]
	v_mfma_f32_16x16x32_bf16 v[80:83], v[172:175], v[208:211], v[80:83]
	v_mfma_f32_16x16x32_bf16 v[68:71], v[148:151], v[216:219], v[68:71]
	v_mfma_f32_16x16x32_bf16 v[64:67], v[172:175], v[216:219], v[64:67]
	s_setprio 0
	s_barrier
	s_add_i32 s42, s59, s45
	v_lshl_add_u64 v[184:185], v[184:185], 0, s[26:27]
	s_mov_b32 m0, s42
	ds_read_b128 v[176:179], v191 offset:49152
	ds_read_b128 v[180:183], v191 offset:50176
	ds_read_b128 v[192:195], v191 offset:51200
	ds_read_b128 v[198:201], v191 offset:52224
	ds_read_b128 v[204:207], v191 offset:53248
	ds_read_b128 v[208:211], v191 offset:54272
	ds_read_b128 v[212:215], v191 offset:55296
	ds_read_b128 v[216:219], v191 offset:56320
	global_load_lds_dwordx4 v[184:185], off
	s_add_i32 m0, s42, 0x2000
	s_add_u32 s4, s4, 0x40080
	v_lshl_add_u64 v[184:185], v[220:221], 0, s[26:27]
	s_addc_u32 s5, s5, 0
	s_add_i32 s42, s60, s45
	global_load_lds_dwordx4 v[184:185], off
	s_mov_b32 m0, s42
	v_lshl_add_u64 v[184:185], s[4:5], 0, v[154:155]
	global_load_lds_dwordx4 v[184:185], off
	s_add_i32 m0, s42, 0x2000
	v_lshl_add_u64 v[184:185], s[4:5], 0, v[158:159]
	global_load_lds_dwordx4 v[184:185], off
	s_mov_b32 m0, s50
	v_lshl_add_u64 v[184:185], v[222:223], 0, s[26:27]
	global_load_lds_dwordx4 v[184:185], off
	s_mov_b32 m0, s51
	v_lshl_add_u64 v[184:185], v[224:225], 0, s[26:27]
	global_load_lds_dwordx4 v[184:185], off
	s_waitcnt vmcnt(8) lgkmcnt(0)
	s_setprio 1
	s_barrier
	v_mfma_f32_16x16x32_bf16 v[60:63], v[128:131], v[176:179], v[60:63]
	v_mfma_f32_16x16x32_bf16 v[56:59], v[136:139], v[176:179], v[56:59]
	v_mfma_f32_16x16x32_bf16 v[44:47], v[128:131], v[192:195], v[44:47]
	v_mfma_f32_16x16x32_bf16 v[40:43], v[136:139], v[192:195], v[40:43]
	v_mfma_f32_16x16x32_bf16 v[28:31], v[128:131], v[204:207], v[28:31]
	v_mfma_f32_16x16x32_bf16 v[24:27], v[136:139], v[204:207], v[24:27]
	v_mfma_f32_16x16x32_bf16 v[12:15], v[128:131], v[212:215], v[12:15]
	v_mfma_f32_16x16x32_bf16 v[8:11], v[136:139], v[212:215], v[8:11]
	v_mfma_f32_16x16x32_bf16 v[60:63], v[132:135], v[180:183], v[60:63]
	v_mfma_f32_16x16x32_bf16 v[56:59], v[140:143], v[180:183], v[56:59]
	v_mfma_f32_16x16x32_bf16 v[44:47], v[132:135], v[198:201], v[44:47]
	v_mfma_f32_16x16x32_bf16 v[40:43], v[140:143], v[198:201], v[40:43]
	v_mfma_f32_16x16x32_bf16 v[28:31], v[132:135], v[208:211], v[28:31]
	v_mfma_f32_16x16x32_bf16 v[24:27], v[140:143], v[208:211], v[24:27]
	v_mfma_f32_16x16x32_bf16 v[12:15], v[132:135], v[216:219], v[12:15]
	v_mfma_f32_16x16x32_bf16 v[8:11], v[140:143], v[216:219], v[8:11]
	s_setprio 0
	s_setprio 1
	v_mfma_f32_16x16x32_bf16 v[52:55], v[144:147], v[176:179], v[52:55]
	v_mfma_f32_16x16x32_bf16 v[48:51], v[168:171], v[176:179], v[48:51]
	v_mfma_f32_16x16x32_bf16 v[36:39], v[144:147], v[192:195], v[36:39]
	v_mfma_f32_16x16x32_bf16 v[32:35], v[168:171], v[192:195], v[32:35]
	v_mfma_f32_16x16x32_bf16 v[20:23], v[144:147], v[204:207], v[20:23]
	v_mfma_f32_16x16x32_bf16 v[16:19], v[168:171], v[204:207], v[16:19]
	v_mfma_f32_16x16x32_bf16 v[4:7], v[144:147], v[212:215], v[4:7]
	v_mfma_f32_16x16x32_bf16 v[0:3], v[168:171], v[212:215], v[0:3]
	v_mfma_f32_16x16x32_bf16 v[52:55], v[148:151], v[180:183], v[52:55]
	v_mfma_f32_16x16x32_bf16 v[48:51], v[172:175], v[180:183], v[48:51]
	v_mfma_f32_16x16x32_bf16 v[36:39], v[148:151], v[198:201], v[36:39]
	v_mfma_f32_16x16x32_bf16 v[32:35], v[172:175], v[198:201], v[32:35]
	v_mfma_f32_16x16x32_bf16 v[20:23], v[148:151], v[208:211], v[20:23]
	v_mfma_f32_16x16x32_bf16 v[16:19], v[172:175], v[208:211], v[16:19]
	v_mfma_f32_16x16x32_bf16 v[4:7], v[148:151], v[216:219], v[4:7]
	v_mfma_f32_16x16x32_bf16 v[0:3], v[172:175], v[216:219], v[0:3]
	s_setprio 0
	s_add_i32 s58, s58, 2
	s_add_u32 s22, s22, 0x100
	s_addc_u32 s23, s23, 0
	s_add_u32 s56, s56, 0x100
	s_addc_u32 s57, s57, 0
	s_cmp_gt_u32 s58, 13
	s_barrier
	s_cbranch_scc0 .LBB0_966
	s_and_b64 vcc, exec, s[28:29]
	s_cbranch_vccz .LBB0_969
	s_barrier

.LBB0_1039:
	s_mov_b32 s90, 0
	s_mov_b32 s62, -1
	s_or_b64 exec, exec, s[6:7]
	v_readlane_b32 s6, v254, 6
	s_mov_b64 s[4:5], s[0:1]
	s_waitcnt lgkmcnt(0)
	v_mov_b32_e32 v0, v202
	v_mov_b32_e32 v8, v202
	v_readlane_b32 s7, v254, 7
	s_barrier
	s_andn2_b64 vcc, exec, s[6:7]
	v_readfirstlane_b32 s13, v8
	s_cbranch_vccnz .LBB0_1055
	v_lshlrev_b32_e32 v0, 4, v8
	v_add_u32_e32 v1, 0x2000, v0
	v_ashrrev_i32_e32 v2, 31, v1
	v_lshrrev_b32_e32 v2, 22, v2
	v_add_u32_e32 v2, v1, v2
	v_ashrrev_i32_e32 v9, 10, v2
	v_mul_i32_i24_e32 v2, 0x400, v9
	v_sub_u32_e32 v1, v1, v2
	v_lshrrev_b32_e32 v2, 4, v1
	v_bitop3_b32 v1, v2, v1, 32 bitop3:0x6c
	v_ashrrev_i32_e32 v2, 31, v1
	v_lshrrev_b32_e32 v2, 26, v2
	v_add_u32_e32 v2, v1, v2
	v_lshlrev_b32_e32 v3, 3, v9
	v_ashrrev_i32_e32 v10, 6, v2
	v_and_b32_e32 v3, -16, v3
	v_add_u32_e32 v3, v10, v3
	s_load_dwordx2 s[6:7], s[4:5], 0xa0
	v_and_b32_e32 v4, 3, v10
	s_mov_b32 s4, 0x1fffe0
	v_lshrrev_b32_e32 v5, 2, v3
	v_lshlrev_b32_e32 v6, 1, v3
	v_and_b32_e32 v2, 0xc0, v2
	v_and_or_b32 v4, v3, s4, v4
	v_and_b32_e32 v5, 4, v5
	v_and_b32_e32 v6, 24, v6
	v_sub_u32_e32 v1, v1, v2
	v_mov_b32_e32 v2, 1
	v_or3_b32 v4, v4, v5, v6
	v_lshlrev_b32_e32 v5, 5, v9
	v_ashrrev_i16_sdwa v1, v2, sext(v1) dst_sel:DWORD dst_unused:UNUSED_PAD src0_sel:DWORD src1_sel:BYTE_0
	v_and_b32_e32 v5, 32, v5
	v_bfe_i32 v11, v1, 0, 16
	v_add_lshl_u32 v1, v5, v11, 1
	v_lshl_add_u32 v128, v4, 11, v1
	v_lshl_add_u32 v130, v3, 11, v1
	v_bfe_i32 v1, v8, 27, 1
	v_lshrrev_b32_e32 v1, 22, v1
	v_add_u32_e32 v1, v0, v1
	v_and_b32_e32 v1, 0xfffffc00, v1
	v_sub_u32_e32 v0, v0, v1
	v_lshrrev_b32_e32 v1, 4, v0
	v_ashrrev_i32_e32 v3, 31, v8
	v_bitop3_b32 v0, v1, v0, 32 bitop3:0x6c
	v_lshrrev_b32_e32 v3, 26, v3
	v_ashrrev_i32_e32 v1, 31, v0
	v_add_u32_e32 v3, v8, v3
	v_lshrrev_b32_e32 v1, 26, v1
	v_ashrrev_i32_e32 v13, 6, v3
	s_waitcnt lgkmcnt(0)
	s_add_u32 s14, s6, 0x4800000
	v_add_u32_e32 v1, v0, v1
	v_lshlrev_b32_e32 v3, 3, v13
	s_addc_u32 s15, s7, 0
	v_ashrrev_i32_e32 v12, 6, v1
	v_and_b32_e32 v3, -16, v3
	s_add_u32 s20, s6, 0x3080000
	v_add_u32_e32 v3, v12, v3
	v_and_b32_e32 v4, 3, v12
	s_addc_u32 s38, s7, 0
	v_and_or_b32 v4, v3, s4, v4
	s_lshr_b32 s4, s21, 29
	s_add_i32 s4, s2, s4
	s_ashr_i32 s24, s13, 6
	s_ashr_i32 s5, s4, 3
	s_and_b32 s4, s4, -8
	s_ashr_i32 s26, s13, 8
	s_lshl_b32 s39, s24, 10
	s_sub_i32 s4, s2, s4
	s_cmp_lt_i32 s4, 0
	s_movk_i32 s40, 0x161
	s_cselect_b32 s8, s40, 0x160
	s_mul_i32 s4, s4, s8
	s_add_i32 s4, s4, s5
	s_mul_hi_i32 s5, s4, 0x2e8ba2e9
	s_lshr_b32 s8, s5, 31
	s_ashr_i32 s5, s5, 5
	s_add_i32 s5, s5, s8
	s_lshl_b32 s8, s5, 3
	s_mulk_i32 s5, 0xb0
	s_sub_i32 s4, s4, s5
	s_sext_i32_i16 s5, s4
	s_bfe_u32 s5, s5, 0x3001c
	s_add_i32 s5, s4, s5
	s_sext_i32_i16 s9, s5
	s_and_b32 s5, s5, 0xfff8
	s_sub_i32 s4, s4, s5
	s_sext_i32_i16 s4, s4
	v_lshrrev_b32_e32 v5, 2, v3
	v_lshlrev_b32_e32 v6, 1, v3
	v_and_b32_e32 v1, 0xc0, v1
	s_lshr_b32 s12, s9, 3
	s_add_i32 s8, s8, s4
	v_and_b32_e32 v5, 4, v5
	v_and_b32_e32 v6, 24, v6
	v_sub_u32_e32 v0, v0, v1
	s_ashr_i32 s9, s8, 31
	s_bfe_i64 s[4:5], s[12:13], 0x100000
	v_or3_b32 v4, v4, v5, v6
	v_lshlrev_b32_e32 v5, 5, v13
	v_ashrrev_i16_sdwa v0, v2, sext(v0) dst_sel:DWORD dst_unused:UNUSED_PAD src0_sel:DWORD src1_sel:BYTE_0
	s_lshl_b64 s[10:11], s[8:9], 19
	s_lshl_b64 s[4:5], s[4:5], 19
	v_and_b32_e32 v5, 32, v5
	v_bfe_i32 v14, v0, 0, 16
	s_add_u32 s4, s20, s4
	v_add_lshl_u32 v0, v5, v14, 1
	s_addc_u32 s5, s38, s5
	s_add_i32 s41, s39, 0
	v_lshl_add_u32 v132, v4, 11, v0
	s_add_i32 m0, s41, 0x10000
	v_lshl_add_u32 v134, v3, 11, v0
	global_load_lds_dwordx4 v132, s[4:5]
	s_add_i32 m0, s41, 0x12000
	s_add_u32 s16, s4, 0x40000
	global_load_lds_dwordx4 v128, s[4:5]
	s_addc_u32 s17, s5, 0
	s_add_i32 m0, s41, 0x14000
	v_mov_b32_e32 v133, 0
	global_load_lds_dwordx4 v132, s[16:17]
	s_add_i32 m0, s41, 0x16000
	s_add_u32 s10, s14, s10
	s_addc_u32 s11, s15, s11
	s_add_i32 s42, s41, 0x2000
	global_load_lds_dwordx4 v128, s[16:17]
	s_mov_b32 m0, s41
	s_add_u32 s16, s10, 0x40000
	global_load_lds_dwordx4 v134, s[10:11]
	s_mov_b32 m0, s42
	s_addc_u32 s17, s11, 0
	s_add_i32 s43, s41, 0x4000
	global_load_lds_dwordx4 v130, s[10:11]
	s_mov_b32 m0, s43
	s_add_i32 s44, s41, 0x6000
	global_load_lds_dwordx4 v134, s[16:17]
	s_mov_b32 m0, s44
	v_mov_b32_e32 v129, v133
	global_load_lds_dwordx4 v130, s[16:17]
	v_mov_b32_e32 v135, v133
	v_mov_b32_e32 v131, v133
	s_cmp_eq_u32 s26, 1
	s_mov_b32 s45, 0
	v_lshl_add_u64 v[6:7], s[4:5], 0, v[132:133]
	v_lshl_add_u64 v[4:5], s[4:5], 0, v[128:129]
	v_lshl_add_u64 v[0:1], s[10:11], 0, v[134:135]
	s_cselect_b64 s[16:17], -1, 0
	s_cmp_lg_u32 s26, 1
	v_lshl_add_u64 v[2:3], s[10:11], 0, v[130:131]
	s_cbranch_scc1 .LBB0_1042
	s_barrier

.LBB0_1047:
	s_ashr_i32 s31, s30, 31
	s_lshl_b64 s[12:13], s[30:31], 19
	s_add_u32 s34, s14, s12
	s_addc_u32 s35, s15, s13
	s_and_b64 s[12:13], s[6:7], exec
	s_cselect_b32 s9, s35, s11
	s_cselect_b32 s31, s34, s10
	s_ashr_i32 s29, s28, 31
	s_lshl_b64 s[12:13], s[28:29], 19
	s_add_u32 s36, s20, s12
	s_addc_u32 s37, s38, s13
	s_and_b64 s[12:13], s[6:7], exec
	s_cselect_b32 s29, s37, s5
	s_cselect_b32 s52, s36, s4
	s_add_u32 s10, s10, 0x40080
	s_addc_u32 s11, s11, 0
	s_add_u32 s53, s4, 0x100
	v_mov_b32_e32 v0, 0
	s_addc_u32 s54, s5, 0
	s_mov_b32 s55, -2
	v_mov_b32_e32 v1, v0
	v_mov_b32_e32 v2, v0
	v_mov_b32_e32 v3, v0
	v_mov_b32_e32 v8, v0
	v_mov_b32_e32 v9, v0
	v_mov_b32_e32 v10, v0
	v_mov_b32_e32 v11, v0
	v_mov_b32_e32 v16, v0
	v_mov_b32_e32 v17, v0
	v_mov_b32_e32 v18, v0
	v_mov_b32_e32 v19, v0
	v_mov_b32_e32 v24, v0
	v_mov_b32_e32 v25, v0
	v_mov_b32_e32 v26, v0
	v_mov_b32_e32 v27, v0
	v_mov_b32_e32 v32, v0
	v_mov_b32_e32 v33, v0
	v_mov_b32_e32 v34, v0
	v_mov_b32_e32 v35, v0
	v_mov_b32_e32 v40, v0
	v_mov_b32_e32 v41, v0
	v_mov_b32_e32 v42, v0
	v_mov_b32_e32 v43, v0
	v_mov_b32_e32 v48, v0
	v_mov_b32_e32 v49, v0
	v_mov_b32_e32 v50, v0
	v_mov_b32_e32 v51, v0
	v_mov_b32_e32 v56, v0
	v_mov_b32_e32 v57, v0
	v_mov_b32_e32 v58, v0
	v_mov_b32_e32 v59, v0
	v_mov_b32_e32 v4, v0
	v_mov_b32_e32 v5, v0
	v_mov_b32_e32 v6, v0
	v_mov_b32_e32 v7, v0
	v_mov_b32_e32 v12, v0
	v_mov_b32_e32 v13, v0
	v_mov_b32_e32 v14, v0
	v_mov_b32_e32 v15, v0
	v_mov_b32_e32 v20, v0
	v_mov_b32_e32 v21, v0
	v_mov_b32_e32 v22, v0
	v_mov_b32_e32 v23, v0
	v_mov_b32_e32 v28, v0
	v_mov_b32_e32 v29, v0
	v_mov_b32_e32 v30, v0
	v_mov_b32_e32 v31, v0
	v_mov_b32_e32 v36, v0
	v_mov_b32_e32 v37, v0
	v_mov_b32_e32 v38, v0
	v_mov_b32_e32 v39, v0
	v_mov_b32_e32 v44, v0
	v_mov_b32_e32 v45, v0
	v_mov_b32_e32 v46, v0
	v_mov_b32_e32 v47, v0
	v_mov_b32_e32 v52, v0
	v_mov_b32_e32 v53, v0
	v_mov_b32_e32 v54, v0
	v_mov_b32_e32 v55, v0
	v_mov_b32_e32 v60, v0
	v_mov_b32_e32 v61, v0
	v_mov_b32_e32 v62, v0
	v_mov_b32_e32 v63, v0
	v_mov_b32_e32 v64, v0
	v_mov_b32_e32 v65, v0
	v_mov_b32_e32 v66, v0
	v_mov_b32_e32 v67, v0
	v_mov_b32_e32 v72, v0
	v_mov_b32_e32 v73, v0
	v_mov_b32_e32 v74, v0
	v_mov_b32_e32 v75, v0
	v_mov_b32_e32 v80, v0
	v_mov_b32_e32 v81, v0
	v_mov_b32_e32 v82, v0
	v_mov_b32_e32 v83, v0
	v_mov_b32_e32 v88, v0
	v_mov_b32_e32 v89, v0
	v_mov_b32_e32 v90, v0
	v_mov_b32_e32 v91, v0
	v_mov_b32_e32 v96, v0
	v_mov_b32_e32 v97, v0
	v_mov_b32_e32 v98, v0
	v_mov_b32_e32 v99, v0
	v_mov_b32_e32 v104, v0
	v_mov_b32_e32 v105, v0
	v_mov_b32_e32 v106, v0
	v_mov_b32_e32 v107, v0
	v_mov_b32_e32 v112, v0
	v_mov_b32_e32 v113, v0
	v_mov_b32_e32 v114, v0
	v_mov_b32_e32 v115, v0
	v_mov_b32_e32 v120, v0
	v_mov_b32_e32 v121, v0
	v_mov_b32_e32 v122, v0
	v_mov_b32_e32 v123, v0
	v_mov_b32_e32 v68, v0
	v_mov_b32_e32 v69, v0
	v_mov_b32_e32 v70, v0
	v_mov_b32_e32 v71, v0
	v_mov_b32_e32 v76, v0
	v_mov_b32_e32 v77, v0
	v_mov_b32_e32 v78, v0
	v_mov_b32_e32 v79, v0
	v_mov_b32_e32 v84, v0
	v_mov_b32_e32 v85, v0
	v_mov_b32_e32 v86, v0
	v_mov_b32_e32 v87, v0
	v_mov_b32_e32 v92, v0
	v_mov_b32_e32 v93, v0
	v_mov_b32_e32 v94, v0
	v_mov_b32_e32 v95, v0
	v_mov_b32_e32 v100, v0
	v_mov_b32_e32 v101, v0
	v_mov_b32_e32 v102, v0
	v_mov_b32_e32 v103, v0
	v_mov_b32_e32 v108, v0
	v_mov_b32_e32 v109, v0
	v_mov_b32_e32 v110, v0
	v_mov_b32_e32 v111, v0
	v_mov_b32_e32 v116, v0
	v_mov_b32_e32 v117, v0
	v_mov_b32_e32 v118, v0
	v_mov_b32_e32 v119, v0
	v_mov_b32_e32 v124, v0
	v_mov_b32_e32 v125, v0
	v_mov_b32_e32 v126, v0
	v_mov_b32_e32 v127, v0
	s_cmp_lg_u32 s90, 0
	s_cbranch_scc0 .Lkl_nobar_6
	s_barrier
	s_mov_b32 s90, 0
.Lkl_nobar_6:
.LBB0_1048:
	ds_read_b128 v[146:149], v169
	ds_read_b128 v[150:153], v169 offset:1024
	ds_read_b128 v[154:157], v169 offset:2048
	ds_read_b128 v[160:163], v169 offset:3072
	ds_read_b128 v[178:181], v171
	ds_read_b128 v[182:185], v171 offset:1024
	ds_read_b128 v[186:189], v171 offset:2048
	ds_read_b128 v[190:193], v171 offset:3072
	s_add_u32 s4, s10, 0xfffc0080
	s_addc_u32 s5, s11, -1
	s_cmp_eq_u32 s55, 12
	s_cselect_b32 s13, s9, s5
	s_cselect_b32 s12, s31, s4
	s_cselect_b32 s5, s29, s54
	s_cselect_b32 s4, s52, s53
	v_lshl_add_u64 v[194:195], s[10:11], 0, v[138:139]
	s_add_i32 m0, s41, 0xc000
	ds_read_b128 v[198:201], v173
	ds_read_b128 v[204:207], v173 offset:1024
	ds_read_b128 v[208:211], v173 offset:2048
	ds_read_b128 v[212:215], v173 offset:3072
	ds_read_b128 v[216:219], v173 offset:4096
	ds_read_b128 v[220:223], v173 offset:5120
	ds_read_b128 v[224:227], v173 offset:6144
	ds_read_b128 v[228:231], v173 offset:7168
	global_load_lds_dwordx4 v[194:195], off
	s_add_i32 m0, s41, 0xe000
	v_lshl_add_u64 v[194:195], s[10:11], 0, v[140:141]
	global_load_lds_dwordx4 v[194:195], off
	s_waitcnt vmcnt(8) lgkmcnt(0)
	s_setprio 1
	s_barrier
	v_mfma_f32_16x16x32_bf16 v[124:127], v[146:149], v[198:201], v[124:127]
	v_mfma_f32_16x16x32_bf16 v[116:119], v[154:157], v[198:201], v[116:119]
	v_mfma_f32_16x16x32_bf16 v[108:111], v[146:149], v[208:211], v[108:111]
	v_mfma_f32_16x16x32_bf16 v[100:103], v[154:157], v[208:211], v[100:103]
	v_mfma_f32_16x16x32_bf16 v[92:95], v[146:149], v[216:219], v[92:95]
	v_mfma_f32_16x16x32_bf16 v[84:87], v[154:157], v[216:219], v[84:87]
	v_mfma_f32_16x16x32_bf16 v[76:79], v[146:149], v[224:227], v[76:79]
	v_mfma_f32_16x16x32_bf16 v[68:71], v[154:157], v[224:227], v[68:71]
	v_mfma_f32_16x16x32_bf16 v[124:127], v[150:153], v[204:207], v[124:127]
	v_mfma_f32_16x16x32_bf16 v[116:119], v[160:163], v[204:207], v[116:119]
	v_mfma_f32_16x16x32_bf16 v[108:111], v[150:153], v[212:215], v[108:111]
	v_mfma_f32_16x16x32_bf16 v[100:103], v[160:163], v[212:215], v[100:103]
	v_mfma_f32_16x16x32_bf16 v[92:95], v[150:153], v[220:223], v[92:95]
	v_mfma_f32_16x16x32_bf16 v[84:87], v[160:163], v[220:223], v[84:87]
	v_mfma_f32_16x16x32_bf16 v[76:79], v[150:153], v[228:231], v[76:79]
	v_mfma_f32_16x16x32_bf16 v[68:71], v[160:163], v[228:231], v[68:71]
	s_setprio 0
	s_setprio 1
	v_mfma_f32_16x16x32_bf16 v[120:123], v[178:181], v[198:201], v[120:123]
	v_mfma_f32_16x16x32_bf16 v[112:115], v[186:189], v[198:201], v[112:115]
	v_mfma_f32_16x16x32_bf16 v[104:107], v[178:181], v[208:211], v[104:107]
	v_mfma_f32_16x16x32_bf16 v[96:99], v[186:189], v[208:211], v[96:99]
	v_mfma_f32_16x16x32_bf16 v[88:91], v[178:181], v[216:219], v[88:91]
	v_mfma_f32_16x16x32_bf16 v[80:83], v[186:189], v[216:219], v[80:83]
	v_mfma_f32_16x16x32_bf16 v[72:75], v[178:181], v[224:227], v[72:75]
	v_mfma_f32_16x16x32_bf16 v[64:67], v[186:189], v[224:227], v[64:67]
	v_mfma_f32_16x16x32_bf16 v[120:123], v[182:185], v[204:207], v[120:123]
	v_mfma_f32_16x16x32_bf16 v[112:115], v[190:193], v[204:207], v[112:115]
	v_mfma_f32_16x16x32_bf16 v[104:107], v[182:185], v[212:215], v[104:107]
	v_mfma_f32_16x16x32_bf16 v[96:99], v[190:193], v[212:215], v[96:99]
	v_mfma_f32_16x16x32_bf16 v[88:91], v[182:185], v[220:223], v[88:91]
	v_mfma_f32_16x16x32_bf16 v[80:83], v[190:193], v[220:223], v[80:83]
	v_mfma_f32_16x16x32_bf16 v[72:75], v[182:185], v[228:231], v[72:75]
	v_mfma_f32_16x16x32_bf16 v[64:67], v[190:193], v[228:231], v[64:67]
	s_setprio 0
	s_barrier
	s_add_i32 s56, s48, s39
	v_lshl_add_u64 v[194:195], s[4:5], 0, v[132:133]
	s_mov_b32 m0, s56
	ds_read_b128 v[198:201], v173 offset:16384
	ds_read_b128 v[204:207], v173 offset:17408
	ds_read_b128 v[208:211], v173 offset:18432
	ds_read_b128 v[212:215], v173 offset:19456
	ds_read_b128 v[216:219], v173 offset:20480
	ds_read_b128 v[220:223], v173 offset:21504
	ds_read_b128 v[224:227], v173 offset:22528
	ds_read_b128 v[228:231], v173 offset:23552
	global_load_lds_dwordx4 v[194:195], off
	s_add_i32 m0, s56, 0x2000
	s_add_u32 s56, s4, 0x40000
	v_lshl_add_u64 v[232:233], s[4:5], 0, v[128:129]
	s_addc_u32 s57, s5, 0
	s_add_i32 s58, s49, s39
	global_load_lds_dwordx4 v[232:233], off
	v_lshl_add_u64 v[234:235], s[56:57], 0, v[132:133]
	s_mov_b32 m0, s58
	v_lshl_add_u64 v[236:237], s[12:13], 0, v[130:131]
	global_load_lds_dwordx4 v[234:235], off
	s_add_i32 m0, s58, 0x2000
	v_lshl_add_u64 v[234:235], s[56:57], 0, v[128:129]
	global_load_lds_dwordx4 v[234:235], off
	s_mov_b32 m0, s41
	v_lshl_add_u64 v[234:235], s[12:13], 0, v[134:135]
	global_load_lds_dwordx4 v[234:235], off
	s_mov_b32 m0, s42
	s_nop 0
	global_load_lds_dwordx4 v[236:237], off
	s_waitcnt vmcnt(8) lgkmcnt(0)
	s_setprio 1
	s_barrier
	v_mfma_f32_16x16x32_bf16 v[60:63], v[146:149], v[198:201], v[60:63]
	v_mfma_f32_16x16x32_bf16 v[52:55], v[154:157], v[198:201], v[52:55]
	v_mfma_f32_16x16x32_bf16 v[44:47], v[146:149], v[208:211], v[44:47]
	v_mfma_f32_16x16x32_bf16 v[36:39], v[154:157], v[208:211], v[36:39]
	v_mfma_f32_16x16x32_bf16 v[28:31], v[146:149], v[216:219], v[28:31]
	v_mfma_f32_16x16x32_bf16 v[20:23], v[154:157], v[216:219], v[20:23]
	v_mfma_f32_16x16x32_bf16 v[12:15], v[146:149], v[224:227], v[12:15]
	v_mfma_f32_16x16x32_bf16 v[4:7], v[154:157], v[224:227], v[4:7]
	v_mfma_f32_16x16x32_bf16 v[60:63], v[150:153], v[204:207], v[60:63]
	v_mfma_f32_16x16x32_bf16 v[52:55], v[160:163], v[204:207], v[52:55]
	v_mfma_f32_16x16x32_bf16 v[44:47], v[150:153], v[212:215], v[44:47]
	v_mfma_f32_16x16x32_bf16 v[36:39], v[160:163], v[212:215], v[36:39]
	v_mfma_f32_16x16x32_bf16 v[28:31], v[150:153], v[220:223], v[28:31]
	v_mfma_f32_16x16x32_bf16 v[20:23], v[160:163], v[220:223], v[20:23]
	v_mfma_f32_16x16x32_bf16 v[12:15], v[150:153], v[228:231], v[12:15]
	v_mfma_f32_16x16x32_bf16 v[4:7], v[160:163], v[228:231], v[4:7]
	s_setprio 0
	s_setprio 1
	v_mfma_f32_16x16x32_bf16 v[56:59], v[178:181], v[198:201], v[56:59]
	v_mfma_f32_16x16x32_bf16 v[48:51], v[186:189], v[198:201], v[48:51]
	v_mfma_f32_16x16x32_bf16 v[40:43], v[178:181], v[208:211], v[40:43]
	v_mfma_f32_16x16x32_bf16 v[32:35], v[186:189], v[208:211], v[32:35]
	v_mfma_f32_16x16x32_bf16 v[24:27], v[178:181], v[216:219], v[24:27]
	v_mfma_f32_16x16x32_bf16 v[16:19], v[186:189], v[216:219], v[16:19]
	v_mfma_f32_16x16x32_bf16 v[8:11], v[178:181], v[224:227], v[8:11]
	v_mfma_f32_16x16x32_bf16 v[0:3], v[186:189], v[224:227], v[0:3]
	v_mfma_f32_16x16x32_bf16 v[56:59], v[182:185], v[204:207], v[56:59]
	v_mfma_f32_16x16x32_bf16 v[48:51], v[190:193], v[204:207], v[48:51]
	v_mfma_f32_16x16x32_bf16 v[40:43], v[182:185], v[212:215], v[40:43]
	v_mfma_f32_16x16x32_bf16 v[32:35], v[190:193], v[212:215], v[32:35]
	v_mfma_f32_16x16x32_bf16 v[24:27], v[182:185], v[220:223], v[24:27]
	v_mfma_f32_16x16x32_bf16 v[16:19], v[190:193], v[220:223], v[16:19]
	v_mfma_f32_16x16x32_bf16 v[8:11], v[182:185], v[228:231], v[8:11]
	v_mfma_f32_16x16x32_bf16 v[0:3], v[190:193], v[228:231], v[0:3]
	s_setprio 0
	s_barrier
	s_add_i32 s56, 0, 0x18000
	v_add_u32_e32 v158, s56, v165
	s_add_i32 s57, 0, 0x1c000
	ds_read_b128 v[146:149], v158
	ds_read_b128 v[150:153], v158 offset:1024
	ds_read_b128 v[154:157], v158 offset:2048
	ds_read_b128 v[160:163], v158 offset:3072
	v_add_u32_e32 v158, s57, v165
	ds_read_b128 v[178:181], v158
	ds_read_b128 v[182:185], v158 offset:1024
	ds_read_b128 v[186:189], v158 offset:2048
	ds_read_b128 v[190:193], v158 offset:3072
	s_add_u32 s12, s12, 0x40000
	s_addc_u32 s13, s13, 0
	s_mov_b32 m0, s43
	v_lshl_add_u64 v[238:239], s[12:13], 0, v[134:135]
	ds_read_b128 v[198:201], v173 offset:32768
	ds_read_b128 v[204:207], v173 offset:33792
	ds_read_b128 v[208:211], v173 offset:34816
	ds_read_b128 v[212:215], v173 offset:35840
	ds_read_b128 v[216:219], v173 offset:36864
	ds_read_b128 v[220:223], v173 offset:37888
	ds_read_b128 v[224:227], v173 offset:38912
	ds_read_b128 v[228:231], v173 offset:39936
	global_load_lds_dwordx4 v[238:239], off
	s_mov_b32 m0, s44
	v_lshl_add_u64 v[238:239], s[12:13], 0, v[130:131]
	global_load_lds_dwordx4 v[238:239], off
	s_waitcnt vmcnt(8) lgkmcnt(0)
	s_setprio 1
	s_barrier
	v_mfma_f32_16x16x32_bf16 v[124:127], v[146:149], v[198:201], v[124:127]
	v_mfma_f32_16x16x32_bf16 v[116:119], v[154:157], v[198:201], v[116:119]
	v_mfma_f32_16x16x32_bf16 v[108:111], v[146:149], v[208:211], v[108:111]
	v_mfma_f32_16x16x32_bf16 v[100:103], v[154:157], v[208:211], v[100:103]
	v_mfma_f32_16x16x32_bf16 v[92:95], v[146:149], v[216:219], v[92:95]
	v_mfma_f32_16x16x32_bf16 v[84:87], v[154:157], v[216:219], v[84:87]
	v_mfma_f32_16x16x32_bf16 v[76:79], v[146:149], v[224:227], v[76:79]
	v_mfma_f32_16x16x32_bf16 v[68:71], v[154:157], v[224:227], v[68:71]
	v_mfma_f32_16x16x32_bf16 v[124:127], v[150:153], v[204:207], v[124:127]
	v_mfma_f32_16x16x32_bf16 v[116:119], v[160:163], v[204:207], v[116:119]
	v_mfma_f32_16x16x32_bf16 v[108:111], v[150:153], v[212:215], v[108:111]
	v_mfma_f32_16x16x32_bf16 v[100:103], v[160:163], v[212:215], v[100:103]
	v_mfma_f32_16x16x32_bf16 v[92:95], v[150:153], v[220:223], v[92:95]
	v_mfma_f32_16x16x32_bf16 v[84:87], v[160:163], v[220:223], v[84:87]
	v_mfma_f32_16x16x32_bf16 v[76:79], v[150:153], v[228:231], v[76:79]
	v_mfma_f32_16x16x32_bf16 v[68:71], v[160:163], v[228:231], v[68:71]
	s_setprio 0
	s_setprio 1
	v_mfma_f32_16x16x32_bf16 v[120:123], v[178:181], v[198:201], v[120:123]
	v_mfma_f32_16x16x32_bf16 v[112:115], v[186:189], v[198:201], v[112:115]
	v_mfma_f32_16x16x32_bf16 v[104:107], v[178:181], v[208:211], v[104:107]
	v_mfma_f32_16x16x32_bf16 v[96:99], v[186:189], v[208:211], v[96:99]
	v_mfma_f32_16x16x32_bf16 v[88:91], v[178:181], v[216:219], v[88:91]
	v_mfma_f32_16x16x32_bf16 v[80:83], v[186:189], v[216:219], v[80:83]
	v_mfma_f32_16x16x32_bf16 v[72:75], v[178:181], v[224:227], v[72:75]
	v_mfma_f32_16x16x32_bf16 v[64:67], v[186:189], v[224:227], v[64:67]
	v_mfma_f32_16x16x32_bf16 v[120:123], v[182:185], v[204:207], v[120:123]
	v_mfma_f32_16x16x32_bf16 v[112:115], v[190:193], v[204:207], v[112:115]
	v_mfma_f32_16x16x32_bf16 v[104:107], v[182:185], v[212:215], v[104:107]
	v_mfma_f32_16x16x32_bf16 v[96:99], v[190:193], v[212:215], v[96:99]
	v_mfma_f32_16x16x32_bf16 v[88:91], v[182:185], v[220:223], v[88:91]
	v_mfma_f32_16x16x32_bf16 v[80:83], v[190:193], v[220:223], v[80:83]
	v_mfma_f32_16x16x32_bf16 v[72:75], v[182:185], v[228:231], v[72:75]
	v_mfma_f32_16x16x32_bf16 v[64:67], v[190:193], v[228:231], v[64:67]
	s_setprio 0
	s_barrier
	s_add_i32 s12, s56, s39
	v_lshl_add_u64 v[194:195], v[194:195], 0, s[24:25]
	s_mov_b32 m0, s12
	ds_read_b128 v[198:201], v173 offset:49152
	ds_read_b128 v[204:207], v173 offset:50176
	ds_read_b128 v[208:211], v173 offset:51200
	ds_read_b128 v[212:215], v173 offset:52224
	ds_read_b128 v[216:219], v173 offset:53248
	ds_read_b128 v[220:223], v173 offset:54272
	ds_read_b128 v[224:227], v173 offset:55296
	ds_read_b128 v[228:231], v173 offset:56320
	global_load_lds_dwordx4 v[194:195], off
	s_add_i32 m0, s12, 0x2000
	s_add_u32 s4, s4, 0x40080
	v_lshl_add_u64 v[194:195], v[232:233], 0, s[24:25]
	s_addc_u32 s5, s5, 0
	s_add_i32 s12, s57, s39
	global_load_lds_dwordx4 v[194:195], off
	s_mov_b32 m0, s12
	v_lshl_add_u64 v[194:195], s[4:5], 0, v[132:133]
	global_load_lds_dwordx4 v[194:195], off
	s_add_i32 m0, s12, 0x2000
	v_lshl_add_u64 v[194:195], s[4:5], 0, v[128:129]
	global_load_lds_dwordx4 v[194:195], off
	s_mov_b32 m0, s46
	v_lshl_add_u64 v[194:195], v[234:235], 0, s[24:25]
	global_load_lds_dwordx4 v[194:195], off
	s_mov_b32 m0, s47
	v_lshl_add_u64 v[194:195], v[236:237], 0, s[24:25]
	global_load_lds_dwordx4 v[194:195], off
	s_waitcnt vmcnt(8) lgkmcnt(0)
	s_setprio 1
	s_barrier
	v_mfma_f32_16x16x32_bf16 v[60:63], v[146:149], v[198:201], v[60:63]
	v_mfma_f32_16x16x32_bf16 v[52:55], v[154:157], v[198:201], v[52:55]
	v_mfma_f32_16x16x32_bf16 v[44:47], v[146:149], v[208:211], v[44:47]
	v_mfma_f32_16x16x32_bf16 v[36:39], v[154:157], v[208:211], v[36:39]
	v_mfma_f32_16x16x32_bf16 v[28:31], v[146:149], v[216:219], v[28:31]
	v_mfma_f32_16x16x32_bf16 v[20:23], v[154:157], v[216:219], v[20:23]
	v_mfma_f32_16x16x32_bf16 v[12:15], v[146:149], v[224:227], v[12:15]
	v_mfma_f32_16x16x32_bf16 v[4:7], v[154:157], v[224:227], v[4:7]
	v_mfma_f32_16x16x32_bf16 v[60:63], v[150:153], v[204:207], v[60:63]
	v_mfma_f32_16x16x32_bf16 v[52:55], v[160:163], v[204:207], v[52:55]
	v_mfma_f32_16x16x32_bf16 v[44:47], v[150:153], v[212:215], v[44:47]
	v_mfma_f32_16x16x32_bf16 v[36:39], v[160:163], v[212:215], v[36:39]
	v_mfma_f32_16x16x32_bf16 v[28:31], v[150:153], v[220:223], v[28:31]
	v_mfma_f32_16x16x32_bf16 v[20:23], v[160:163], v[220:223], v[20:23]
	v_mfma_f32_16x16x32_bf16 v[12:15], v[150:153], v[228:231], v[12:15]
	v_mfma_f32_16x16x32_bf16 v[4:7], v[160:163], v[228:231], v[4:7]
	s_setprio 0
	s_setprio 1
	v_mfma_f32_16x16x32_bf16 v[56:59], v[178:181], v[198:201], v[56:59]
	v_mfma_f32_16x16x32_bf16 v[48:51], v[186:189], v[198:201], v[48:51]
	v_mfma_f32_16x16x32_bf16 v[40:43], v[178:181], v[208:211], v[40:43]
	v_mfma_f32_16x16x32_bf16 v[32:35], v[186:189], v[208:211], v[32:35]
	v_mfma_f32_16x16x32_bf16 v[24:27], v[178:181], v[216:219], v[24:27]
	v_mfma_f32_16x16x32_bf16 v[16:19], v[186:189], v[216:219], v[16:19]
	v_mfma_f32_16x16x32_bf16 v[8:11], v[178:181], v[224:227], v[8:11]
	v_mfma_f32_16x16x32_bf16 v[0:3], v[186:189], v[224:227], v[0:3]
	v_mfma_f32_16x16x32_bf16 v[56:59], v[182:185], v[204:207], v[56:59]
	v_mfma_f32_16x16x32_bf16 v[48:51], v[190:193], v[204:207], v[48:51]
	v_mfma_f32_16x16x32_bf16 v[40:43], v[182:185], v[212:215], v[40:43]
	v_mfma_f32_16x16x32_bf16 v[32:35], v[190:193], v[212:215], v[32:35]
	v_mfma_f32_16x16x32_bf16 v[24:27], v[182:185], v[220:223], v[24:27]
	v_mfma_f32_16x16x32_bf16 v[16:19], v[190:193], v[220:223], v[16:19]
	v_mfma_f32_16x16x32_bf16 v[8:11], v[182:185], v[228:231], v[8:11]
	v_mfma_f32_16x16x32_bf16 v[0:3], v[190:193], v[228:231], v[0:3]
	s_setprio 0
	s_add_i32 s55, s55, 2
	s_add_u32 s10, s10, 0x100
	s_addc_u32 s11, s11, 0
	s_add_u32 s53, s53, 0x100
	s_addc_u32 s54, s54, 0
	s_cmp_gt_u32 s55, 13
	s_barrier
	s_cbranch_scc0 .LBB0_1048
	s_and_b64 vcc, exec, s[26:27]
	s_cbranch_vccz .LBB0_1051
	s_barrier

.Lrstd_done_p9:
	v_or_b32_e32 v160, 16, v162
	v_or_b32_e32 v156, 32, v162
	v_or_b32_e32 v154, 48, v162
	v_add_u32_e32 v148, 0x80, v162
	s_nop 0
	v_add_u32_e32 v152, 0x90, v162
	v_add_u32_e32 v150, 0xa0, v162
	s_nop 0
	s_nop 1
	v_add_u32_e32 v146, 0xb0, v162
	s_waitcnt lgkmcnt(0)
	s_waitcnt vmcnt(1)
	s_waitcnt lgkmcnt(0)
	s_waitcnt lgkmcnt(0)
	s_waitcnt vmcnt(0)
	v_mov_b32_e32 v178, v120
	s_waitcnt lgkmcnt(0)
	s_waitcnt lgkmcnt(0)
	v_mov_b32_e32 v179, v124
	v_pk_mul_f32 v[178:179], v[178:179], v[176:177] op_sel_hi:[1,0]
	v_mov_b32_e32 v124, v121
	v_mul_f32_e32 v120, 0xbfb8aa3b, v179
	v_exp_f32_e32 v147, v120
	v_pk_mul_f32 v[120:121], v[124:125], v[176:177] op_sel_hi:[1,0]
	s_andn2_b64 vcc, exec, s[6:7]
	v_mul_f32_e32 v124, 0xbfb8aa3b, v121
	v_exp_f32_e32 v125, v124
	v_add_f32_e32 v147, 1.0, v147
	v_rcp_f32_e32 v147, v147
	v_lshl_or_b32 v124, s33, 7, v167
	v_add_f32_e32 v125, 1.0, v125
	v_rcp_f32_e32 v149, v125
	v_mul_f32_e32 v147, v179, v147
	v_mul_f32_e32 v147, v178, v147
	v_mov_b32_e32 v178, v122
	v_mov_b32_e32 v179, v126
	v_pk_mul_f32 v[178:179], v[178:179], v[176:177] op_sel_hi:[1,0]
	v_mov_b32_e32 v126, v123
	v_mul_f32_e32 v122, 0xbfb8aa3b, v179
	v_mul_f32_e32 v121, v121, v149
	v_exp_f32_e32 v149, v122
	v_pk_mul_f32 v[122:123], v[126:127], v[176:177] op_sel_hi:[1,0]
	v_mul_f32_e32 v127, v120, v121
	v_mul_f32_e32 v126, 0xbfb8aa3b, v123
	v_exp_f32_e32 v126, v126
	v_add_f32_e32 v120, 1.0, v149
	v_rcp_f32_e32 v149, v120
	v_mov_b32_e32 v121, v116
	v_add_f32_e32 v120, 1.0, v126
	v_rcp_f32_e32 v126, v120
	v_mov_b32_e32 v120, v112
	v_pk_mul_f32 v[120:121], v[120:121], v[176:177] op_sel_hi:[1,0]
	v_mul_f32_e32 v116, v179, v149
	v_mul_f32_e32 v112, 0xbfb8aa3b, v121
	v_exp_f32_e32 v112, v112
	v_mul_f32_e32 v149, v178, v116
	v_mov_b32_e32 v116, v113
	v_mul_f32_e32 v123, v123, v126
	v_add_f32_e32 v112, 1.0, v112
	v_rcp_f32_e32 v126, v112
	v_pk_mul_f32 v[112:113], v[116:117], v[176:177] op_sel_hi:[1,0]
	v_mul_f32_e32 v122, v122, v123
	v_mul_f32_e32 v116, 0xbfb8aa3b, v113
	v_exp_f32_e32 v116, v116
	v_mul_f32_e32 v117, v121, v126
	v_mul_f32_e32 v120, v120, v117
	v_mov_b32_e32 v117, v118
	v_add_f32_e32 v116, 1.0, v116
	v_rcp_f32_e32 v121, v116
	v_mov_b32_e32 v116, v114
	v_pk_mul_f32 v[116:117], v[116:117], v[176:177] op_sel_hi:[1,0]
	v_mov_b32_e32 v118, v115
	v_mul_f32_e32 v114, 0xbfb8aa3b, v117
	v_exp_f32_e32 v123, v114
	v_pk_mul_f32 v[114:115], v[118:119], v[176:177] op_sel_hi:[1,0]
	v_mul_f32_e32 v113, v113, v121
	v_mul_f32_e32 v118, 0xbfb8aa3b, v115
	v_exp_f32_e32 v118, v118
	v_add_f32_e32 v119, 1.0, v123
	v_rcp_f32_e32 v119, v119
	v_mul_f32_e32 v112, v112, v113
	v_add_f32_e32 v118, 1.0, v118
	v_rcp_f32_e32 v118, v118
	v_mul_f32_e32 v113, v117, v119
	v_mul_f32_e32 v113, v116, v113
	v_cvt_pk_bf16_f32 v116, v147, v127
	v_cvt_pk_bf16_f32 v117, v149, v122
	v_mov_b32_e32 v122, v104
	v_mov_b32_e32 v123, v108
	v_mul_f32_e32 v115, v115, v118
	v_pk_mul_f32 v[122:123], v[122:123], v[174:175] op_sel_hi:[1,0]
	v_ashrrev_i32_e32 v125, 31, v124
	v_mul_f32_e32 v114, v114, v115
	v_mul_f32_e32 v104, 0xbfb8aa3b, v123
	v_cvt_pk_bf16_f32 v118, v120, v112
	v_cvt_pk_bf16_f32 v119, v113, v114
	v_lshlrev_b64 v[114:115], 1, v[124:125]
	v_exp_f32_e32 v124, v104
	v_mov_b32_e32 v108, v105
	v_mov_b64_e32 v[112:113], s[22:23]
	v_pk_mul_f32 v[104:105], v[108:109], v[174:175] op_sel_hi:[1,0]
	v_mad_i64_i32 v[120:121], s[4:5], v162, s51, v[112:113]
	v_mul_f32_e32 v108, 0xbfb8aa3b, v105
	v_exp_f32_e32 v125, v108
	v_lshl_add_u64 v[108:109], v[120:121], 0, v[114:115]
	v_add_f32_e32 v120, 1.0, v124
	v_rcp_f32_e32 v120, v120
	global_store_dwordx4 v[108:109], v[116:119], off
	v_mov_b32_e32 v109, v110
	v_add_f32_e32 v121, 1.0, v125
	v_mul_f32_e32 v108, v123, v120
	v_mul_f32_e32 v116, v122, v108
	v_mov_b32_e32 v108, v106
	v_pk_mul_f32 v[108:109], v[108:109], v[174:175] op_sel_hi:[1,0]
	v_mov_b32_e32 v110, v107
	v_mul_f32_e32 v106, 0xbfb8aa3b, v109
	v_rcp_f32_e32 v121, v121
	v_exp_f32_e32 v117, v106
	v_pk_mul_f32 v[106:107], v[110:111], v[174:175] op_sel_hi:[1,0]
	v_mul_f32_e32 v105, v105, v121
	v_mul_f32_e32 v110, 0xbfb8aa3b, v107
	v_exp_f32_e32 v110, v110
	v_mul_f32_e32 v111, v104, v105
	v_add_f32_e32 v104, 1.0, v117
	v_rcp_f32_e32 v117, v104
	v_add_f32_e32 v104, 1.0, v110
	v_rcp_f32_e32 v110, v104
	v_mov_b32_e32 v104, v96
	v_mov_b32_e32 v105, v100
	v_pk_mul_f32 v[104:105], v[104:105], v[174:175] op_sel_hi:[1,0]
	v_mul_f32_e32 v100, v109, v117
	v_mul_f32_e32 v96, 0xbfb8aa3b, v105
	v_exp_f32_e32 v96, v96
	v_mul_f32_e32 v108, v108, v100
	v_mov_b32_e32 v100, v97
	v_mul_f32_e32 v107, v107, v110
	v_add_f32_e32 v96, 1.0, v96
	v_rcp_f32_e32 v109, v96
	v_pk_mul_f32 v[96:97], v[100:101], v[174:175] op_sel_hi:[1,0]
	v_mul_f32_e32 v106, v106, v107
	v_mul_f32_e32 v100, 0xbfb8aa3b, v97
	v_exp_f32_e32 v100, v100
	v_mul_f32_e32 v101, v105, v109
	v_mul_f32_e32 v104, v104, v101
	v_mov_b32_e32 v101, v102
	v_add_f32_e32 v100, 1.0, v100
	v_rcp_f32_e32 v105, v100
	v_mov_b32_e32 v100, v98
	v_pk_mul_f32 v[100:101], v[100:101], v[174:175] op_sel_hi:[1,0]
	v_mov_b32_e32 v102, v99
	v_mul_f32_e32 v98, 0xbfb8aa3b, v101
	v_exp_f32_e32 v107, v98
	v_pk_mul_f32 v[98:99], v[102:103], v[174:175] op_sel_hi:[1,0]
	v_mul_f32_e32 v97, v97, v105
	v_mul_f32_e32 v102, 0xbfb8aa3b, v99
	v_exp_f32_e32 v102, v102
	v_add_f32_e32 v103, 1.0, v107
	v_rcp_f32_e32 v103, v103
	v_mul_f32_e32 v105, v96, v97
	v_add_f32_e32 v102, 1.0, v102
	v_rcp_f32_e32 v102, v102
	v_mul_f32_e32 v96, v101, v103
	v_mul_f32_e32 v100, v100, v96
	v_mov_b32_e32 v103, v92
	v_mul_f32_e32 v96, v99, v102
	v_mov_b32_e32 v102, v88
	v_pk_mul_f32 v[102:103], v[102:103], v[172:173] op_sel_hi:[1,0]
	v_mul_f32_e32 v99, v98, v96
	v_mul_f32_e32 v88, 0xbfb8aa3b, v103
	v_cvt_pk_bf16_f32 v96, v116, v111
	v_cvt_pk_bf16_f32 v97, v108, v106
	v_cvt_pk_bf16_f32 v98, v104, v105
	v_exp_f32_e32 v104, v88
	v_mov_b32_e32 v92, v89
	v_pk_mul_f32 v[88:89], v[92:93], v[172:173] op_sel_hi:[1,0]
	v_cvt_pk_bf16_f32 v99, v100, v99
	v_mad_i64_i32 v[100:101], s[4:5], v160, s51, v[112:113]
	v_mul_f32_e32 v92, 0xbfb8aa3b, v89
	v_exp_f32_e32 v105, v92
	v_lshl_add_u64 v[92:93], v[100:101], 0, v[114:115]
	v_add_f32_e32 v100, 1.0, v104
	v_rcp_f32_e32 v100, v100
	global_store_dwordx4 v[92:93], v[96:99], off
	v_mov_b32_e32 v93, v94
	v_add_f32_e32 v101, 1.0, v105
	v_mul_f32_e32 v92, v103, v100
	v_mul_f32_e32 v96, v102, v92
	v_mov_b32_e32 v92, v90
	v_pk_mul_f32 v[92:93], v[92:93], v[172:173] op_sel_hi:[1,0]
	v_mov_b32_e32 v94, v91
	v_mul_f32_e32 v90, 0xbfb8aa3b, v93
	v_rcp_f32_e32 v101, v101
	v_exp_f32_e32 v97, v90
	v_pk_mul_f32 v[90:91], v[94:95], v[172:173] op_sel_hi:[1,0]
	v_mul_f32_e32 v89, v89, v101
	v_mul_f32_e32 v94, 0xbfb8aa3b, v91
	v_exp_f32_e32 v94, v94
	v_mul_f32_e32 v95, v88, v89
	v_add_f32_e32 v88, 1.0, v97
	v_rcp_f32_e32 v97, v88
	v_add_f32_e32 v88, 1.0, v94
	v_rcp_f32_e32 v94, v88
	v_mov_b32_e32 v88, v80
	v_mov_b32_e32 v89, v84
	v_pk_mul_f32 v[88:89], v[88:89], v[172:173] op_sel_hi:[1,0]
	v_mul_f32_e32 v84, v93, v97
	v_mul_f32_e32 v80, 0xbfb8aa3b, v89
	v_exp_f32_e32 v80, v80
	v_mul_f32_e32 v92, v92, v84
	v_mov_b32_e32 v84, v81
	v_mul_f32_e32 v91, v91, v94
	v_add_f32_e32 v80, 1.0, v80
	v_rcp_f32_e32 v93, v80
	v_pk_mul_f32 v[80:81], v[84:85], v[172:173] op_sel_hi:[1,0]
	v_mul_f32_e32 v90, v90, v91
	v_mul_f32_e32 v84, 0xbfb8aa3b, v81
	v_exp_f32_e32 v84, v84
	v_mul_f32_e32 v85, v89, v93
	v_mul_f32_e32 v88, v88, v85
	v_mov_b32_e32 v85, v86
	v_add_f32_e32 v84, 1.0, v84
	v_rcp_f32_e32 v89, v84
	v_mov_b32_e32 v84, v82
	v_pk_mul_f32 v[84:85], v[84:85], v[172:173] op_sel_hi:[1,0]
	v_mov_b32_e32 v86, v83
	v_mul_f32_e32 v82, 0xbfb8aa3b, v85
	v_exp_f32_e32 v91, v82
	v_pk_mul_f32 v[82:83], v[86:87], v[172:173] op_sel_hi:[1,0]
	v_mul_f32_e32 v81, v81, v89
	v_mul_f32_e32 v86, 0xbfb8aa3b, v83
	v_exp_f32_e32 v86, v86
	v_add_f32_e32 v87, 1.0, v91
	v_rcp_f32_e32 v87, v87
	v_mul_f32_e32 v89, v80, v81
	v_add_f32_e32 v86, 1.0, v86
	v_rcp_f32_e32 v86, v86
	v_mul_f32_e32 v80, v85, v87
	v_mul_f32_e32 v84, v84, v80
	v_mov_b32_e32 v87, v76
	v_mul_f32_e32 v80, v83, v86
	v_mov_b32_e32 v86, v72
	v_pk_mul_f32 v[86:87], v[86:87], v[170:171] op_sel_hi:[1,0]
	v_mul_f32_e32 v83, v82, v80
	v_mul_f32_e32 v72, 0xbfb8aa3b, v87
	v_cvt_pk_bf16_f32 v80, v96, v95
	v_cvt_pk_bf16_f32 v81, v92, v90
	v_cvt_pk_bf16_f32 v82, v88, v89
	v_exp_f32_e32 v88, v72
	v_mov_b32_e32 v76, v73
	v_pk_mul_f32 v[72:73], v[76:77], v[170:171] op_sel_hi:[1,0]
	v_cvt_pk_bf16_f32 v83, v84, v83
	v_mad_i64_i32 v[84:85], s[4:5], v156, s51, v[112:113]
	v_mul_f32_e32 v76, 0xbfb8aa3b, v73
	v_exp_f32_e32 v89, v76
	v_lshl_add_u64 v[76:77], v[84:85], 0, v[114:115]
	v_add_f32_e32 v84, 1.0, v88
	v_rcp_f32_e32 v84, v84
	global_store_dwordx4 v[76:77], v[80:83], off
	v_mov_b32_e32 v77, v78
	v_add_f32_e32 v85, 1.0, v89
	v_mul_f32_e32 v76, v87, v84
	v_mul_f32_e32 v80, v86, v76
	v_mov_b32_e32 v76, v74
	v_pk_mul_f32 v[76:77], v[76:77], v[170:171] op_sel_hi:[1,0]
	v_mov_b32_e32 v78, v75
	v_mul_f32_e32 v74, 0xbfb8aa3b, v77
	v_rcp_f32_e32 v85, v85
	v_exp_f32_e32 v81, v74
	v_pk_mul_f32 v[74:75], v[78:79], v[170:171] op_sel_hi:[1,0]
	v_mul_f32_e32 v73, v73, v85
	v_mul_f32_e32 v78, 0xbfb8aa3b, v75
	v_exp_f32_e32 v78, v78
	v_mul_f32_e32 v79, v72, v73
	v_add_f32_e32 v72, 1.0, v81
	v_rcp_f32_e32 v81, v72
	v_add_f32_e32 v72, 1.0, v78
	v_rcp_f32_e32 v78, v72
	v_mov_b32_e32 v72, v64
	v_mov_b32_e32 v73, v68
	v_pk_mul_f32 v[72:73], v[72:73], v[170:171] op_sel_hi:[1,0]
	v_mul_f32_e32 v68, v77, v81
	v_mul_f32_e32 v64, 0xbfb8aa3b, v73
	v_exp_f32_e32 v64, v64
	v_mul_f32_e32 v76, v76, v68
	v_mov_b32_e32 v68, v65
	v_mul_f32_e32 v75, v75, v78
	v_add_f32_e32 v64, 1.0, v64
	v_rcp_f32_e32 v77, v64
	v_pk_mul_f32 v[64:65], v[68:69], v[170:171] op_sel_hi:[1,0]
	v_mul_f32_e32 v74, v74, v75
	v_mul_f32_e32 v68, 0xbfb8aa3b, v65
	v_exp_f32_e32 v68, v68
	v_mul_f32_e32 v69, v73, v77
	v_mul_f32_e32 v72, v72, v69
	v_mov_b32_e32 v69, v70
	v_add_f32_e32 v68, 1.0, v68
	v_rcp_f32_e32 v73, v68
	v_mov_b32_e32 v68, v66
	v_pk_mul_f32 v[68:69], v[68:69], v[170:171] op_sel_hi:[1,0]
	v_mov_b32_e32 v70, v67
	v_mul_f32_e32 v66, 0xbfb8aa3b, v69
	v_exp_f32_e32 v75, v66
	v_pk_mul_f32 v[66:67], v[70:71], v[170:171] op_sel_hi:[1,0]
	v_mul_f32_e32 v65, v65, v73
	v_mul_f32_e32 v70, 0xbfb8aa3b, v67
	v_exp_f32_e32 v70, v70
	v_add_f32_e32 v71, 1.0, v75
	v_rcp_f32_e32 v71, v71
	v_mul_f32_e32 v73, v64, v65
	v_add_f32_e32 v70, 1.0, v70
	v_rcp_f32_e32 v70, v70
	v_mul_f32_e32 v64, v69, v71
	v_mul_f32_e32 v68, v68, v64
	v_mov_b32_e32 v71, v60
	v_mul_f32_e32 v64, v67, v70
	v_mov_b32_e32 v70, v56
	v_pk_mul_f32 v[70:71], v[70:71], v[168:169] op_sel_hi:[1,0]
	v_mul_f32_e32 v67, v66, v64
	v_mul_f32_e32 v56, 0xbfb8aa3b, v71
	v_cvt_pk_bf16_f32 v64, v80, v79
	v_cvt_pk_bf16_f32 v65, v76, v74
	v_cvt_pk_bf16_f32 v66, v72, v73
	v_exp_f32_e32 v72, v56
	v_mov_b32_e32 v60, v57
	v_pk_mul_f32 v[56:57], v[60:61], v[168:169] op_sel_hi:[1,0]
	v_cvt_pk_bf16_f32 v67, v68, v67
	v_mad_i64_i32 v[68:69], s[4:5], v154, s51, v[112:113]
	v_mul_f32_e32 v60, 0xbfb8aa3b, v57
	v_exp_f32_e32 v73, v60
	v_lshl_add_u64 v[60:61], v[68:69], 0, v[114:115]
	v_add_f32_e32 v68, 1.0, v72
	v_rcp_f32_e32 v68, v68
	global_store_dwordx4 v[60:61], v[64:67], off
	v_mov_b32_e32 v61, v62
	v_add_f32_e32 v69, 1.0, v73
	v_mul_f32_e32 v60, v71, v68
	v_mul_f32_e32 v64, v70, v60
	v_mov_b32_e32 v60, v58
	v_pk_mul_f32 v[60:61], v[60:61], v[168:169] op_sel_hi:[1,0]
	v_mov_b32_e32 v62, v59
	v_mul_f32_e32 v58, 0xbfb8aa3b, v61
	v_rcp_f32_e32 v69, v69
	v_exp_f32_e32 v65, v58
	v_pk_mul_f32 v[58:59], v[62:63], v[168:169] op_sel_hi:[1,0]
	v_mul_f32_e32 v57, v57, v69
	v_mul_f32_e32 v62, 0xbfb8aa3b, v59
	v_exp_f32_e32 v62, v62
	v_mul_f32_e32 v63, v56, v57
	v_add_f32_e32 v56, 1.0, v65
	v_rcp_f32_e32 v65, v56
	v_add_f32_e32 v56, 1.0, v62
	v_rcp_f32_e32 v62, v56
	v_mov_b32_e32 v56, v48
	v_mov_b32_e32 v57, v52
	v_pk_mul_f32 v[56:57], v[56:57], v[168:169] op_sel_hi:[1,0]
	v_mul_f32_e32 v52, v61, v65
	v_mul_f32_e32 v48, 0xbfb8aa3b, v57
	v_exp_f32_e32 v48, v48
	v_mul_f32_e32 v60, v60, v52
	v_mov_b32_e32 v52, v49
	v_mul_f32_e32 v59, v59, v62
	v_add_f32_e32 v48, 1.0, v48
	v_rcp_f32_e32 v61, v48
	v_pk_mul_f32 v[48:49], v[52:53], v[168:169] op_sel_hi:[1,0]
	v_mul_f32_e32 v58, v58, v59
	v_mul_f32_e32 v52, 0xbfb8aa3b, v49
	v_exp_f32_e32 v52, v52
	v_mul_f32_e32 v53, v57, v61
	v_mul_f32_e32 v56, v56, v53
	v_mov_b32_e32 v53, v54
	v_add_f32_e32 v52, 1.0, v52
	v_rcp_f32_e32 v57, v52
	v_mov_b32_e32 v52, v50
	v_pk_mul_f32 v[52:53], v[52:53], v[168:169] op_sel_hi:[1,0]
	v_mov_b32_e32 v54, v51
	v_mul_f32_e32 v50, 0xbfb8aa3b, v53
	v_exp_f32_e32 v59, v50
	v_pk_mul_f32 v[50:51], v[54:55], v[168:169] op_sel_hi:[1,0]
	v_mul_f32_e32 v49, v49, v57
	v_mul_f32_e32 v54, 0xbfb8aa3b, v51
	v_exp_f32_e32 v54, v54
	v_add_f32_e32 v55, 1.0, v59
	v_rcp_f32_e32 v55, v55
	v_mul_f32_e32 v57, v48, v49
	v_add_f32_e32 v54, 1.0, v54
	v_rcp_f32_e32 v54, v54
	v_mul_f32_e32 v48, v53, v55
	v_mul_f32_e32 v52, v52, v48
	v_mov_b32_e32 v55, v44
	v_mul_f32_e32 v48, v51, v54
	v_mov_b32_e32 v54, v40
	v_pk_mul_f32 v[54:55], v[54:55], v[166:167] op_sel_hi:[1,0]
	v_mul_f32_e32 v51, v50, v48
	v_mul_f32_e32 v40, 0xbfb8aa3b, v55
	v_cvt_pk_bf16_f32 v48, v64, v63
	v_cvt_pk_bf16_f32 v49, v60, v58
	v_cvt_pk_bf16_f32 v50, v56, v57
	v_exp_f32_e32 v56, v40
	v_mov_b32_e32 v44, v41
	v_pk_mul_f32 v[40:41], v[44:45], v[166:167] op_sel_hi:[1,0]
	v_cvt_pk_bf16_f32 v51, v52, v51
	v_mad_i64_i32 v[52:53], s[4:5], v148, s51, v[112:113]
	v_mul_f32_e32 v44, 0xbfb8aa3b, v41
	v_exp_f32_e32 v57, v44
	v_lshl_add_u64 v[44:45], v[52:53], 0, v[114:115]
	v_add_f32_e32 v52, 1.0, v56
	v_rcp_f32_e32 v52, v52
	global_store_dwordx4 v[44:45], v[48:51], off
	v_mov_b32_e32 v45, v46
	v_add_f32_e32 v53, 1.0, v57
	v_mul_f32_e32 v44, v55, v52
	v_mul_f32_e32 v48, v54, v44
	v_mov_b32_e32 v44, v42
	v_pk_mul_f32 v[44:45], v[44:45], v[166:167] op_sel_hi:[1,0]
	v_mov_b32_e32 v46, v43
	v_mul_f32_e32 v42, 0xbfb8aa3b, v45
	v_rcp_f32_e32 v53, v53
	v_exp_f32_e32 v49, v42
	v_pk_mul_f32 v[42:43], v[46:47], v[166:167] op_sel_hi:[1,0]
	v_mul_f32_e32 v41, v41, v53
	v_mul_f32_e32 v46, 0xbfb8aa3b, v43
	v_exp_f32_e32 v46, v46
	v_mul_f32_e32 v47, v40, v41
	v_add_f32_e32 v40, 1.0, v49
	v_rcp_f32_e32 v49, v40
	v_add_f32_e32 v40, 1.0, v46
	v_rcp_f32_e32 v46, v40
	v_mov_b32_e32 v40, v32
	v_mov_b32_e32 v41, v36
	v_pk_mul_f32 v[40:41], v[40:41], v[166:167] op_sel_hi:[1,0]
	v_mul_f32_e32 v36, v45, v49
	v_mul_f32_e32 v32, 0xbfb8aa3b, v41
	v_exp_f32_e32 v32, v32
	v_mul_f32_e32 v44, v44, v36
	v_mov_b32_e32 v36, v33
	v_mul_f32_e32 v43, v43, v46
	v_add_f32_e32 v32, 1.0, v32
	v_rcp_f32_e32 v45, v32
	v_pk_mul_f32 v[32:33], v[36:37], v[166:167] op_sel_hi:[1,0]
	v_mul_f32_e32 v42, v42, v43
	v_mul_f32_e32 v36, 0xbfb8aa3b, v33
	v_exp_f32_e32 v36, v36
	v_mul_f32_e32 v37, v41, v45
	v_mul_f32_e32 v40, v40, v37
	v_mov_b32_e32 v37, v38
	v_add_f32_e32 v36, 1.0, v36
	v_rcp_f32_e32 v41, v36
	v_mov_b32_e32 v36, v34
	v_pk_mul_f32 v[36:37], v[36:37], v[166:167] op_sel_hi:[1,0]
	v_mov_b32_e32 v38, v35
	v_mul_f32_e32 v34, 0xbfb8aa3b, v37
	v_exp_f32_e32 v43, v34
	v_pk_mul_f32 v[34:35], v[38:39], v[166:167] op_sel_hi:[1,0]
	v_mul_f32_e32 v33, v33, v41
	v_mul_f32_e32 v38, 0xbfb8aa3b, v35
	v_exp_f32_e32 v38, v38
	v_add_f32_e32 v39, 1.0, v43
	v_rcp_f32_e32 v39, v39
	v_mul_f32_e32 v41, v32, v33
	v_add_f32_e32 v38, 1.0, v38
	v_rcp_f32_e32 v38, v38
	v_mul_f32_e32 v32, v37, v39
	v_mul_f32_e32 v36, v36, v32
	v_mov_b32_e32 v39, v28
	v_mul_f32_e32 v32, v35, v38
	v_mov_b32_e32 v38, v24
	v_pk_mul_f32 v[38:39], v[38:39], v[164:165] op_sel_hi:[1,0]
	v_mul_f32_e32 v35, v34, v32
	v_mul_f32_e32 v24, 0xbfb8aa3b, v39
	v_cvt_pk_bf16_f32 v32, v48, v47
	v_cvt_pk_bf16_f32 v33, v44, v42
	v_cvt_pk_bf16_f32 v34, v40, v41
	v_exp_f32_e32 v40, v24
	v_mov_b32_e32 v28, v25
	v_pk_mul_f32 v[24:25], v[28:29], v[164:165] op_sel_hi:[1,0]
	v_cvt_pk_bf16_f32 v35, v36, v35
	v_mad_i64_i32 v[36:37], s[4:5], v152, s51, v[112:113]
	v_mul_f32_e32 v28, 0xbfb8aa3b, v25
	v_exp_f32_e32 v41, v28
	v_lshl_add_u64 v[28:29], v[36:37], 0, v[114:115]
	v_add_f32_e32 v36, 1.0, v40
	v_rcp_f32_e32 v36, v36
	global_store_dwordx4 v[28:29], v[32:35], off
	v_mov_b32_e32 v29, v30
	v_add_f32_e32 v37, 1.0, v41
	v_mul_f32_e32 v28, v39, v36
	v_mul_f32_e32 v32, v38, v28
	v_mov_b32_e32 v28, v26
	v_pk_mul_f32 v[28:29], v[28:29], v[164:165] op_sel_hi:[1,0]
	v_mov_b32_e32 v30, v27
	v_mul_f32_e32 v26, 0xbfb8aa3b, v29
	v_rcp_f32_e32 v37, v37
	v_exp_f32_e32 v33, v26
	v_pk_mul_f32 v[26:27], v[30:31], v[164:165] op_sel_hi:[1,0]
	v_mul_f32_e32 v25, v25, v37
	v_mul_f32_e32 v30, 0xbfb8aa3b, v27
	v_exp_f32_e32 v30, v30
	v_mul_f32_e32 v31, v24, v25
	v_add_f32_e32 v24, 1.0, v33
	v_rcp_f32_e32 v33, v24
	v_add_f32_e32 v24, 1.0, v30
	v_rcp_f32_e32 v30, v24
	v_mov_b32_e32 v24, v16
	v_mov_b32_e32 v25, v20
	v_pk_mul_f32 v[24:25], v[24:25], v[164:165] op_sel_hi:[1,0]
	v_mul_f32_e32 v20, v29, v33
	v_mul_f32_e32 v16, 0xbfb8aa3b, v25
	v_exp_f32_e32 v16, v16
	v_mul_f32_e32 v28, v28, v20
	v_mov_b32_e32 v20, v17
	v_mul_f32_e32 v27, v27, v30
	v_add_f32_e32 v16, 1.0, v16
	v_rcp_f32_e32 v29, v16
	v_pk_mul_f32 v[16:17], v[20:21], v[164:165] op_sel_hi:[1,0]
	v_mul_f32_e32 v26, v26, v27
	v_mul_f32_e32 v20, 0xbfb8aa3b, v17
	v_exp_f32_e32 v20, v20
	v_mul_f32_e32 v21, v25, v29
	v_mul_f32_e32 v24, v24, v21
	v_mov_b32_e32 v21, v22
	v_add_f32_e32 v20, 1.0, v20
	v_rcp_f32_e32 v25, v20
	v_mov_b32_e32 v20, v18
	v_pk_mul_f32 v[20:21], v[20:21], v[164:165] op_sel_hi:[1,0]
	v_mov_b32_e32 v22, v19
	v_mul_f32_e32 v18, 0xbfb8aa3b, v21
	v_exp_f32_e32 v27, v18
	v_pk_mul_f32 v[18:19], v[22:23], v[164:165] op_sel_hi:[1,0]
	v_mul_f32_e32 v17, v17, v25
	v_mul_f32_e32 v22, 0xbfb8aa3b, v19
	v_exp_f32_e32 v22, v22
	v_add_f32_e32 v23, 1.0, v27
	v_rcp_f32_e32 v23, v23
	v_mul_f32_e32 v25, v16, v17
	v_add_f32_e32 v22, 1.0, v22
	v_rcp_f32_e32 v22, v22
	v_mul_f32_e32 v16, v21, v23
	v_mul_f32_e32 v20, v20, v16
	v_mov_b32_e32 v23, v12
	v_mul_f32_e32 v16, v19, v22
	v_mov_b32_e32 v22, v8
	v_pk_mul_f32 v[22:23], v[22:23], v[158:159] op_sel_hi:[1,0]
	v_mul_f32_e32 v19, v18, v16
	v_mul_f32_e32 v8, 0xbfb8aa3b, v23
	v_cvt_pk_bf16_f32 v16, v32, v31
	v_cvt_pk_bf16_f32 v17, v28, v26
	v_cvt_pk_bf16_f32 v18, v24, v25
	v_exp_f32_e32 v24, v8
	v_mov_b32_e32 v12, v9
	v_pk_mul_f32 v[8:9], v[12:13], v[158:159] op_sel_hi:[1,0]
	v_cvt_pk_bf16_f32 v19, v20, v19
	v_mad_i64_i32 v[20:21], s[4:5], v150, s51, v[112:113]
	v_mul_f32_e32 v12, 0xbfb8aa3b, v9
	v_exp_f32_e32 v25, v12
	v_lshl_add_u64 v[12:13], v[20:21], 0, v[114:115]
	v_add_f32_e32 v20, 1.0, v24
	v_rcp_f32_e32 v20, v20
	global_store_dwordx4 v[12:13], v[16:19], off
	v_mov_b32_e32 v13, v14
	v_add_f32_e32 v21, 1.0, v25
	v_mul_f32_e32 v12, v23, v20
	v_mul_f32_e32 v16, v22, v12
	v_mov_b32_e32 v12, v10
	v_pk_mul_f32 v[12:13], v[12:13], v[158:159] op_sel_hi:[1,0]
	v_mov_b32_e32 v14, v11
	v_mul_f32_e32 v10, 0xbfb8aa3b, v13
	v_rcp_f32_e32 v21, v21
	v_exp_f32_e32 v17, v10
	v_pk_mul_f32 v[10:11], v[14:15], v[158:159] op_sel_hi:[1,0]
	v_mul_f32_e32 v9, v9, v21
	v_mul_f32_e32 v14, 0xbfb8aa3b, v11
	v_exp_f32_e32 v14, v14
	v_mul_f32_e32 v15, v8, v9
	v_add_f32_e32 v8, 1.0, v17
	v_rcp_f32_e32 v17, v8
	v_add_f32_e32 v8, 1.0, v14
	v_rcp_f32_e32 v14, v8
	v_mov_b32_e32 v8, v0
	v_mov_b32_e32 v9, v4
	v_pk_mul_f32 v[8:9], v[8:9], v[158:159] op_sel_hi:[1,0]
	v_mul_f32_e32 v4, v13, v17
	v_mul_f32_e32 v0, 0xbfb8aa3b, v9
	v_exp_f32_e32 v0, v0
	v_mul_f32_e32 v12, v12, v4
	v_mov_b32_e32 v4, v1
	v_mul_f32_e32 v11, v11, v14
	v_add_f32_e32 v0, 1.0, v0
	v_rcp_f32_e32 v13, v0
	v_pk_mul_f32 v[0:1], v[4:5], v[158:159] op_sel_hi:[1,0]
	v_mul_f32_e32 v10, v10, v11
	v_mul_f32_e32 v4, 0xbfb8aa3b, v1
	v_exp_f32_e32 v4, v4
	v_mul_f32_e32 v5, v9, v13
	v_mul_f32_e32 v8, v8, v5
	v_mov_b32_e32 v5, v6
	v_add_f32_e32 v4, 1.0, v4
	v_rcp_f32_e32 v9, v4
	v_mov_b32_e32 v4, v2
	v_pk_mul_f32 v[4:5], v[4:5], v[158:159] op_sel_hi:[1,0]
	v_mov_b32_e32 v6, v3
	v_mul_f32_e32 v2, 0xbfb8aa3b, v5
	v_exp_f32_e32 v11, v2
	v_pk_mul_f32 v[2:3], v[6:7], v[158:159] op_sel_hi:[1,0]
	v_mul_f32_e32 v1, v1, v9
	v_mul_f32_e32 v6, 0xbfb8aa3b, v3
	v_exp_f32_e32 v6, v6
	v_add_f32_e32 v7, 1.0, v11
	v_rcp_f32_e32 v7, v7
	v_mul_f32_e32 v9, v0, v1
	v_add_f32_e32 v6, 1.0, v6
	v_rcp_f32_e32 v6, v6
	v_mul_f32_e32 v0, v5, v7
	v_mul_f32_e32 v4, v4, v0
	v_mul_f32_e32 v0, v3, v6
	v_mul_f32_e32 v3, v2, v0
	v_cvt_pk_bf16_f32 v0, v16, v15
	v_cvt_pk_bf16_f32 v1, v12, v10
	v_cvt_pk_bf16_f32 v2, v8, v9
	v_cvt_pk_bf16_f32 v3, v4, v3
	v_mad_i64_i32 v[4:5], s[4:5], v146, s51, v[112:113]
	v_lshl_add_u64 v[4:5], v[4:5], 0, v[114:115]
	s_mov_b64 s[4:5], -1
	global_store_dwordx4 v[4:5], v[0:3], off
	s_cbranch_vccnz .LBB0_1044
	s_andn2_b64 vcc, exec, s[16:17]
	s_cbranch_vccnz .LBB0_1043
	s_mov_b32 s90, 1
	s_branch .LBB0_1043

.LBB0_1105:
	s_mov_b32 s90, 0
	s_or_b64 exec, exec, s[6:7]
	v_readlane_b32 s6, v254, 4
	s_mov_b64 s[4:5], s[0:1]
	s_waitcnt lgkmcnt(0)
	v_mov_b32_e32 v0, v202
	v_mov_b32_e32 v8, v202
	v_readlane_b32 s7, v254, 5
	s_barrier
	s_and_b64 vcc, exec, s[6:7]
	v_readfirstlane_b32 s6, v8
	s_cbranch_vccnz .LBB0_1107
	s_lshr_b32 s7, s21, 29
	s_add_i32 s7, s2, s7
	s_ashr_i32 s8, s7, 3
	s_and_b32 s7, s7, -8
	s_sub_i32 s7, s2, s7
	s_lshl_b32 s10, s7, 6
	s_mul_i32 s9, s7, 0x41
	s_cmp_lt_i32 s7, 0
	s_cselect_b32 s7, s9, s10
	s_add_i32 s7, s7, s8
	s_ashr_i32 s8, s7, 31
	s_lshr_b32 s8, s8, 27
	s_add_i32 s8, s7, s8
	s_ashr_i32 s9, s8, 5
	s_and_b32 s8, s8, 0xffe0
	s_sub_i32 s7, s7, s8
	s_bfe_i32 s8, s7, 0x80000
	s_bfe_u32 s8, s8, 0x3000c
	s_add_i32 s8, s7, s8
	s_bfe_i32 s10, s8, 0x80000
	s_and_b32 s8, s8, 0xf8
	s_sub_i32 s7, s7, s8
	s_lshl_b32 s9, s9, 3
	s_sext_i32_i16 s10, s10
	s_sext_i32_i8 s7, s7
	s_add_i32 s53, s9, s7
	s_ashr_i32 s10, s10, 3

.LBB0_1123:
	s_add_u32 s54, s34, 0x100
	v_mov_b32_e32 v0, 0
	s_addc_u32 s55, s35, 0
	s_mov_b32 s56, -2
	s_waitcnt lgkmcnt(0)
	v_mov_b32_e32 v1, v0
	v_mov_b32_e32 v2, v0
	v_mov_b32_e32 v3, v0
	v_mov_b32_e32 v4, v0
	v_mov_b32_e32 v5, v0
	v_mov_b32_e32 v6, v0
	v_mov_b32_e32 v7, v0
	v_mov_b32_e32 v16, v0
	v_mov_b32_e32 v17, v0
	v_mov_b32_e32 v18, v0
	v_mov_b32_e32 v19, v0
	v_mov_b32_e32 v20, v0
	v_mov_b32_e32 v21, v0
	v_mov_b32_e32 v22, v0
	v_mov_b32_e32 v23, v0
	v_mov_b32_e32 v32, v0
	v_mov_b32_e32 v33, v0
	v_mov_b32_e32 v34, v0
	v_mov_b32_e32 v35, v0
	v_mov_b32_e32 v36, v0
	v_mov_b32_e32 v37, v0
	v_mov_b32_e32 v38, v0
	v_mov_b32_e32 v39, v0
	v_mov_b32_e32 v48, v0
	v_mov_b32_e32 v49, v0
	v_mov_b32_e32 v50, v0
	v_mov_b32_e32 v51, v0
	v_mov_b32_e32 v52, v0
	v_mov_b32_e32 v53, v0
	v_mov_b32_e32 v54, v0
	v_mov_b32_e32 v55, v0
	v_mov_b32_e32 v8, v0
	v_mov_b32_e32 v9, v0
	v_mov_b32_e32 v10, v0
	v_mov_b32_e32 v11, v0
	v_mov_b32_e32 v12, v0
	v_mov_b32_e32 v13, v0
	v_mov_b32_e32 v14, v0
	v_mov_b32_e32 v15, v0
	v_mov_b32_e32 v24, v0
	v_mov_b32_e32 v25, v0
	v_mov_b32_e32 v26, v0
	v_mov_b32_e32 v27, v0
	v_mov_b32_e32 v28, v0
	v_mov_b32_e32 v29, v0
	v_mov_b32_e32 v30, v0
	v_mov_b32_e32 v31, v0
	v_mov_b32_e32 v40, v0
	v_mov_b32_e32 v41, v0
	v_mov_b32_e32 v42, v0
	v_mov_b32_e32 v43, v0
	v_mov_b32_e32 v44, v0
	v_mov_b32_e32 v45, v0
	v_mov_b32_e32 v46, v0
	v_mov_b32_e32 v47, v0
	v_mov_b32_e32 v56, v0
	v_mov_b32_e32 v57, v0
	v_mov_b32_e32 v58, v0
	v_mov_b32_e32 v59, v0
	v_mov_b32_e32 v60, v0
	v_mov_b32_e32 v61, v0
	v_mov_b32_e32 v62, v0
	v_mov_b32_e32 v63, v0
	v_mov_b32_e32 v64, v0
	v_mov_b32_e32 v65, v0
	v_mov_b32_e32 v66, v0
	v_mov_b32_e32 v67, v0
	v_mov_b32_e32 v68, v0
	v_mov_b32_e32 v69, v0
	v_mov_b32_e32 v70, v0
	v_mov_b32_e32 v71, v0
	v_mov_b32_e32 v80, v0
	v_mov_b32_e32 v81, v0
	v_mov_b32_e32 v82, v0
	v_mov_b32_e32 v83, v0
	v_mov_b32_e32 v84, v0
	v_mov_b32_e32 v85, v0
	v_mov_b32_e32 v86, v0
	v_mov_b32_e32 v87, v0
	v_mov_b32_e32 v96, v0
	v_mov_b32_e32 v97, v0
	v_mov_b32_e32 v98, v0
	v_mov_b32_e32 v99, v0
	v_mov_b32_e32 v100, v0
	v_mov_b32_e32 v101, v0
	v_mov_b32_e32 v102, v0
	v_mov_b32_e32 v103, v0
	v_mov_b32_e32 v112, v0
	v_mov_b32_e32 v113, v0
	v_mov_b32_e32 v114, v0
	v_mov_b32_e32 v115, v0
	v_mov_b32_e32 v116, v0
	v_mov_b32_e32 v117, v0
	v_mov_b32_e32 v118, v0
	v_mov_b32_e32 v119, v0
	v_mov_b32_e32 v72, v0
	v_mov_b32_e32 v73, v0
	v_mov_b32_e32 v74, v0
	v_mov_b32_e32 v75, v0
	v_mov_b32_e32 v76, v0
	v_mov_b32_e32 v77, v0
	v_mov_b32_e32 v78, v0
	v_mov_b32_e32 v79, v0
	v_mov_b32_e32 v88, v0
	v_mov_b32_e32 v89, v0
	v_mov_b32_e32 v90, v0
	v_mov_b32_e32 v91, v0
	v_mov_b32_e32 v92, v0
	v_mov_b32_e32 v93, v0
	v_mov_b32_e32 v94, v0
	v_mov_b32_e32 v95, v0
	v_mov_b32_e32 v104, v0
	v_mov_b32_e32 v105, v0
	v_mov_b32_e32 v106, v0
	v_mov_b32_e32 v107, v0
	v_mov_b32_e32 v108, v0
	v_mov_b32_e32 v109, v0
	v_mov_b32_e32 v110, v0
	v_mov_b32_e32 v111, v0
	v_mov_b32_e32 v120, v0
	v_mov_b32_e32 v121, v0
	v_mov_b32_e32 v122, v0
	v_mov_b32_e32 v123, v0
	v_mov_b32_e32 v124, v0
	v_mov_b32_e32 v125, v0
	v_mov_b32_e32 v126, v0
	v_mov_b32_e32 v127, v0
	s_cmp_lg_u32 s90, 0
	s_cbranch_scc0 .Lkl_nobar_7
	s_barrier
	s_mov_b32 s90, 0
.Lkl_nobar_7:
.LBB0_1124:
	ds_read_b128 v[128:131], v189
	ds_read_b128 v[132:135], v189 offset:1024
	ds_read_b128 v[136:139], v189 offset:2048
	ds_read_b128 v[140:143], v189 offset:3072
	ds_read_b128 v[144:147], v190
	ds_read_b128 v[148:151], v190 offset:1024
	ds_read_b128 v[168:171], v190 offset:2048
	ds_read_b128 v[172:175], v190 offset:3072
	s_add_u32 s34, s30, 0x100
	s_addc_u32 s35, s31, 0
	s_cmp_eq_u32 s56, 40
	s_cselect_b32 s39, s9, s35
	s_cselect_b32 s38, s8, s34
	s_cselect_b32 s37, s29, s55
	s_cselect_b32 s36, s28, s54
	v_lshl_add_u64 v[184:185], s[30:31], 0, v[160:161]
	s_add_i32 m0, s42, 0xc000
	ds_read_b128 v[176:179], v191
	ds_read_b128 v[180:183], v191 offset:1024
	ds_read_b128 v[192:195], v191 offset:2048
	ds_read_b128 v[198:201], v191 offset:3072
	ds_read_b128 v[204:207], v191 offset:4096
	ds_read_b128 v[208:211], v191 offset:5120
	ds_read_b128 v[212:215], v191 offset:6144
	ds_read_b128 v[216:219], v191 offset:7168
	global_load_lds_dwordx4 v[184:185], off
	s_add_i32 m0, s42, 0xe000
	v_lshl_add_u64 v[184:185], s[30:31], 0, v[162:163]
	global_load_lds_dwordx4 v[184:185], off
	s_waitcnt vmcnt(8) lgkmcnt(0)
	s_setprio 1
	s_barrier
	v_mfma_f32_16x16x32_bf16 v[124:127], v[128:131], v[176:179], v[124:127]
	v_mfma_f32_16x16x32_bf16 v[120:123], v[136:139], v[176:179], v[120:123]
	v_mfma_f32_16x16x32_bf16 v[108:111], v[128:131], v[192:195], v[108:111]
	v_mfma_f32_16x16x32_bf16 v[104:107], v[136:139], v[192:195], v[104:107]
	v_mfma_f32_16x16x32_bf16 v[92:95], v[128:131], v[204:207], v[92:95]
	v_mfma_f32_16x16x32_bf16 v[88:91], v[136:139], v[204:207], v[88:91]
	v_mfma_f32_16x16x32_bf16 v[76:79], v[128:131], v[212:215], v[76:79]
	v_mfma_f32_16x16x32_bf16 v[72:75], v[136:139], v[212:215], v[72:75]
	v_mfma_f32_16x16x32_bf16 v[124:127], v[132:135], v[180:183], v[124:127]
	v_mfma_f32_16x16x32_bf16 v[120:123], v[140:143], v[180:183], v[120:123]
	v_mfma_f32_16x16x32_bf16 v[108:111], v[132:135], v[198:201], v[108:111]
	v_mfma_f32_16x16x32_bf16 v[104:107], v[140:143], v[198:201], v[104:107]
	v_mfma_f32_16x16x32_bf16 v[92:95], v[132:135], v[208:211], v[92:95]
	v_mfma_f32_16x16x32_bf16 v[88:91], v[140:143], v[208:211], v[88:91]
	v_mfma_f32_16x16x32_bf16 v[76:79], v[132:135], v[216:219], v[76:79]
	v_mfma_f32_16x16x32_bf16 v[72:75], v[140:143], v[216:219], v[72:75]
	s_setprio 0
	s_setprio 1
	v_mfma_f32_16x16x32_bf16 v[116:119], v[144:147], v[176:179], v[116:119]
	v_mfma_f32_16x16x32_bf16 v[112:115], v[168:171], v[176:179], v[112:115]
	v_mfma_f32_16x16x32_bf16 v[100:103], v[144:147], v[192:195], v[100:103]
	v_mfma_f32_16x16x32_bf16 v[96:99], v[168:171], v[192:195], v[96:99]
	v_mfma_f32_16x16x32_bf16 v[84:87], v[144:147], v[204:207], v[84:87]
	v_mfma_f32_16x16x32_bf16 v[80:83], v[168:171], v[204:207], v[80:83]
	v_mfma_f32_16x16x32_bf16 v[68:71], v[144:147], v[212:215], v[68:71]
	v_mfma_f32_16x16x32_bf16 v[64:67], v[168:171], v[212:215], v[64:67]
	v_mfma_f32_16x16x32_bf16 v[116:119], v[148:151], v[180:183], v[116:119]
	v_mfma_f32_16x16x32_bf16 v[112:115], v[172:175], v[180:183], v[112:115]
	v_mfma_f32_16x16x32_bf16 v[100:103], v[148:151], v[198:201], v[100:103]
	v_mfma_f32_16x16x32_bf16 v[96:99], v[172:175], v[198:201], v[96:99]
	v_mfma_f32_16x16x32_bf16 v[84:87], v[148:151], v[208:211], v[84:87]
	v_mfma_f32_16x16x32_bf16 v[80:83], v[172:175], v[208:211], v[80:83]
	v_mfma_f32_16x16x32_bf16 v[68:71], v[148:151], v[216:219], v[68:71]
	v_mfma_f32_16x16x32_bf16 v[64:67], v[172:175], v[216:219], v[64:67]
	s_setprio 0
	s_barrier
	s_add_i32 s30, s48, s41
	v_lshl_add_u64 v[184:185], s[36:37], 0, v[154:155]
	s_mov_b32 m0, s30
	ds_read_b128 v[176:179], v191 offset:16384
	ds_read_b128 v[180:183], v191 offset:17408
	ds_read_b128 v[192:195], v191 offset:18432
	ds_read_b128 v[198:201], v191 offset:19456
	ds_read_b128 v[204:207], v191 offset:20480
	ds_read_b128 v[208:211], v191 offset:21504
	ds_read_b128 v[212:215], v191 offset:22528
	ds_read_b128 v[216:219], v191 offset:23552
	global_load_lds_dwordx4 v[184:185], off
	s_add_i32 m0, s30, 0x2000
	s_add_u32 s30, s36, 0xb0000
	v_lshl_add_u64 v[220:221], s[36:37], 0, v[158:159]
	s_addc_u32 s31, s37, 0
	s_add_i32 s57, s49, s41
	global_load_lds_dwordx4 v[220:221], off
	v_lshl_add_u64 v[222:223], s[30:31], 0, v[154:155]
	s_mov_b32 m0, s57
	v_lshl_add_u64 v[224:225], s[38:39], 0, v[156:157]
	global_load_lds_dwordx4 v[222:223], off
	s_add_i32 m0, s57, 0x2000
	v_lshl_add_u64 v[222:223], s[30:31], 0, v[158:159]
	global_load_lds_dwordx4 v[222:223], off
	s_mov_b32 m0, s42
	v_lshl_add_u64 v[222:223], s[38:39], 0, v[152:153]
	global_load_lds_dwordx4 v[222:223], off
	s_mov_b32 m0, s33
	s_nop 0
	global_load_lds_dwordx4 v[224:225], off
	s_waitcnt vmcnt(8) lgkmcnt(0)
	s_setprio 1
	s_barrier
	v_mfma_f32_16x16x32_bf16 v[60:63], v[128:131], v[176:179], v[60:63]
	v_mfma_f32_16x16x32_bf16 v[56:59], v[136:139], v[176:179], v[56:59]
	v_mfma_f32_16x16x32_bf16 v[44:47], v[128:131], v[192:195], v[44:47]
	v_mfma_f32_16x16x32_bf16 v[40:43], v[136:139], v[192:195], v[40:43]
	v_mfma_f32_16x16x32_bf16 v[28:31], v[128:131], v[204:207], v[28:31]
	v_mfma_f32_16x16x32_bf16 v[24:27], v[136:139], v[204:207], v[24:27]
	v_mfma_f32_16x16x32_bf16 v[12:15], v[128:131], v[212:215], v[12:15]
	v_mfma_f32_16x16x32_bf16 v[8:11], v[136:139], v[212:215], v[8:11]
	v_mfma_f32_16x16x32_bf16 v[60:63], v[132:135], v[180:183], v[60:63]
	v_mfma_f32_16x16x32_bf16 v[56:59], v[140:143], v[180:183], v[56:59]
	v_mfma_f32_16x16x32_bf16 v[44:47], v[132:135], v[198:201], v[44:47]
	v_mfma_f32_16x16x32_bf16 v[40:43], v[140:143], v[198:201], v[40:43]
	v_mfma_f32_16x16x32_bf16 v[28:31], v[132:135], v[208:211], v[28:31]
	v_mfma_f32_16x16x32_bf16 v[24:27], v[140:143], v[208:211], v[24:27]
	v_mfma_f32_16x16x32_bf16 v[12:15], v[132:135], v[216:219], v[12:15]
	v_mfma_f32_16x16x32_bf16 v[8:11], v[140:143], v[216:219], v[8:11]
	s_setprio 0
	s_setprio 1
	v_mfma_f32_16x16x32_bf16 v[52:55], v[144:147], v[176:179], v[52:55]
	v_mfma_f32_16x16x32_bf16 v[48:51], v[168:171], v[176:179], v[48:51]
	v_mfma_f32_16x16x32_bf16 v[36:39], v[144:147], v[192:195], v[36:39]
	v_mfma_f32_16x16x32_bf16 v[32:35], v[168:171], v[192:195], v[32:35]
	v_mfma_f32_16x16x32_bf16 v[20:23], v[144:147], v[204:207], v[20:23]
	v_mfma_f32_16x16x32_bf16 v[16:19], v[168:171], v[204:207], v[16:19]
	v_mfma_f32_16x16x32_bf16 v[4:7], v[144:147], v[212:215], v[4:7]
	v_mfma_f32_16x16x32_bf16 v[0:3], v[168:171], v[212:215], v[0:3]
	v_mfma_f32_16x16x32_bf16 v[52:55], v[148:151], v[180:183], v[52:55]
	v_mfma_f32_16x16x32_bf16 v[48:51], v[172:175], v[180:183], v[48:51]
	v_mfma_f32_16x16x32_bf16 v[36:39], v[148:151], v[198:201], v[36:39]
	v_mfma_f32_16x16x32_bf16 v[32:35], v[172:175], v[198:201], v[32:35]
	v_mfma_f32_16x16x32_bf16 v[20:23], v[148:151], v[208:211], v[20:23]
	v_mfma_f32_16x16x32_bf16 v[16:19], v[172:175], v[208:211], v[16:19]
	v_mfma_f32_16x16x32_bf16 v[4:7], v[148:151], v[216:219], v[4:7]
	v_mfma_f32_16x16x32_bf16 v[0:3], v[172:175], v[216:219], v[0:3]
	s_setprio 0
	s_barrier
	s_add_i32 s57, 0, 0x18000
	s_add_i32 s58, 0, 0x1c000
	v_add_u32_e32 v140, s57, v187
	v_add_u32_e32 v172, s58, v187
	ds_read_b128 v[128:131], v140
	ds_read_b128 v[132:135], v140 offset:1024
	ds_read_b128 v[136:139], v140 offset:2048
	ds_read_b128 v[140:143], v140 offset:3072
	ds_read_b128 v[144:147], v172
	ds_read_b128 v[148:151], v172 offset:1024
	ds_read_b128 v[168:171], v172 offset:2048
	ds_read_b128 v[172:175], v172 offset:3072
	s_add_u32 s30, s38, 0xb0000
	s_addc_u32 s31, s39, 0
	s_mov_b32 m0, s43
	v_lshl_add_u64 v[226:227], s[30:31], 0, v[152:153]
	ds_read_b128 v[176:179], v191 offset:32768
	ds_read_b128 v[180:183], v191 offset:33792
	ds_read_b128 v[192:195], v191 offset:34816
	ds_read_b128 v[198:201], v191 offset:35840
	ds_read_b128 v[204:207], v191 offset:36864
	ds_read_b128 v[208:211], v191 offset:37888
	ds_read_b128 v[212:215], v191 offset:38912
	ds_read_b128 v[216:219], v191 offset:39936
	global_load_lds_dwordx4 v[226:227], off
	s_mov_b32 m0, s44
	v_lshl_add_u64 v[226:227], s[30:31], 0, v[156:157]
	global_load_lds_dwordx4 v[226:227], off
	s_waitcnt vmcnt(8) lgkmcnt(0)
	s_setprio 1
	s_barrier
	v_mfma_f32_16x16x32_bf16 v[124:127], v[128:131], v[176:179], v[124:127]
	v_mfma_f32_16x16x32_bf16 v[120:123], v[136:139], v[176:179], v[120:123]
	v_mfma_f32_16x16x32_bf16 v[108:111], v[128:131], v[192:195], v[108:111]
	v_mfma_f32_16x16x32_bf16 v[104:107], v[136:139], v[192:195], v[104:107]
	v_mfma_f32_16x16x32_bf16 v[92:95], v[128:131], v[204:207], v[92:95]
	v_mfma_f32_16x16x32_bf16 v[88:91], v[136:139], v[204:207], v[88:91]
	v_mfma_f32_16x16x32_bf16 v[76:79], v[128:131], v[212:215], v[76:79]
	v_mfma_f32_16x16x32_bf16 v[72:75], v[136:139], v[212:215], v[72:75]
	v_mfma_f32_16x16x32_bf16 v[124:127], v[132:135], v[180:183], v[124:127]
	v_mfma_f32_16x16x32_bf16 v[120:123], v[140:143], v[180:183], v[120:123]
	v_mfma_f32_16x16x32_bf16 v[108:111], v[132:135], v[198:201], v[108:111]
	v_mfma_f32_16x16x32_bf16 v[104:107], v[140:143], v[198:201], v[104:107]
	v_mfma_f32_16x16x32_bf16 v[92:95], v[132:135], v[208:211], v[92:95]
	v_mfma_f32_16x16x32_bf16 v[88:91], v[140:143], v[208:211], v[88:91]
	v_mfma_f32_16x16x32_bf16 v[76:79], v[132:135], v[216:219], v[76:79]
	v_mfma_f32_16x16x32_bf16 v[72:75], v[140:143], v[216:219], v[72:75]
	s_setprio 0
	s_setprio 1
	v_mfma_f32_16x16x32_bf16 v[116:119], v[144:147], v[176:179], v[116:119]
	v_mfma_f32_16x16x32_bf16 v[112:115], v[168:171], v[176:179], v[112:115]
	v_mfma_f32_16x16x32_bf16 v[100:103], v[144:147], v[192:195], v[100:103]
	v_mfma_f32_16x16x32_bf16 v[96:99], v[168:171], v[192:195], v[96:99]
	v_mfma_f32_16x16x32_bf16 v[84:87], v[144:147], v[204:207], v[84:87]
	v_mfma_f32_16x16x32_bf16 v[80:83], v[168:171], v[204:207], v[80:83]
	v_mfma_f32_16x16x32_bf16 v[68:71], v[144:147], v[212:215], v[68:71]
	v_mfma_f32_16x16x32_bf16 v[64:67], v[168:171], v[212:215], v[64:67]
	v_mfma_f32_16x16x32_bf16 v[116:119], v[148:151], v[180:183], v[116:119]
	v_mfma_f32_16x16x32_bf16 v[112:115], v[172:175], v[180:183], v[112:115]
	v_mfma_f32_16x16x32_bf16 v[100:103], v[148:151], v[198:201], v[100:103]
	v_mfma_f32_16x16x32_bf16 v[96:99], v[172:175], v[198:201], v[96:99]
	v_mfma_f32_16x16x32_bf16 v[84:87], v[148:151], v[208:211], v[84:87]
	v_mfma_f32_16x16x32_bf16 v[80:83], v[172:175], v[208:211], v[80:83]
	v_mfma_f32_16x16x32_bf16 v[68:71], v[148:151], v[216:219], v[68:71]
	v_mfma_f32_16x16x32_bf16 v[64:67], v[172:175], v[216:219], v[64:67]
	s_setprio 0
	s_barrier
	s_add_i32 s30, s57, s41
	v_lshl_add_u64 v[184:185], v[184:185], 0, s[24:25]
	s_mov_b32 m0, s30
	ds_read_b128 v[176:179], v191 offset:49152
	ds_read_b128 v[180:183], v191 offset:50176
	ds_read_b128 v[192:195], v191 offset:51200
	ds_read_b128 v[198:201], v191 offset:52224
	ds_read_b128 v[204:207], v191 offset:53248
	ds_read_b128 v[208:211], v191 offset:54272
	ds_read_b128 v[212:215], v191 offset:55296
	ds_read_b128 v[216:219], v191 offset:56320
	global_load_lds_dwordx4 v[184:185], off
	s_add_i32 m0, s30, 0x2000
	s_add_u32 s30, s36, 0xb0080
	v_lshl_add_u64 v[184:185], v[220:221], 0, s[24:25]
	s_addc_u32 s31, s37, 0
	s_add_i32 s36, s58, s41
	global_load_lds_dwordx4 v[184:185], off
	s_mov_b32 m0, s36
	v_lshl_add_u64 v[184:185], s[30:31], 0, v[154:155]
	global_load_lds_dwordx4 v[184:185], off
	s_add_i32 m0, s36, 0x2000
	v_lshl_add_u64 v[184:185], s[30:31], 0, v[158:159]
	global_load_lds_dwordx4 v[184:185], off
	s_mov_b32 m0, s46
	v_lshl_add_u64 v[184:185], v[222:223], 0, s[24:25]
	global_load_lds_dwordx4 v[184:185], off
	s_mov_b32 m0, s47
	v_lshl_add_u64 v[184:185], v[224:225], 0, s[24:25]
	global_load_lds_dwordx4 v[184:185], off
	s_waitcnt vmcnt(8) lgkmcnt(0)
	s_setprio 1
	s_barrier
	v_mfma_f32_16x16x32_bf16 v[60:63], v[128:131], v[176:179], v[60:63]
	v_mfma_f32_16x16x32_bf16 v[56:59], v[136:139], v[176:179], v[56:59]
	v_mfma_f32_16x16x32_bf16 v[44:47], v[128:131], v[192:195], v[44:47]
	v_mfma_f32_16x16x32_bf16 v[40:43], v[136:139], v[192:195], v[40:43]
	v_mfma_f32_16x16x32_bf16 v[28:31], v[128:131], v[204:207], v[28:31]
	v_mfma_f32_16x16x32_bf16 v[24:27], v[136:139], v[204:207], v[24:27]
	v_mfma_f32_16x16x32_bf16 v[12:15], v[128:131], v[212:215], v[12:15]
	v_mfma_f32_16x16x32_bf16 v[8:11], v[136:139], v[212:215], v[8:11]
	v_mfma_f32_16x16x32_bf16 v[60:63], v[132:135], v[180:183], v[60:63]
	v_mfma_f32_16x16x32_bf16 v[56:59], v[140:143], v[180:183], v[56:59]
	v_mfma_f32_16x16x32_bf16 v[44:47], v[132:135], v[198:201], v[44:47]
	v_mfma_f32_16x16x32_bf16 v[40:43], v[140:143], v[198:201], v[40:43]
	v_mfma_f32_16x16x32_bf16 v[28:31], v[132:135], v[208:211], v[28:31]
	v_mfma_f32_16x16x32_bf16 v[24:27], v[140:143], v[208:211], v[24:27]
	v_mfma_f32_16x16x32_bf16 v[12:15], v[132:135], v[216:219], v[12:15]
	v_mfma_f32_16x16x32_bf16 v[8:11], v[140:143], v[216:219], v[8:11]
	s_setprio 0
	s_setprio 1
	v_mfma_f32_16x16x32_bf16 v[52:55], v[144:147], v[176:179], v[52:55]
	v_mfma_f32_16x16x32_bf16 v[48:51], v[168:171], v[176:179], v[48:51]
	v_mfma_f32_16x16x32_bf16 v[36:39], v[144:147], v[192:195], v[36:39]
	v_mfma_f32_16x16x32_bf16 v[32:35], v[168:171], v[192:195], v[32:35]
	v_mfma_f32_16x16x32_bf16 v[20:23], v[144:147], v[204:207], v[20:23]
	v_mfma_f32_16x16x32_bf16 v[16:19], v[168:171], v[204:207], v[16:19]
	v_mfma_f32_16x16x32_bf16 v[4:7], v[144:147], v[212:215], v[4:7]
	v_mfma_f32_16x16x32_bf16 v[0:3], v[168:171], v[212:215], v[0:3]
	v_mfma_f32_16x16x32_bf16 v[52:55], v[148:151], v[180:183], v[52:55]
	v_mfma_f32_16x16x32_bf16 v[48:51], v[172:175], v[180:183], v[48:51]
	v_mfma_f32_16x16x32_bf16 v[36:39], v[148:151], v[198:201], v[36:39]
	v_mfma_f32_16x16x32_bf16 v[32:35], v[172:175], v[198:201], v[32:35]
	v_mfma_f32_16x16x32_bf16 v[20:23], v[148:151], v[208:211], v[20:23]
	v_mfma_f32_16x16x32_bf16 v[16:19], v[172:175], v[208:211], v[16:19]
	v_mfma_f32_16x16x32_bf16 v[4:7], v[148:151], v[216:219], v[4:7]
	v_mfma_f32_16x16x32_bf16 v[0:3], v[172:175], v[216:219], v[0:3]
	s_setprio 0
	s_add_i32 s56, s56, 2
	s_add_u32 s54, s54, 0x100
	s_addc_u32 s55, s55, 0
	s_cmp_gt_u32 s56, 41
	s_mov_b64 s[30:31], s[34:35]
	s_barrier
	s_cbranch_scc0 .LBB0_1124
	s_and_b64 vcc, exec, s[26:27]
	s_cbranch_vccz .LBB0_1127
	s_barrier

.LBB0_1143:
	s_or_b64 exec, exec, s[34:35]
	s_and_b64 vcc, exec, s[6:7]
	s_mov_b64 s[6:7], -1
	s_cbranch_vccnz .LBB0_1112
	s_andn2_b64 vcc, exec, s[12:13]
	s_cbranch_vccnz .LBB0_1111
	s_mov_b32 s90, 1
	s_branch .LBB0_1111
